# v004 + K-loop MMA blocks: drop redundant post-barrier lgkmcnt(0) and mid-block setprio 0/1 pair
# speedup vs baseline: 1.0043x; 1.0024x over previous
; #define PG8_STAGE(bufoff, gbase, voff) do { _Pragma("unroll") for (int _i = 0; _i < 2; ++_i) \
;         __builtin_amdgcn_global_load_lds((const unsigned*)((const char*)(gbase) + (voff)[_i]), (LAS unsigned*)(lds + (bufoff) + ldsw + _i * 8192), 16, 0, 0); } while (0)
; #define PG8_LDA(dst, b, h) do { _Pragma("unroll") for (int m = 0; m < 4; ++m) _Pragma("unroll") for (int k = 0; k < 2; ++k) dst[m][k] = *(const LAS bf16x8*)(lds + PG8_SA(b, h) + aoff + m * 2048 + k * 1024); } while (0)
; #define PG8_LDB(dst, b, h) do { _Pragma("unroll") for (int n = 0; n < 2; ++n) _Pragma("unroll") for (int k = 0; k < 2; ++k) dst[n][k] = *(const LAS bf16x8*)(lds + PG8_SB(b, h) + boff + n * 2048 + k * 1024); } while (0)
; #define PG8_MMA(ai, bj, At, Bt) do { __builtin_amdgcn_s_setprio(1); _Pragma("unroll") for (int m = 0; m < 4; ++m) _Pragma("unroll") for (int n = 0; n < 2; ++n) _Pragma("unroll") for (int k = 0; k < 2; ++k) \
;         acc[ai][bj][m][n] = __builtin_amdgcn_mfma_f32_16x16x32_bf16(Bt[n][k], At[m][k], acc[ai][bj][m][n], 0, 0, 0); __builtin_amdgcn_s_setprio(0); } while (0)
; #define PG8_WAIT_V(n) asm volatile("s_waitcnt vmcnt(" #n ")" ::: "memory")
; #define PG8_WAIT_L(n) asm volatile("s_waitcnt lgkmcnt(" #n ")" ::: "memory")
; #define PG8_BAR __builtin_amdgcn_s_barrier()
; #define PG8_SCHED __builtin_amdgcn_sched_barrier(0)
; template <class Epi, class Sched, bool ALIGN_EPI, bool SP2>
; __device__ __forceinline__ void gemm_phase(LAS unsigned char* lds, const Gemm g, const Sched& S, const Epi& E) {
;     ...
;             PG8_LDB(B0, 0, 0); PG8_LDB(B1, 0, 1); PG8_SCHED; PG8_LDA(At, 0, 0); PG8_STAGE(PG8_SA(1, 1), a1 + hstep, voffA);
;             PG8_WAIT_V(8); PG8_WAIT_L(0); PG8_BAR; PG8_MMA(0, 0, At, B0); PG8_MMA(0, 1, At, B1); PG8_BAR; PG8_SCHED;
;             PG8_LDA(At, 0, 1); PG8_STAGE(PG8_SB(0, 0), b2, voffB); PG8_STAGE(PG8_SB(0, 1), b2 + hstepB, voffB); PG8_STAGE(PG8_SA(0, 0), a2, voffA);
;             PG8_WAIT_V(8); PG8_WAIT_L(0); PG8_BAR; PG8_MMA(1, 0, At, B0); PG8_MMA(1, 1, At, B1); PG8_BAR; PG8_SCHED;
.LBB0_392:
	ds_read_b128 v[128:131], v171
	ds_read_b128 v[132:135], v171 offset:1024
	ds_read_b128 v[136:139], v171 offset:2048
	ds_read_b128 v[162:165], v171 offset:3072
	ds_read_b128 v[174:177], v172
	ds_read_b128 v[178:181], v172 offset:1024
	ds_read_b128 v[182:185], v172 offset:2048
	ds_read_b128 v[186:189], v172 offset:3072
	s_add_u32 s14, s74, 0xfff80080
	s_addc_u32 s15, s75, -1
	s_cmp_eq_u32 s73, 28
	s_cselect_b32 s79, s33, s15
	s_cselect_b32 s78, s48, s14
	s_cselect_b32 s77, s11, s71
	s_cselect_b32 s76, s49, s65
	v_lshl_add_u64 v[140:141], s[74:75], 0, v[154:155]
	s_add_i32 m0, s59, 0xc000
	ds_read_b128 v[190:193], v173
	ds_read_b128 v[194:197], v173 offset:1024
	ds_read_b128 v[198:201], v173 offset:2048
	ds_read_b128 v[202:205], v173 offset:3072
	ds_read_b128 v[208:211], v173 offset:4096
	ds_read_b128 v[212:215], v173 offset:5120
	ds_read_b128 v[216:219], v173 offset:6144
	ds_read_b128 v[220:223], v173 offset:7168
	global_load_lds_dwordx4 v[140:141], off
	v_lshl_add_u64 v[140:141], s[74:75], 0, v[156:157]
	s_add_i32 m0, s59, 0xe000
	s_nop 0
	global_load_lds_dwordx4 v[140:141], off
	s_waitcnt vmcnt(8)
	s_waitcnt lgkmcnt(0)
	s_barrier
	s_setprio 1
	v_mfma_f32_16x16x32_bf16 v[124:127], v[128:131], v[190:193], v[124:127]
	v_mfma_f32_16x16x32_bf16 v[120:123], v[136:139], v[190:193], v[120:123]
	v_mfma_f32_16x16x32_bf16 v[108:111], v[128:131], v[198:201], v[108:111]
	v_mfma_f32_16x16x32_bf16 v[104:107], v[136:139], v[198:201], v[104:107]
	v_mfma_f32_16x16x32_bf16 v[92:95], v[128:131], v[208:211], v[92:95]
	v_mfma_f32_16x16x32_bf16 v[88:91], v[136:139], v[208:211], v[88:91]
	v_mfma_f32_16x16x32_bf16 v[76:79], v[128:131], v[216:219], v[76:79]
	v_mfma_f32_16x16x32_bf16 v[72:75], v[136:139], v[216:219], v[72:75]
	v_mfma_f32_16x16x32_bf16 v[124:127], v[132:135], v[194:197], v[124:127]
	v_mfma_f32_16x16x32_bf16 v[120:123], v[162:165], v[194:197], v[120:123]
	v_mfma_f32_16x16x32_bf16 v[108:111], v[132:135], v[202:205], v[108:111]
	v_mfma_f32_16x16x32_bf16 v[104:107], v[162:165], v[202:205], v[104:107]
	v_mfma_f32_16x16x32_bf16 v[92:95], v[132:135], v[212:215], v[92:95]
	v_mfma_f32_16x16x32_bf16 v[88:91], v[162:165], v[212:215], v[88:91]
	v_mfma_f32_16x16x32_bf16 v[76:79], v[132:135], v[220:223], v[76:79]
	v_mfma_f32_16x16x32_bf16 v[72:75], v[162:165], v[220:223], v[72:75]
	v_mfma_f32_16x16x32_bf16 v[116:119], v[174:177], v[190:193], v[116:119]
	v_mfma_f32_16x16x32_bf16 v[112:115], v[182:185], v[190:193], v[112:115]
	v_mfma_f32_16x16x32_bf16 v[100:103], v[174:177], v[198:201], v[100:103]
	v_mfma_f32_16x16x32_bf16 v[96:99], v[182:185], v[198:201], v[96:99]
	v_mfma_f32_16x16x32_bf16 v[84:87], v[174:177], v[208:211], v[84:87]
	v_mfma_f32_16x16x32_bf16 v[80:83], v[182:185], v[208:211], v[80:83]
	v_mfma_f32_16x16x32_bf16 v[68:71], v[174:177], v[216:219], v[68:71]
	v_mfma_f32_16x16x32_bf16 v[64:67], v[182:185], v[216:219], v[64:67]
	v_mfma_f32_16x16x32_bf16 v[116:119], v[178:181], v[194:197], v[116:119]
	v_mfma_f32_16x16x32_bf16 v[112:115], v[186:189], v[194:197], v[112:115]
	v_mfma_f32_16x16x32_bf16 v[100:103], v[178:181], v[202:205], v[100:103]
	v_mfma_f32_16x16x32_bf16 v[96:99], v[186:189], v[202:205], v[96:99]
	v_mfma_f32_16x16x32_bf16 v[84:87], v[178:181], v[212:215], v[84:87]
	v_mfma_f32_16x16x32_bf16 v[80:83], v[186:189], v[212:215], v[80:83]
	v_mfma_f32_16x16x32_bf16 v[68:71], v[178:181], v[220:223], v[68:71]
	v_mfma_f32_16x16x32_bf16 v[64:67], v[186:189], v[220:223], v[64:67]
	s_setprio 0
	s_barrier
	s_add_i32 s14, s87, s57
	v_lshl_add_u64 v[140:141], s[76:77], 0, v[144:145]
	s_mov_b32 m0, s14
	ds_read_b128 v[190:193], v173 offset:16384
	ds_read_b128 v[194:197], v173 offset:17408
	ds_read_b128 v[198:201], v173 offset:18432
	ds_read_b128 v[202:205], v173 offset:19456
	ds_read_b128 v[208:211], v173 offset:20480
	ds_read_b128 v[212:215], v173 offset:21504
	ds_read_b128 v[216:219], v173 offset:22528
	ds_read_b128 v[220:223], v173 offset:23552
	global_load_lds_dwordx4 v[140:141], off
	s_add_i32 m0, s14, 0x2000
	s_add_u32 s14, s76, 0x80000
	v_lshl_add_u64 v[166:167], s[76:77], 0, v[148:149]
	s_addc_u32 s15, s77, 0
	s_add_i32 s58, s88, s57
	global_load_lds_dwordx4 v[166:167], off
	v_lshl_add_u64 v[224:225], s[14:15], 0, v[144:145]
	s_mov_b32 m0, s58
	v_lshl_add_u64 v[226:227], s[78:79], 0, v[146:147]
	global_load_lds_dwordx4 v[224:225], off
	v_lshl_add_u64 v[224:225], s[14:15], 0, v[148:149]
	s_add_i32 m0, s58, 0x2000
	s_nop 0
	global_load_lds_dwordx4 v[224:225], off
	v_lshl_add_u64 v[224:225], s[78:79], 0, v[142:143]
	s_mov_b32 m0, s59
	s_nop 0
	global_load_lds_dwordx4 v[224:225], off
	s_mov_b32 m0, s80
	s_nop 0
	global_load_lds_dwordx4 v[226:227], off
	s_waitcnt vmcnt(8)
	s_waitcnt lgkmcnt(0)
	s_barrier
; #define PG8_STAGE(bufoff, gbase, voff) do { _Pragma("unroll") for (int _i = 0; _i < 2; ++_i) \
;         __builtin_amdgcn_global_load_lds((const unsigned*)((const char*)(gbase) + (voff)[_i]), (LAS unsigned*)(lds + (bufoff) + ldsw + _i * 8192), 16, 0, 0); } while (0)
; #define PG8_LDA(dst, b, h) do { _Pragma("unroll") for (int m = 0; m < 4; ++m) _Pragma("unroll") for (int k = 0; k < 2; ++k) dst[m][k] = *(const LAS bf16x8*)(lds + PG8_SA(b, h) + aoff + m * 2048 + k * 1024); } while (0)
; #define PG8_LDB(dst, b, h) do { _Pragma("unroll") for (int n = 0; n < 2; ++n) _Pragma("unroll") for (int k = 0; k < 2; ++k) dst[n][k] = *(const LAS bf16x8*)(lds + PG8_SB(b, h) + boff + n * 2048 + k * 1024); } while (0)
; #define PG8_MMA(ai, bj, At, Bt) do { __builtin_amdgcn_s_setprio(1); _Pragma("unroll") for (int m = 0; m < 4; ++m) _Pragma("unroll") for (int n = 0; n < 2; ++n) _Pragma("unroll") for (int k = 0; k < 2; ++k) \
;         acc[ai][bj][m][n] = __builtin_amdgcn_mfma_f32_16x16x32_bf16(Bt[n][k], At[m][k], acc[ai][bj][m][n], 0, 0, 0); __builtin_amdgcn_s_setprio(0); } while (0)
; #define PG8_WAIT_V(n) asm volatile("s_waitcnt vmcnt(" #n ")" ::: "memory")
; #define PG8_WAIT_L(n) asm volatile("s_waitcnt lgkmcnt(" #n ")" ::: "memory")
; #define PG8_BAR __builtin_amdgcn_s_barrier()
; #define PG8_SCHED __builtin_amdgcn_sched_barrier(0)
; template <class Epi, class Sched, bool ALIGN_EPI, bool SP2>
; __device__ __forceinline__ void gemm_phase(LAS unsigned char* lds, const Gemm g, const Sched& S, const Epi& E) {
;     ...
;             PG8_WAIT_V(8); PG8_WAIT_L(0); PG8_BAR; PG8_MMA(1, 0, At, B0); PG8_MMA(1, 1, At, B1); PG8_BAR; PG8_SCHED;
;             PG8_LDB(B0, 1, 0); PG8_LDB(B1, 1, 1); PG8_SCHED; PG8_LDA(At, 1, 0); PG8_STAGE(PG8_SA(0, 1), a2 + hstep, voffA);
;             PG8_WAIT_V(8); PG8_WAIT_L(0); PG8_BAR; PG8_MMA(0, 0, At, B0); PG8_MMA(0, 1, At, B1); PG8_BAR; PG8_SCHED;
	s_setprio 1
	v_mfma_f32_16x16x32_bf16 v[60:63], v[128:131], v[190:193], v[60:63]
	v_mfma_f32_16x16x32_bf16 v[56:59], v[136:139], v[190:193], v[56:59]
	v_mfma_f32_16x16x32_bf16 v[44:47], v[128:131], v[198:201], v[44:47]
	v_mfma_f32_16x16x32_bf16 v[40:43], v[136:139], v[198:201], v[40:43]
	v_mfma_f32_16x16x32_bf16 v[28:31], v[128:131], v[208:211], v[28:31]
	v_mfma_f32_16x16x32_bf16 v[24:27], v[136:139], v[208:211], v[24:27]
	v_mfma_f32_16x16x32_bf16 v[12:15], v[128:131], v[216:219], v[12:15]
	v_mfma_f32_16x16x32_bf16 v[8:11], v[136:139], v[216:219], v[8:11]
	v_mfma_f32_16x16x32_bf16 v[60:63], v[132:135], v[194:197], v[60:63]
	v_mfma_f32_16x16x32_bf16 v[56:59], v[162:165], v[194:197], v[56:59]
	v_mfma_f32_16x16x32_bf16 v[44:47], v[132:135], v[202:205], v[44:47]
	v_mfma_f32_16x16x32_bf16 v[40:43], v[162:165], v[202:205], v[40:43]
	v_mfma_f32_16x16x32_bf16 v[28:31], v[132:135], v[212:215], v[28:31]
	v_mfma_f32_16x16x32_bf16 v[24:27], v[162:165], v[212:215], v[24:27]
	v_mfma_f32_16x16x32_bf16 v[12:15], v[132:135], v[220:223], v[12:15]
	v_mfma_f32_16x16x32_bf16 v[8:11], v[162:165], v[220:223], v[8:11]
	v_mfma_f32_16x16x32_bf16 v[52:55], v[174:177], v[190:193], v[52:55]
	v_mfma_f32_16x16x32_bf16 v[48:51], v[182:185], v[190:193], v[48:51]
	v_mfma_f32_16x16x32_bf16 v[36:39], v[174:177], v[198:201], v[36:39]
	v_mfma_f32_16x16x32_bf16 v[32:35], v[182:185], v[198:201], v[32:35]
	v_mfma_f32_16x16x32_bf16 v[20:23], v[174:177], v[208:211], v[20:23]
	v_mfma_f32_16x16x32_bf16 v[16:19], v[182:185], v[208:211], v[16:19]
	v_mfma_f32_16x16x32_bf16 v[4:7], v[174:177], v[216:219], v[4:7]
	v_mfma_f32_16x16x32_bf16 v[0:3], v[182:185], v[216:219], v[0:3]
	v_mfma_f32_16x16x32_bf16 v[52:55], v[178:181], v[194:197], v[52:55]
	v_mfma_f32_16x16x32_bf16 v[48:51], v[186:189], v[194:197], v[48:51]
	v_mfma_f32_16x16x32_bf16 v[36:39], v[178:181], v[202:205], v[36:39]
	v_mfma_f32_16x16x32_bf16 v[32:35], v[186:189], v[202:205], v[32:35]
	v_mfma_f32_16x16x32_bf16 v[20:23], v[178:181], v[212:215], v[20:23]
	v_mfma_f32_16x16x32_bf16 v[16:19], v[186:189], v[212:215], v[16:19]
	v_mfma_f32_16x16x32_bf16 v[4:7], v[178:181], v[220:223], v[4:7]
	v_mfma_f32_16x16x32_bf16 v[0:3], v[186:189], v[220:223], v[0:3]
	s_setprio 0
	s_barrier
	s_add_i32 s58, 0, 0x18000
	v_add_u32_e32 v150, s58, v169
	s_add_i32 s89, 0, 0x1c000
	ds_read_b128 v[128:131], v150
	ds_read_b128 v[132:135], v150 offset:1024
	ds_read_b128 v[136:139], v150 offset:2048
	ds_read_b128 v[162:165], v150 offset:3072
	v_add_u32_e32 v150, s89, v169
	ds_read_b128 v[174:177], v150
	ds_read_b128 v[178:181], v150 offset:1024
	ds_read_b128 v[182:185], v150 offset:2048
	ds_read_b128 v[186:189], v150 offset:3072
	s_add_u32 s14, s78, 0x80000
	s_addc_u32 s15, s79, 0
	s_mov_b32 m0, s81
	v_lshl_add_u64 v[228:229], s[14:15], 0, v[142:143]
	ds_read_b128 v[190:193], v173 offset:32768
	ds_read_b128 v[194:197], v173 offset:33792
	ds_read_b128 v[198:201], v173 offset:34816
	ds_read_b128 v[202:205], v173 offset:35840
	ds_read_b128 v[208:211], v173 offset:36864
	ds_read_b128 v[212:215], v173 offset:37888
	ds_read_b128 v[216:219], v173 offset:38912
	ds_read_b128 v[220:223], v173 offset:39936
	global_load_lds_dwordx4 v[228:229], off
	v_lshl_add_u64 v[228:229], s[14:15], 0, v[146:147]
	s_mov_b32 m0, s82
	s_nop 0
	global_load_lds_dwordx4 v[228:229], off
	s_waitcnt vmcnt(8)
	s_waitcnt lgkmcnt(0)
	s_barrier
	s_setprio 1
	v_mfma_f32_16x16x32_bf16 v[124:127], v[128:131], v[190:193], v[124:127]
	v_mfma_f32_16x16x32_bf16 v[120:123], v[136:139], v[190:193], v[120:123]
	v_mfma_f32_16x16x32_bf16 v[108:111], v[128:131], v[198:201], v[108:111]
	v_mfma_f32_16x16x32_bf16 v[104:107], v[136:139], v[198:201], v[104:107]
	v_mfma_f32_16x16x32_bf16 v[92:95], v[128:131], v[208:211], v[92:95]
	v_mfma_f32_16x16x32_bf16 v[88:91], v[136:139], v[208:211], v[88:91]
	v_mfma_f32_16x16x32_bf16 v[76:79], v[128:131], v[216:219], v[76:79]
	v_mfma_f32_16x16x32_bf16 v[72:75], v[136:139], v[216:219], v[72:75]
	v_mfma_f32_16x16x32_bf16 v[124:127], v[132:135], v[194:197], v[124:127]
	v_mfma_f32_16x16x32_bf16 v[120:123], v[162:165], v[194:197], v[120:123]
	v_mfma_f32_16x16x32_bf16 v[108:111], v[132:135], v[202:205], v[108:111]
	v_mfma_f32_16x16x32_bf16 v[104:107], v[162:165], v[202:205], v[104:107]
	v_mfma_f32_16x16x32_bf16 v[92:95], v[132:135], v[212:215], v[92:95]
	v_mfma_f32_16x16x32_bf16 v[88:91], v[162:165], v[212:215], v[88:91]
	v_mfma_f32_16x16x32_bf16 v[76:79], v[132:135], v[220:223], v[76:79]
	v_mfma_f32_16x16x32_bf16 v[72:75], v[162:165], v[220:223], v[72:75]
	v_mfma_f32_16x16x32_bf16 v[116:119], v[174:177], v[190:193], v[116:119]
	v_mfma_f32_16x16x32_bf16 v[112:115], v[182:185], v[190:193], v[112:115]
	v_mfma_f32_16x16x32_bf16 v[100:103], v[174:177], v[198:201], v[100:103]
	v_mfma_f32_16x16x32_bf16 v[96:99], v[182:185], v[198:201], v[96:99]
	v_mfma_f32_16x16x32_bf16 v[84:87], v[174:177], v[208:211], v[84:87]
	v_mfma_f32_16x16x32_bf16 v[80:83], v[182:185], v[208:211], v[80:83]
	v_mfma_f32_16x16x32_bf16 v[68:71], v[174:177], v[216:219], v[68:71]
	v_mfma_f32_16x16x32_bf16 v[64:67], v[182:185], v[216:219], v[64:67]
	v_mfma_f32_16x16x32_bf16 v[116:119], v[178:181], v[194:197], v[116:119]
	v_mfma_f32_16x16x32_bf16 v[112:115], v[186:189], v[194:197], v[112:115]
	v_mfma_f32_16x16x32_bf16 v[100:103], v[178:181], v[202:205], v[100:103]
	v_mfma_f32_16x16x32_bf16 v[96:99], v[186:189], v[202:205], v[96:99]
	v_mfma_f32_16x16x32_bf16 v[84:87], v[178:181], v[212:215], v[84:87]
	v_mfma_f32_16x16x32_bf16 v[80:83], v[186:189], v[212:215], v[80:83]
	v_mfma_f32_16x16x32_bf16 v[68:71], v[178:181], v[220:223], v[68:71]
	v_mfma_f32_16x16x32_bf16 v[64:67], v[186:189], v[220:223], v[64:67]
	s_setprio 0
	s_barrier
; #define PG8_STAGE(bufoff, gbase, voff) do { _Pragma("unroll") for (int _i = 0; _i < 2; ++_i) \
;         __builtin_amdgcn_global_load_lds((const unsigned*)((const char*)(gbase) + (voff)[_i]), (LAS unsigned*)(lds + (bufoff) + ldsw + _i * 8192), 16, 0, 0); } while (0)
; #define PG8_LDA(dst, b, h) do { _Pragma("unroll") for (int m = 0; m < 4; ++m) _Pragma("unroll") for (int k = 0; k < 2; ++k) dst[m][k] = *(const LAS bf16x8*)(lds + PG8_SA(b, h) + aoff + m * 2048 + k * 1024); } while (0)
; #define PG8_MMA(ai, bj, At, Bt) do { __builtin_amdgcn_s_setprio(1); _Pragma("unroll") for (int m = 0; m < 4; ++m) _Pragma("unroll") for (int n = 0; n < 2; ++n) _Pragma("unroll") for (int k = 0; k < 2; ++k) \
;         acc[ai][bj][m][n] = __builtin_amdgcn_mfma_f32_16x16x32_bf16(Bt[n][k], At[m][k], acc[ai][bj][m][n], 0, 0, 0); __builtin_amdgcn_s_setprio(0); } while (0)
; #define PG8_WAIT_V(n) asm volatile("s_waitcnt vmcnt(" #n ")" ::: "memory")
; #define PG8_WAIT_L(n) asm volatile("s_waitcnt lgkmcnt(" #n ")" ::: "memory")
; #define PG8_BAR __builtin_amdgcn_s_barrier()
; #define PG8_SCHED __builtin_amdgcn_sched_barrier(0)
; template <class Epi, class Sched, bool ALIGN_EPI, bool SP2>
; __device__ __forceinline__ void gemm_phase(LAS unsigned char* lds, const Gemm g, const Sched& S, const Epi& E) {
;     ...
;         for (int t = tb; t < te; t += 2) {
;             const bool last = (t == nt - 2);
;             const char* a1 = cA + (size_t)(t + 1) * kstep;
;             const char* a2 = last ? nA : cA + (size_t)(t + 2) * kstep; const char* b2 = last ? nB : cB + (size_t)(t + 2) * kstep;
;             const char* a3 = a2 + kstep; const char* b3 = b2 + kstep;
;             if (last && has_next) S.a_ready(nxt);
;     ...
;             PG8_LDA(At, 1, 1); PG8_STAGE(PG8_SB(1, 0), b3, voffB); PG8_STAGE(PG8_SB(1, 1), b3 + hstepB, voffB); PG8_STAGE(PG8_SA(1, 0), a3, voffA);
;             PG8_WAIT_V(8); PG8_WAIT_L(0); PG8_BAR; PG8_MMA(1, 0, At, B0); PG8_MMA(1, 1, At, B1); PG8_BAR; PG8_SCHED;
	s_add_i32 s14, s58, s57
	v_lshl_add_u64 v[140:141], v[140:141], 0, s[44:45]
	s_mov_b32 m0, s14
	ds_read_b128 v[190:193], v173 offset:49152
	ds_read_b128 v[194:197], v173 offset:50176
	ds_read_b128 v[198:201], v173 offset:51200
	ds_read_b128 v[202:205], v173 offset:52224
	ds_read_b128 v[208:211], v173 offset:53248
	ds_read_b128 v[212:215], v173 offset:54272
	ds_read_b128 v[216:219], v173 offset:55296
	ds_read_b128 v[220:223], v173 offset:56320
	global_load_lds_dwordx4 v[140:141], off
	s_add_i32 m0, s14, 0x2000
	s_add_u32 s14, s76, 0x80080
	v_lshl_add_u64 v[140:141], v[166:167], 0, s[44:45]
	s_addc_u32 s15, s77, 0
	s_add_i32 s58, s89, s57
	global_load_lds_dwordx4 v[140:141], off
	v_lshl_add_u64 v[140:141], s[14:15], 0, v[144:145]
	s_mov_b32 m0, s58
	s_nop 0
	global_load_lds_dwordx4 v[140:141], off
	v_lshl_add_u64 v[140:141], s[14:15], 0, v[148:149]
	s_add_i32 m0, s58, 0x2000
	s_nop 0
	global_load_lds_dwordx4 v[140:141], off
	v_lshl_add_u64 v[140:141], v[224:225], 0, s[44:45]
	s_mov_b32 m0, s84
	s_nop 0
	global_load_lds_dwordx4 v[140:141], off
	v_lshl_add_u64 v[140:141], v[226:227], 0, s[44:45]
	s_mov_b32 m0, s85
	s_nop 0
	global_load_lds_dwordx4 v[140:141], off
	s_waitcnt vmcnt(8)
	s_waitcnt lgkmcnt(0)
	s_barrier
	s_setprio 1
	v_mfma_f32_16x16x32_bf16 v[60:63], v[128:131], v[190:193], v[60:63]
	v_mfma_f32_16x16x32_bf16 v[56:59], v[136:139], v[190:193], v[56:59]
	v_mfma_f32_16x16x32_bf16 v[44:47], v[128:131], v[198:201], v[44:47]
	v_mfma_f32_16x16x32_bf16 v[40:43], v[136:139], v[198:201], v[40:43]
	v_mfma_f32_16x16x32_bf16 v[28:31], v[128:131], v[208:211], v[28:31]
	v_mfma_f32_16x16x32_bf16 v[24:27], v[136:139], v[208:211], v[24:27]
	v_mfma_f32_16x16x32_bf16 v[12:15], v[128:131], v[216:219], v[12:15]
	v_mfma_f32_16x16x32_bf16 v[8:11], v[136:139], v[216:219], v[8:11]
	v_mfma_f32_16x16x32_bf16 v[60:63], v[132:135], v[194:197], v[60:63]
	v_mfma_f32_16x16x32_bf16 v[56:59], v[162:165], v[194:197], v[56:59]
	v_mfma_f32_16x16x32_bf16 v[44:47], v[132:135], v[202:205], v[44:47]
	v_mfma_f32_16x16x32_bf16 v[40:43], v[162:165], v[202:205], v[40:43]
	v_mfma_f32_16x16x32_bf16 v[28:31], v[132:135], v[212:215], v[28:31]
	v_mfma_f32_16x16x32_bf16 v[24:27], v[162:165], v[212:215], v[24:27]
	v_mfma_f32_16x16x32_bf16 v[12:15], v[132:135], v[220:223], v[12:15]
	v_mfma_f32_16x16x32_bf16 v[8:11], v[162:165], v[220:223], v[8:11]
	v_mfma_f32_16x16x32_bf16 v[52:55], v[174:177], v[190:193], v[52:55]
	v_mfma_f32_16x16x32_bf16 v[48:51], v[182:185], v[190:193], v[48:51]
	v_mfma_f32_16x16x32_bf16 v[36:39], v[174:177], v[198:201], v[36:39]
	v_mfma_f32_16x16x32_bf16 v[32:35], v[182:185], v[198:201], v[32:35]
	v_mfma_f32_16x16x32_bf16 v[20:23], v[174:177], v[208:211], v[20:23]
	v_mfma_f32_16x16x32_bf16 v[16:19], v[182:185], v[208:211], v[16:19]
	v_mfma_f32_16x16x32_bf16 v[4:7], v[174:177], v[216:219], v[4:7]
	v_mfma_f32_16x16x32_bf16 v[0:3], v[182:185], v[216:219], v[0:3]
	v_mfma_f32_16x16x32_bf16 v[52:55], v[178:181], v[194:197], v[52:55]
	v_mfma_f32_16x16x32_bf16 v[48:51], v[186:189], v[194:197], v[48:51]
	v_mfma_f32_16x16x32_bf16 v[36:39], v[178:181], v[202:205], v[36:39]
	v_mfma_f32_16x16x32_bf16 v[32:35], v[186:189], v[202:205], v[32:35]
	v_mfma_f32_16x16x32_bf16 v[20:23], v[178:181], v[212:215], v[20:23]
	v_mfma_f32_16x16x32_bf16 v[16:19], v[186:189], v[212:215], v[16:19]
	v_mfma_f32_16x16x32_bf16 v[4:7], v[178:181], v[220:223], v[4:7]
	v_mfma_f32_16x16x32_bf16 v[0:3], v[186:189], v[220:223], v[0:3]
	s_setprio 0
	s_barrier
	s_add_i32 s73, s73, 2
	s_add_u32 s74, s74, 0x100
	s_addc_u32 s75, s75, 0
	s_add_u32 s65, s65, 0x100
	s_addc_u32 s71, s71, 0
	s_cmp_gt_u32 s73, 29
	s_cbranch_scc0 .LBB0_392
	s_and_b64 vcc, exec, s[46:47]
	s_cbranch_vccz .LBB0_395
	s_barrier

; #define PG8_STAGE(bufoff, gbase, voff) do { _Pragma("unroll") for (int _i = 0; _i < 2; ++_i) \
;         __builtin_amdgcn_global_load_lds((const unsigned*)((const char*)(gbase) + (voff)[_i]), (LAS unsigned*)(lds + (bufoff) + ldsw + _i * 8192), 16, 0, 0); } while (0)
; #define PG8_LDA(dst, b, h) do { _Pragma("unroll") for (int m = 0; m < 4; ++m) _Pragma("unroll") for (int k = 0; k < 2; ++k) dst[m][k] = *(const LAS bf16x8*)(lds + PG8_SA(b, h) + aoff + m * 2048 + k * 1024); } while (0)
; #define PG8_LDB(dst, b, h) do { _Pragma("unroll") for (int n = 0; n < 2; ++n) _Pragma("unroll") for (int k = 0; k < 2; ++k) dst[n][k] = *(const LAS bf16x8*)(lds + PG8_SB(b, h) + boff + n * 2048 + k * 1024); } while (0)
; #define PG8_MMA(ai, bj, At, Bt) do { __builtin_amdgcn_s_setprio(1); _Pragma("unroll") for (int m = 0; m < 4; ++m) _Pragma("unroll") for (int n = 0; n < 2; ++n) _Pragma("unroll") for (int k = 0; k < 2; ++k) \
;         acc[ai][bj][m][n] = __builtin_amdgcn_mfma_f32_16x16x32_bf16(Bt[n][k], At[m][k], acc[ai][bj][m][n], 0, 0, 0); __builtin_amdgcn_s_setprio(0); } while (0)
; #define PG8_WAIT_V(n) asm volatile("s_waitcnt vmcnt(" #n ")" ::: "memory")
; #define PG8_WAIT_L(n) asm volatile("s_waitcnt lgkmcnt(" #n ")" ::: "memory")
; #define PG8_BAR __builtin_amdgcn_s_barrier()
; #define PG8_SCHED __builtin_amdgcn_sched_barrier(0)
; template <class Epi, class Sched, bool ALIGN_EPI, bool SP2>
; __device__ __forceinline__ void gemm_phase(LAS unsigned char* lds, const Gemm g, const Sched& S, const Epi& E) {
;     ...
;             PG8_LDB(B0, 0, 0); PG8_LDB(B1, 0, 1); PG8_SCHED; PG8_LDA(At, 0, 0); PG8_STAGE(PG8_SA(1, 1), a1 + hstep, voffA);
;             PG8_WAIT_V(8); PG8_WAIT_L(0); PG8_BAR; PG8_MMA(0, 0, At, B0); PG8_MMA(0, 1, At, B1); PG8_BAR; PG8_SCHED;
;             PG8_LDA(At, 0, 1); PG8_STAGE(PG8_SB(0, 0), b2, voffB); PG8_STAGE(PG8_SB(0, 1), b2 + hstepB, voffB); PG8_STAGE(PG8_SA(0, 0), a2, voffA);
;             PG8_WAIT_V(8); PG8_WAIT_L(0); PG8_BAR; PG8_MMA(1, 0, At, B0); PG8_MMA(1, 1, At, B1); PG8_BAR; PG8_SCHED;
.LBB0_429:
	ds_read_b128 v[148:151], v167
	ds_read_b128 v[152:155], v167 offset:1024
	ds_read_b128 v[156:159], v167 offset:2048
	ds_read_b128 v[170:173], v167 offset:3072
	ds_read_b128 v[174:177], v168
	ds_read_b128 v[178:181], v168 offset:1024
	ds_read_b128 v[182:185], v168 offset:2048
	ds_read_b128 v[186:189], v168 offset:3072
	s_add_u32 s14, s0, 0xfff80080
	s_addc_u32 s15, s1, -1
	s_cmp_eq_u32 s69, 28
	s_cselect_b32 s73, s33, s15
	s_cselect_b32 s72, s48, s14
	s_cselect_b32 s71, s65, s63
	s_cselect_b32 s70, s64, s49
	v_lshl_add_u64 v[160:161], s[0:1], 0, v[140:141]
	s_add_i32 m0, s74, 0xc000
	ds_read_b128 v[190:193], v169
	ds_read_b128 v[194:197], v169 offset:1024
	ds_read_b128 v[198:201], v169 offset:2048
	ds_read_b128 v[202:205], v169 offset:3072
	ds_read_b128 v[208:211], v169 offset:4096
	ds_read_b128 v[212:215], v169 offset:5120
	ds_read_b128 v[216:219], v169 offset:6144
	ds_read_b128 v[220:223], v169 offset:7168
	global_load_lds_dwordx4 v[160:161], off
	v_lshl_add_u64 v[160:161], s[0:1], 0, v[142:143]
	s_add_i32 m0, s74, 0xe000
	s_nop 0
	global_load_lds_dwordx4 v[160:161], off
	s_waitcnt vmcnt(8)
	s_waitcnt lgkmcnt(0)
	s_barrier
	s_setprio 1
	v_mfma_f32_16x16x32_bf16 v[124:127], v[148:151], v[190:193], v[124:127]
	v_mfma_f32_16x16x32_bf16 v[120:123], v[156:159], v[190:193], v[120:123]
	v_mfma_f32_16x16x32_bf16 v[116:119], v[148:151], v[198:201], v[116:119]
	v_mfma_f32_16x16x32_bf16 v[112:115], v[156:159], v[198:201], v[112:115]
	v_mfma_f32_16x16x32_bf16 v[108:111], v[148:151], v[208:211], v[108:111]
	v_mfma_f32_16x16x32_bf16 v[104:107], v[156:159], v[208:211], v[104:107]
	v_mfma_f32_16x16x32_bf16 v[100:103], v[148:151], v[216:219], v[100:103]
	v_mfma_f32_16x16x32_bf16 v[96:99], v[156:159], v[216:219], v[96:99]
	v_mfma_f32_16x16x32_bf16 v[124:127], v[152:155], v[194:197], v[124:127]
	v_mfma_f32_16x16x32_bf16 v[120:123], v[170:173], v[194:197], v[120:123]
	v_mfma_f32_16x16x32_bf16 v[116:119], v[152:155], v[202:205], v[116:119]
	v_mfma_f32_16x16x32_bf16 v[112:115], v[170:173], v[202:205], v[112:115]
	v_mfma_f32_16x16x32_bf16 v[108:111], v[152:155], v[212:215], v[108:111]
	v_mfma_f32_16x16x32_bf16 v[104:107], v[170:173], v[212:215], v[104:107]
	v_mfma_f32_16x16x32_bf16 v[100:103], v[152:155], v[220:223], v[100:103]
	v_mfma_f32_16x16x32_bf16 v[96:99], v[170:173], v[220:223], v[96:99]
	v_mfma_f32_16x16x32_bf16 v[68:71], v[174:177], v[190:193], v[68:71]
	v_mfma_f32_16x16x32_bf16 v[60:63], v[182:185], v[190:193], v[60:63]
	v_mfma_f32_16x16x32_bf16 v[52:55], v[174:177], v[198:201], v[52:55]
	v_mfma_f32_16x16x32_bf16 v[48:51], v[182:185], v[198:201], v[48:51]
	v_mfma_f32_16x16x32_bf16 v[44:47], v[174:177], v[208:211], v[44:47]
	v_mfma_f32_16x16x32_bf16 v[40:43], v[182:185], v[208:211], v[40:43]
	v_mfma_f32_16x16x32_bf16 v[36:39], v[174:177], v[216:219], v[36:39]
	v_mfma_f32_16x16x32_bf16 v[32:35], v[182:185], v[216:219], v[32:35]
	v_mfma_f32_16x16x32_bf16 v[68:71], v[178:181], v[194:197], v[68:71]
	v_mfma_f32_16x16x32_bf16 v[60:63], v[186:189], v[194:197], v[60:63]
	v_mfma_f32_16x16x32_bf16 v[52:55], v[178:181], v[202:205], v[52:55]
	v_mfma_f32_16x16x32_bf16 v[48:51], v[186:189], v[202:205], v[48:51]
	v_mfma_f32_16x16x32_bf16 v[44:47], v[178:181], v[212:215], v[44:47]
	v_mfma_f32_16x16x32_bf16 v[40:43], v[186:189], v[212:215], v[40:43]
	v_mfma_f32_16x16x32_bf16 v[36:39], v[178:181], v[220:223], v[36:39]
	v_mfma_f32_16x16x32_bf16 v[32:35], v[186:189], v[220:223], v[32:35]
	s_setprio 0
	s_barrier
	s_add_i32 s14, s81, s57
	v_lshl_add_u64 v[160:161], s[70:71], 0, v[132:133]
	s_mov_b32 m0, s14
	ds_read_b128 v[190:193], v169 offset:16384
	ds_read_b128 v[194:197], v169 offset:17408
	ds_read_b128 v[198:201], v169 offset:18432
	ds_read_b128 v[202:205], v169 offset:19456
	ds_read_b128 v[208:211], v169 offset:20480
	ds_read_b128 v[212:215], v169 offset:21504
	ds_read_b128 v[216:219], v169 offset:22528
	ds_read_b128 v[220:223], v169 offset:23552
	global_load_lds_dwordx4 v[160:161], off
	s_add_i32 m0, s14, 0x2000
	s_add_u32 s14, s70, 0x1000
	v_lshl_add_u64 v[224:225], s[70:71], 0, v[128:129]
	s_addc_u32 s15, s71, 0
	s_add_i32 s58, s82, s57
	global_load_lds_dwordx4 v[224:225], off
	v_lshl_add_u64 v[226:227], s[14:15], 0, v[132:133]
	s_mov_b32 m0, s58
	v_lshl_add_u64 v[228:229], s[72:73], 0, v[130:131]
	global_load_lds_dwordx4 v[226:227], off
	v_lshl_add_u64 v[226:227], s[14:15], 0, v[128:129]
	s_add_i32 m0, s58, 0x2000
	s_nop 0
	global_load_lds_dwordx4 v[226:227], off
	v_lshl_add_u64 v[226:227], s[72:73], 0, v[134:135]
	s_mov_b32 m0, s74
	s_nop 0
	global_load_lds_dwordx4 v[226:227], off
	s_mov_b32 m0, s75
	s_nop 0
	global_load_lds_dwordx4 v[228:229], off
	s_waitcnt vmcnt(8)
	s_waitcnt lgkmcnt(0)
	s_barrier
; #define PG8_STAGE(bufoff, gbase, voff) do { _Pragma("unroll") for (int _i = 0; _i < 2; ++_i) \
;         __builtin_amdgcn_global_load_lds((const unsigned*)((const char*)(gbase) + (voff)[_i]), (LAS unsigned*)(lds + (bufoff) + ldsw + _i * 8192), 16, 0, 0); } while (0)
; #define PG8_LDA(dst, b, h) do { _Pragma("unroll") for (int m = 0; m < 4; ++m) _Pragma("unroll") for (int k = 0; k < 2; ++k) dst[m][k] = *(const LAS bf16x8*)(lds + PG8_SA(b, h) + aoff + m * 2048 + k * 1024); } while (0)
; #define PG8_LDB(dst, b, h) do { _Pragma("unroll") for (int n = 0; n < 2; ++n) _Pragma("unroll") for (int k = 0; k < 2; ++k) dst[n][k] = *(const LAS bf16x8*)(lds + PG8_SB(b, h) + boff + n * 2048 + k * 1024); } while (0)
; #define PG8_MMA(ai, bj, At, Bt) do { __builtin_amdgcn_s_setprio(1); _Pragma("unroll") for (int m = 0; m < 4; ++m) _Pragma("unroll") for (int n = 0; n < 2; ++n) _Pragma("unroll") for (int k = 0; k < 2; ++k) \
;         acc[ai][bj][m][n] = __builtin_amdgcn_mfma_f32_16x16x32_bf16(Bt[n][k], At[m][k], acc[ai][bj][m][n], 0, 0, 0); __builtin_amdgcn_s_setprio(0); } while (0)
; #define PG8_WAIT_V(n) asm volatile("s_waitcnt vmcnt(" #n ")" ::: "memory")
; #define PG8_WAIT_L(n) asm volatile("s_waitcnt lgkmcnt(" #n ")" ::: "memory")
; #define PG8_BAR __builtin_amdgcn_s_barrier()
; #define PG8_SCHED __builtin_amdgcn_sched_barrier(0)
; template <class Epi, class Sched, bool ALIGN_EPI, bool SP2>
; __device__ __forceinline__ void gemm_phase(LAS unsigned char* lds, const Gemm g, const Sched& S, const Epi& E) {
;     ...
;             PG8_WAIT_V(8); PG8_WAIT_L(0); PG8_BAR; PG8_MMA(1, 0, At, B0); PG8_MMA(1, 1, At, B1); PG8_BAR; PG8_SCHED;
;             PG8_LDB(B0, 1, 0); PG8_LDB(B1, 1, 1); PG8_SCHED; PG8_LDA(At, 1, 0); PG8_STAGE(PG8_SA(0, 1), a2 + hstep, voffA);
;             PG8_WAIT_V(8); PG8_WAIT_L(0); PG8_BAR; PG8_MMA(0, 0, At, B0); PG8_MMA(0, 1, At, B1); PG8_BAR; PG8_SCHED;
	s_setprio 1
	v_mfma_f32_16x16x32_bf16 v[92:95], v[148:151], v[190:193], v[92:95]
	v_mfma_f32_16x16x32_bf16 v[88:91], v[156:159], v[190:193], v[88:91]
	v_mfma_f32_16x16x32_bf16 v[84:87], v[148:151], v[198:201], v[84:87]
	v_mfma_f32_16x16x32_bf16 v[80:83], v[156:159], v[198:201], v[80:83]
	v_mfma_f32_16x16x32_bf16 v[76:79], v[148:151], v[208:211], v[76:79]
	v_mfma_f32_16x16x32_bf16 v[72:75], v[156:159], v[208:211], v[72:75]
	v_mfma_f32_16x16x32_bf16 v[64:67], v[148:151], v[216:219], v[64:67]
	v_mfma_f32_16x16x32_bf16 v[56:59], v[156:159], v[216:219], v[56:59]
	v_mfma_f32_16x16x32_bf16 v[92:95], v[152:155], v[194:197], v[92:95]
	v_mfma_f32_16x16x32_bf16 v[88:91], v[170:173], v[194:197], v[88:91]
	v_mfma_f32_16x16x32_bf16 v[84:87], v[152:155], v[202:205], v[84:87]
	v_mfma_f32_16x16x32_bf16 v[80:83], v[170:173], v[202:205], v[80:83]
	v_mfma_f32_16x16x32_bf16 v[76:79], v[152:155], v[212:215], v[76:79]
	v_mfma_f32_16x16x32_bf16 v[72:75], v[170:173], v[212:215], v[72:75]
	v_mfma_f32_16x16x32_bf16 v[64:67], v[152:155], v[220:223], v[64:67]
	v_mfma_f32_16x16x32_bf16 v[56:59], v[170:173], v[220:223], v[56:59]
	v_mfma_f32_16x16x32_bf16 v[28:31], v[174:177], v[190:193], v[28:31]
	v_mfma_f32_16x16x32_bf16 v[24:27], v[182:185], v[190:193], v[24:27]
	v_mfma_f32_16x16x32_bf16 v[20:23], v[174:177], v[198:201], v[20:23]
	v_mfma_f32_16x16x32_bf16 v[16:19], v[182:185], v[198:201], v[16:19]
	v_mfma_f32_16x16x32_bf16 v[12:15], v[174:177], v[208:211], v[12:15]
	v_mfma_f32_16x16x32_bf16 v[8:11], v[182:185], v[208:211], v[8:11]
	v_mfma_f32_16x16x32_bf16 v[4:7], v[174:177], v[216:219], v[4:7]
	v_mfma_f32_16x16x32_bf16 v[0:3], v[182:185], v[216:219], v[0:3]
	v_mfma_f32_16x16x32_bf16 v[28:31], v[178:181], v[194:197], v[28:31]
	v_mfma_f32_16x16x32_bf16 v[24:27], v[186:189], v[194:197], v[24:27]
	v_mfma_f32_16x16x32_bf16 v[20:23], v[178:181], v[202:205], v[20:23]
	v_mfma_f32_16x16x32_bf16 v[16:19], v[186:189], v[202:205], v[16:19]
	v_mfma_f32_16x16x32_bf16 v[12:15], v[178:181], v[212:215], v[12:15]
	v_mfma_f32_16x16x32_bf16 v[8:11], v[186:189], v[212:215], v[8:11]
	v_mfma_f32_16x16x32_bf16 v[4:7], v[178:181], v[220:223], v[4:7]
	v_mfma_f32_16x16x32_bf16 v[0:3], v[186:189], v[220:223], v[0:3]
	s_setprio 0
	s_barrier
	s_add_i32 s58, 0, 0x18000
	s_add_i32 s85, 0, 0x1c000
	v_add_u32_e32 v170, s58, v163
	v_add_u32_e32 v186, s85, v163
	ds_read_b128 v[148:151], v170
	ds_read_b128 v[152:155], v170 offset:1024
	ds_read_b128 v[156:159], v170 offset:2048
	ds_read_b128 v[170:173], v170 offset:3072
	ds_read_b128 v[174:177], v186
	ds_read_b128 v[178:181], v186 offset:1024
	ds_read_b128 v[182:185], v186 offset:2048
	ds_read_b128 v[186:189], v186 offset:3072
	s_add_u32 s14, s72, 0x80000
	s_addc_u32 s15, s73, 0
	s_mov_b32 m0, s76
	v_lshl_add_u64 v[230:231], s[14:15], 0, v[134:135]
	ds_read_b128 v[190:193], v169 offset:32768
	ds_read_b128 v[194:197], v169 offset:33792
	ds_read_b128 v[198:201], v169 offset:34816
	ds_read_b128 v[202:205], v169 offset:35840
	ds_read_b128 v[208:211], v169 offset:36864
	ds_read_b128 v[212:215], v169 offset:37888
	ds_read_b128 v[216:219], v169 offset:38912
	ds_read_b128 v[220:223], v169 offset:39936
	global_load_lds_dwordx4 v[230:231], off
	v_lshl_add_u64 v[230:231], s[14:15], 0, v[130:131]
	s_mov_b32 m0, s77
	s_nop 0
	global_load_lds_dwordx4 v[230:231], off
	s_waitcnt vmcnt(8)
	s_waitcnt lgkmcnt(0)
	s_barrier
	s_setprio 1
	v_mfma_f32_16x16x32_bf16 v[124:127], v[148:151], v[190:193], v[124:127]
	v_mfma_f32_16x16x32_bf16 v[120:123], v[156:159], v[190:193], v[120:123]
	v_mfma_f32_16x16x32_bf16 v[116:119], v[148:151], v[198:201], v[116:119]
	v_mfma_f32_16x16x32_bf16 v[112:115], v[156:159], v[198:201], v[112:115]
	v_mfma_f32_16x16x32_bf16 v[108:111], v[148:151], v[208:211], v[108:111]
	v_mfma_f32_16x16x32_bf16 v[104:107], v[156:159], v[208:211], v[104:107]
	v_mfma_f32_16x16x32_bf16 v[100:103], v[148:151], v[216:219], v[100:103]
	v_mfma_f32_16x16x32_bf16 v[96:99], v[156:159], v[216:219], v[96:99]
	v_mfma_f32_16x16x32_bf16 v[124:127], v[152:155], v[194:197], v[124:127]
	v_mfma_f32_16x16x32_bf16 v[120:123], v[170:173], v[194:197], v[120:123]
	v_mfma_f32_16x16x32_bf16 v[116:119], v[152:155], v[202:205], v[116:119]
	v_mfma_f32_16x16x32_bf16 v[112:115], v[170:173], v[202:205], v[112:115]
	v_mfma_f32_16x16x32_bf16 v[108:111], v[152:155], v[212:215], v[108:111]
	v_mfma_f32_16x16x32_bf16 v[104:107], v[170:173], v[212:215], v[104:107]
	v_mfma_f32_16x16x32_bf16 v[100:103], v[152:155], v[220:223], v[100:103]
	v_mfma_f32_16x16x32_bf16 v[96:99], v[170:173], v[220:223], v[96:99]
	v_mfma_f32_16x16x32_bf16 v[68:71], v[174:177], v[190:193], v[68:71]
	v_mfma_f32_16x16x32_bf16 v[60:63], v[182:185], v[190:193], v[60:63]
	v_mfma_f32_16x16x32_bf16 v[52:55], v[174:177], v[198:201], v[52:55]
	v_mfma_f32_16x16x32_bf16 v[48:51], v[182:185], v[198:201], v[48:51]
	v_mfma_f32_16x16x32_bf16 v[44:47], v[174:177], v[208:211], v[44:47]
	v_mfma_f32_16x16x32_bf16 v[40:43], v[182:185], v[208:211], v[40:43]
	v_mfma_f32_16x16x32_bf16 v[36:39], v[174:177], v[216:219], v[36:39]
	v_mfma_f32_16x16x32_bf16 v[32:35], v[182:185], v[216:219], v[32:35]
	v_mfma_f32_16x16x32_bf16 v[68:71], v[178:181], v[194:197], v[68:71]
	v_mfma_f32_16x16x32_bf16 v[60:63], v[186:189], v[194:197], v[60:63]
	v_mfma_f32_16x16x32_bf16 v[52:55], v[178:181], v[202:205], v[52:55]
	v_mfma_f32_16x16x32_bf16 v[48:51], v[186:189], v[202:205], v[48:51]
	v_mfma_f32_16x16x32_bf16 v[44:47], v[178:181], v[212:215], v[44:47]
	v_mfma_f32_16x16x32_bf16 v[40:43], v[186:189], v[212:215], v[40:43]
	v_mfma_f32_16x16x32_bf16 v[36:39], v[178:181], v[220:223], v[36:39]
	v_mfma_f32_16x16x32_bf16 v[32:35], v[186:189], v[220:223], v[32:35]
	s_setprio 0
	s_barrier
; #define PG8_STAGE(bufoff, gbase, voff) do { _Pragma("unroll") for (int _i = 0; _i < 2; ++_i) \
;         __builtin_amdgcn_global_load_lds((const unsigned*)((const char*)(gbase) + (voff)[_i]), (LAS unsigned*)(lds + (bufoff) + ldsw + _i * 8192), 16, 0, 0); } while (0)
; #define PG8_LDA(dst, b, h) do { _Pragma("unroll") for (int m = 0; m < 4; ++m) _Pragma("unroll") for (int k = 0; k < 2; ++k) dst[m][k] = *(const LAS bf16x8*)(lds + PG8_SA(b, h) + aoff + m * 2048 + k * 1024); } while (0)
; #define PG8_MMA(ai, bj, At, Bt) do { __builtin_amdgcn_s_setprio(1); _Pragma("unroll") for (int m = 0; m < 4; ++m) _Pragma("unroll") for (int n = 0; n < 2; ++n) _Pragma("unroll") for (int k = 0; k < 2; ++k) \
;         acc[ai][bj][m][n] = __builtin_amdgcn_mfma_f32_16x16x32_bf16(Bt[n][k], At[m][k], acc[ai][bj][m][n], 0, 0, 0); __builtin_amdgcn_s_setprio(0); } while (0)
; #define PG8_WAIT_V(n) asm volatile("s_waitcnt vmcnt(" #n ")" ::: "memory")
; #define PG8_WAIT_L(n) asm volatile("s_waitcnt lgkmcnt(" #n ")" ::: "memory")
; #define PG8_BAR __builtin_amdgcn_s_barrier()
; #define PG8_SCHED __builtin_amdgcn_sched_barrier(0)
; template <class Epi, class Sched, bool ALIGN_EPI, bool SP2>
; __device__ __forceinline__ void gemm_phase(LAS unsigned char* lds, const Gemm g, const Sched& S, const Epi& E) {
;     ...
;         for (int t = tb; t < te; t += 2) {
;             const bool last = (t == nt - 2);
;             const char* a1 = cA + (size_t)(t + 1) * kstep;
;             const char* a2 = last ? nA : cA + (size_t)(t + 2) * kstep; const char* b2 = last ? nB : cB + (size_t)(t + 2) * kstep;
;             const char* a3 = a2 + kstep; const char* b3 = b2 + kstep;
;             if (last && has_next) S.a_ready(nxt);
;     ...
;             PG8_LDA(At, 1, 1); PG8_STAGE(PG8_SB(1, 0), b3, voffB); PG8_STAGE(PG8_SB(1, 1), b3 + hstepB, voffB); PG8_STAGE(PG8_SA(1, 0), a3, voffA);
;             PG8_WAIT_V(8); PG8_WAIT_L(0); PG8_BAR; PG8_MMA(1, 0, At, B0); PG8_MMA(1, 1, At, B1); PG8_BAR; PG8_SCHED;
	s_add_i32 s14, s58, s57
	v_lshl_add_u64 v[160:161], v[160:161], 0, s[44:45]
	s_mov_b32 m0, s14
	ds_read_b128 v[190:193], v169 offset:49152
	ds_read_b128 v[194:197], v169 offset:50176
	ds_read_b128 v[198:201], v169 offset:51200
	ds_read_b128 v[202:205], v169 offset:52224
	ds_read_b128 v[208:211], v169 offset:53248
	ds_read_b128 v[212:215], v169 offset:54272
	ds_read_b128 v[216:219], v169 offset:55296
	ds_read_b128 v[220:223], v169 offset:56320
	global_load_lds_dwordx4 v[160:161], off
	s_add_i32 m0, s14, 0x2000
	s_add_u32 s14, s70, 0x1080
	v_lshl_add_u64 v[160:161], v[224:225], 0, s[44:45]
	s_addc_u32 s15, s71, 0
	s_add_i32 s58, s85, s57
	global_load_lds_dwordx4 v[160:161], off
	v_lshl_add_u64 v[160:161], s[14:15], 0, v[132:133]
	s_mov_b32 m0, s58
	s_nop 0
	global_load_lds_dwordx4 v[160:161], off
	v_lshl_add_u64 v[160:161], s[14:15], 0, v[128:129]
	s_add_i32 m0, s58, 0x2000
	s_nop 0
	global_load_lds_dwordx4 v[160:161], off
	v_lshl_add_u64 v[160:161], v[226:227], 0, s[44:45]
	s_mov_b32 m0, s79
	s_nop 0
	global_load_lds_dwordx4 v[160:161], off
	v_lshl_add_u64 v[160:161], v[228:229], 0, s[44:45]
	s_mov_b32 m0, s80
	s_nop 0
	global_load_lds_dwordx4 v[160:161], off
	s_waitcnt vmcnt(8)
	s_waitcnt lgkmcnt(0)
	s_barrier
	s_setprio 1
	v_mfma_f32_16x16x32_bf16 v[92:95], v[148:151], v[190:193], v[92:95]
	v_mfma_f32_16x16x32_bf16 v[88:91], v[156:159], v[190:193], v[88:91]
	v_mfma_f32_16x16x32_bf16 v[84:87], v[148:151], v[198:201], v[84:87]
	v_mfma_f32_16x16x32_bf16 v[80:83], v[156:159], v[198:201], v[80:83]
	v_mfma_f32_16x16x32_bf16 v[76:79], v[148:151], v[208:211], v[76:79]
	v_mfma_f32_16x16x32_bf16 v[72:75], v[156:159], v[208:211], v[72:75]
	v_mfma_f32_16x16x32_bf16 v[64:67], v[148:151], v[216:219], v[64:67]
	v_mfma_f32_16x16x32_bf16 v[56:59], v[156:159], v[216:219], v[56:59]
	v_mfma_f32_16x16x32_bf16 v[92:95], v[152:155], v[194:197], v[92:95]
	v_mfma_f32_16x16x32_bf16 v[88:91], v[170:173], v[194:197], v[88:91]
	v_mfma_f32_16x16x32_bf16 v[84:87], v[152:155], v[202:205], v[84:87]
	v_mfma_f32_16x16x32_bf16 v[80:83], v[170:173], v[202:205], v[80:83]
	v_mfma_f32_16x16x32_bf16 v[76:79], v[152:155], v[212:215], v[76:79]
	v_mfma_f32_16x16x32_bf16 v[72:75], v[170:173], v[212:215], v[72:75]
	v_mfma_f32_16x16x32_bf16 v[64:67], v[152:155], v[220:223], v[64:67]
	v_mfma_f32_16x16x32_bf16 v[56:59], v[170:173], v[220:223], v[56:59]
	v_mfma_f32_16x16x32_bf16 v[28:31], v[174:177], v[190:193], v[28:31]
	v_mfma_f32_16x16x32_bf16 v[24:27], v[182:185], v[190:193], v[24:27]
	v_mfma_f32_16x16x32_bf16 v[20:23], v[174:177], v[198:201], v[20:23]
	v_mfma_f32_16x16x32_bf16 v[16:19], v[182:185], v[198:201], v[16:19]
	v_mfma_f32_16x16x32_bf16 v[12:15], v[174:177], v[208:211], v[12:15]
	v_mfma_f32_16x16x32_bf16 v[8:11], v[182:185], v[208:211], v[8:11]
	v_mfma_f32_16x16x32_bf16 v[4:7], v[174:177], v[216:219], v[4:7]
	v_mfma_f32_16x16x32_bf16 v[0:3], v[182:185], v[216:219], v[0:3]
	v_mfma_f32_16x16x32_bf16 v[28:31], v[178:181], v[194:197], v[28:31]
	v_mfma_f32_16x16x32_bf16 v[24:27], v[186:189], v[194:197], v[24:27]
	v_mfma_f32_16x16x32_bf16 v[20:23], v[178:181], v[202:205], v[20:23]
	v_mfma_f32_16x16x32_bf16 v[16:19], v[186:189], v[202:205], v[16:19]
	v_mfma_f32_16x16x32_bf16 v[12:15], v[178:181], v[212:215], v[12:15]
	v_mfma_f32_16x16x32_bf16 v[8:11], v[186:189], v[212:215], v[8:11]
	v_mfma_f32_16x16x32_bf16 v[4:7], v[178:181], v[220:223], v[4:7]
	v_mfma_f32_16x16x32_bf16 v[0:3], v[186:189], v[220:223], v[0:3]
	s_setprio 0
	s_barrier
	s_add_i32 s69, s69, 2
	s_add_u32 s0, s0, 0x100
	s_addc_u32 s1, s1, 0
	s_add_u32 s49, s49, 0x100
	s_addc_u32 s63, s63, 0
	s_cmp_gt_u32 s69, 29
	s_cbranch_scc0 .LBB0_429
	s_and_b64 vcc, exec, s[46:47]
	s_cbranch_vccz .LBB0_432
	s_barrier

; #define PG8_STAGE(bufoff, gbase, voff) do { _Pragma("unroll") for (int _i = 0; _i < 2; ++_i) \
;         __builtin_amdgcn_global_load_lds((const unsigned*)((const char*)(gbase) + (voff)[_i]), (LAS unsigned*)(lds + (bufoff) + ldsw + _i * 8192), 16, 0, 0); } while (0)
; #define PG8_LDA(dst, b, h) do { _Pragma("unroll") for (int m = 0; m < 4; ++m) _Pragma("unroll") for (int k = 0; k < 2; ++k) dst[m][k] = *(const LAS bf16x8*)(lds + PG8_SA(b, h) + aoff + m * 2048 + k * 1024); } while (0)
; #define PG8_LDB(dst, b, h) do { _Pragma("unroll") for (int n = 0; n < 2; ++n) _Pragma("unroll") for (int k = 0; k < 2; ++k) dst[n][k] = *(const LAS bf16x8*)(lds + PG8_SB(b, h) + boff + n * 2048 + k * 1024); } while (0)
; #define PG8_MMA(ai, bj, At, Bt) do { __builtin_amdgcn_s_setprio(1); _Pragma("unroll") for (int m = 0; m < 4; ++m) _Pragma("unroll") for (int n = 0; n < 2; ++n) _Pragma("unroll") for (int k = 0; k < 2; ++k) \
;         acc[ai][bj][m][n] = __builtin_amdgcn_mfma_f32_16x16x32_bf16(Bt[n][k], At[m][k], acc[ai][bj][m][n], 0, 0, 0); __builtin_amdgcn_s_setprio(0); } while (0)
; #define PG8_WAIT_V(n) asm volatile("s_waitcnt vmcnt(" #n ")" ::: "memory")
; #define PG8_WAIT_L(n) asm volatile("s_waitcnt lgkmcnt(" #n ")" ::: "memory")
; #define PG8_BAR __builtin_amdgcn_s_barrier()
; #define PG8_SCHED __builtin_amdgcn_sched_barrier(0)
; template <class Epi, class Sched, bool ALIGN_EPI, bool SP2>
; __device__ __forceinline__ void gemm_phase(LAS unsigned char* lds, const Gemm g, const Sched& S, const Epi& E) {
;     ...
;             PG8_LDB(B0, 0, 0); PG8_LDB(B1, 0, 1); PG8_SCHED; PG8_LDA(At, 0, 0); PG8_STAGE(PG8_SA(1, 1), a1 + hstep, voffA);
;             PG8_WAIT_V(8); PG8_WAIT_L(0); PG8_BAR; PG8_MMA(0, 0, At, B0); PG8_MMA(0, 1, At, B1); PG8_BAR; PG8_SCHED;
;             PG8_LDA(At, 0, 1); PG8_STAGE(PG8_SB(0, 0), b2, voffB); PG8_STAGE(PG8_SB(0, 1), b2 + hstepB, voffB); PG8_STAGE(PG8_SA(0, 0), a2, voffA);
;             PG8_WAIT_V(8); PG8_WAIT_L(0); PG8_BAR; PG8_MMA(1, 0, At, B0); PG8_MMA(1, 1, At, B1); PG8_BAR; PG8_SCHED;
.LBB0_502:
	ds_read_b128 v[158:161], v153
	ds_read_b128 v[162:165], v153 offset:1024
	ds_read_b128 v[166:169], v153 offset:2048
	ds_read_b128 v[170:173], v153 offset:3072
	ds_read_b128 v[174:177], v154
	ds_read_b128 v[178:181], v154 offset:1024
	ds_read_b128 v[182:185], v154 offset:2048
	ds_read_b128 v[186:189], v154 offset:3072
	s_add_i32 s90, s66, 2
	s_add_u32 s14, s64, 0x80
	s_addc_u32 s15, s65, 0
	s_cmp_eq_u32 s79, s66
	s_cselect_b32 s66, s0, s14
	s_cselect_b32 s67, s1, s15
	s_cselect_b32 s15, s63, s49
	s_cselect_b32 s14, s62, s33
	s_mov_b32 m0, s81
	v_lshl_add_u64 v[224:225], s[64:65], 0, v[140:141]
	ds_read_b128 v[190:193], v155
	ds_read_b128 v[194:197], v155 offset:1024
	ds_read_b128 v[198:201], v155 offset:2048
	ds_read_b128 v[202:205], v155 offset:3072
	ds_read_b128 v[208:211], v155 offset:4096
	ds_read_b128 v[212:215], v155 offset:5120
	ds_read_b128 v[216:219], v155 offset:6144
	ds_read_b128 v[220:223], v155 offset:7168
	global_load_lds_dwordx4 v[224:225], off
	v_lshl_add_u64 v[224:225], s[64:65], 0, v[142:143]
	s_mov_b32 m0, s82
	s_nop 0
	global_load_lds_dwordx4 v[224:225], off
	s_waitcnt vmcnt(8)
	s_waitcnt lgkmcnt(0)
	s_barrier
	s_setprio 1
	v_mfma_f32_16x16x32_bf16 v[124:127], v[158:161], v[190:193], v[124:127]
	v_mfma_f32_16x16x32_bf16 v[116:119], v[166:169], v[190:193], v[116:119]
	v_mfma_f32_16x16x32_bf16 v[92:95], v[158:161], v[198:201], v[92:95]
	v_mfma_f32_16x16x32_bf16 v[84:87], v[166:169], v[198:201], v[84:87]
	v_mfma_f32_16x16x32_bf16 v[60:63], v[158:161], v[208:211], v[60:63]
	v_mfma_f32_16x16x32_bf16 v[52:55], v[166:169], v[208:211], v[52:55]
	v_mfma_f32_16x16x32_bf16 v[28:31], v[158:161], v[216:219], v[28:31]
	v_mfma_f32_16x16x32_bf16 v[20:23], v[166:169], v[216:219], v[20:23]
	v_mfma_f32_16x16x32_bf16 v[124:127], v[162:165], v[194:197], v[124:127]
	v_mfma_f32_16x16x32_bf16 v[116:119], v[170:173], v[194:197], v[116:119]
	v_mfma_f32_16x16x32_bf16 v[92:95], v[162:165], v[202:205], v[92:95]
	v_mfma_f32_16x16x32_bf16 v[84:87], v[170:173], v[202:205], v[84:87]
	v_mfma_f32_16x16x32_bf16 v[60:63], v[162:165], v[212:215], v[60:63]
	v_mfma_f32_16x16x32_bf16 v[52:55], v[170:173], v[212:215], v[52:55]
	v_mfma_f32_16x16x32_bf16 v[28:31], v[162:165], v[220:223], v[28:31]
	v_mfma_f32_16x16x32_bf16 v[20:23], v[170:173], v[220:223], v[20:23]
	v_mfma_f32_16x16x32_bf16 v[108:111], v[174:177], v[190:193], v[108:111]
	v_mfma_f32_16x16x32_bf16 v[100:103], v[182:185], v[190:193], v[100:103]
	v_mfma_f32_16x16x32_bf16 v[76:79], v[174:177], v[198:201], v[76:79]
	v_mfma_f32_16x16x32_bf16 v[68:71], v[182:185], v[198:201], v[68:71]
	v_mfma_f32_16x16x32_bf16 v[44:47], v[174:177], v[208:211], v[44:47]
	v_mfma_f32_16x16x32_bf16 v[36:39], v[182:185], v[208:211], v[36:39]
	v_mfma_f32_16x16x32_bf16 v[12:15], v[174:177], v[216:219], v[12:15]
	v_mfma_f32_16x16x32_bf16 v[4:7], v[182:185], v[216:219], v[4:7]
	v_mfma_f32_16x16x32_bf16 v[108:111], v[178:181], v[194:197], v[108:111]
	v_mfma_f32_16x16x32_bf16 v[100:103], v[186:189], v[194:197], v[100:103]
	v_mfma_f32_16x16x32_bf16 v[76:79], v[178:181], v[202:205], v[76:79]
	v_mfma_f32_16x16x32_bf16 v[68:71], v[186:189], v[202:205], v[68:71]
	v_mfma_f32_16x16x32_bf16 v[44:47], v[178:181], v[212:215], v[44:47]
	v_mfma_f32_16x16x32_bf16 v[36:39], v[186:189], v[212:215], v[36:39]
	v_mfma_f32_16x16x32_bf16 v[12:15], v[178:181], v[220:223], v[12:15]
	v_mfma_f32_16x16x32_bf16 v[4:7], v[186:189], v[220:223], v[4:7]
	s_setprio 0
	s_barrier
	s_mov_b32 m0, s83
	v_lshl_add_u64 v[224:225], s[14:15], 0, v[132:133]
	v_lshl_add_u64 v[226:227], s[14:15], 0, v[128:129]
	s_add_u32 s14, s14, s8
	ds_read_b128 v[190:193], v155 offset:16384
	ds_read_b128 v[194:197], v155 offset:17408
	ds_read_b128 v[198:201], v155 offset:18432
	ds_read_b128 v[202:205], v155 offset:19456
	ds_read_b128 v[208:211], v155 offset:20480
	ds_read_b128 v[212:215], v155 offset:21504
	ds_read_b128 v[216:219], v155 offset:22528
	ds_read_b128 v[220:223], v155 offset:23552
	global_load_lds_dwordx4 v[224:225], off
	s_mov_b32 m0, s84
	s_addc_u32 s15, s15, s9
	global_load_lds_dwordx4 v[226:227], off
	v_lshl_add_u64 v[228:229], s[14:15], 0, v[132:133]
	s_mov_b32 m0, s85
	v_lshl_add_u64 v[230:231], s[14:15], 0, v[128:129]
	global_load_lds_dwordx4 v[228:229], off
	s_mov_b32 m0, s86
	v_lshl_add_u64 v[232:233], s[66:67], 0, v[134:135]
	global_load_lds_dwordx4 v[230:231], off
	s_mov_b32 m0, s71
	v_lshl_add_u64 v[234:235], s[66:67], 0, v[130:131]
	global_load_lds_dwordx4 v[232:233], off
	s_mov_b32 m0, s72
	s_nop 0
	global_load_lds_dwordx4 v[234:235], off
	s_waitcnt vmcnt(8)
	s_waitcnt lgkmcnt(0)
	s_barrier
; #define PG8_STAGE(bufoff, gbase, voff) do { _Pragma("unroll") for (int _i = 0; _i < 2; ++_i) \
;         __builtin_amdgcn_global_load_lds((const unsigned*)((const char*)(gbase) + (voff)[_i]), (LAS unsigned*)(lds + (bufoff) + ldsw + _i * 8192), 16, 0, 0); } while (0)
; #define PG8_LDA(dst, b, h) do { _Pragma("unroll") for (int m = 0; m < 4; ++m) _Pragma("unroll") for (int k = 0; k < 2; ++k) dst[m][k] = *(const LAS bf16x8*)(lds + PG8_SA(b, h) + aoff + m * 2048 + k * 1024); } while (0)
; #define PG8_LDB(dst, b, h) do { _Pragma("unroll") for (int n = 0; n < 2; ++n) _Pragma("unroll") for (int k = 0; k < 2; ++k) dst[n][k] = *(const LAS bf16x8*)(lds + PG8_SB(b, h) + boff + n * 2048 + k * 1024); } while (0)
; #define PG8_MMA(ai, bj, At, Bt) do { __builtin_amdgcn_s_setprio(1); _Pragma("unroll") for (int m = 0; m < 4; ++m) _Pragma("unroll") for (int n = 0; n < 2; ++n) _Pragma("unroll") for (int k = 0; k < 2; ++k) \
;         acc[ai][bj][m][n] = __builtin_amdgcn_mfma_f32_16x16x32_bf16(Bt[n][k], At[m][k], acc[ai][bj][m][n], 0, 0, 0); __builtin_amdgcn_s_setprio(0); } while (0)
; #define PG8_WAIT_V(n) asm volatile("s_waitcnt vmcnt(" #n ")" ::: "memory")
; #define PG8_WAIT_L(n) asm volatile("s_waitcnt lgkmcnt(" #n ")" ::: "memory")
; #define PG8_BAR __builtin_amdgcn_s_barrier()
; #define PG8_SCHED __builtin_amdgcn_sched_barrier(0)
; template <class Epi, class Sched, bool ALIGN_EPI, bool SP2>
; __device__ __forceinline__ void gemm_phase(LAS unsigned char* lds, const Gemm g, const Sched& S, const Epi& E) {
;     ...
;             PG8_WAIT_V(8); PG8_WAIT_L(0); PG8_BAR; PG8_MMA(1, 0, At, B0); PG8_MMA(1, 1, At, B1); PG8_BAR; PG8_SCHED;
;             PG8_LDB(B0, 1, 0); PG8_LDB(B1, 1, 1); PG8_SCHED; PG8_LDA(At, 1, 0); PG8_STAGE(PG8_SA(0, 1), a2 + hstep, voffA);
;             PG8_WAIT_V(8); PG8_WAIT_L(0); PG8_BAR; PG8_MMA(0, 0, At, B0); PG8_MMA(0, 1, At, B1); PG8_BAR; PG8_SCHED;
	s_setprio 1
	v_mfma_f32_16x16x32_bf16 v[120:123], v[158:161], v[190:193], v[120:123]
	v_mfma_f32_16x16x32_bf16 v[112:115], v[166:169], v[190:193], v[112:115]
	v_mfma_f32_16x16x32_bf16 v[88:91], v[158:161], v[198:201], v[88:91]
	v_mfma_f32_16x16x32_bf16 v[80:83], v[166:169], v[198:201], v[80:83]
	v_mfma_f32_16x16x32_bf16 v[56:59], v[158:161], v[208:211], v[56:59]
	v_mfma_f32_16x16x32_bf16 v[48:51], v[166:169], v[208:211], v[48:51]
	v_mfma_f32_16x16x32_bf16 v[24:27], v[158:161], v[216:219], v[24:27]
	v_mfma_f32_16x16x32_bf16 v[16:19], v[166:169], v[216:219], v[16:19]
	v_mfma_f32_16x16x32_bf16 v[120:123], v[162:165], v[194:197], v[120:123]
	v_mfma_f32_16x16x32_bf16 v[112:115], v[170:173], v[194:197], v[112:115]
	v_mfma_f32_16x16x32_bf16 v[88:91], v[162:165], v[202:205], v[88:91]
	v_mfma_f32_16x16x32_bf16 v[80:83], v[170:173], v[202:205], v[80:83]
	v_mfma_f32_16x16x32_bf16 v[56:59], v[162:165], v[212:215], v[56:59]
	v_mfma_f32_16x16x32_bf16 v[48:51], v[170:173], v[212:215], v[48:51]
	v_mfma_f32_16x16x32_bf16 v[24:27], v[162:165], v[220:223], v[24:27]
	v_mfma_f32_16x16x32_bf16 v[16:19], v[170:173], v[220:223], v[16:19]
	v_mfma_f32_16x16x32_bf16 v[104:107], v[174:177], v[190:193], v[104:107]
	v_mfma_f32_16x16x32_bf16 v[96:99], v[182:185], v[190:193], v[96:99]
	v_mfma_f32_16x16x32_bf16 v[72:75], v[174:177], v[198:201], v[72:75]
	v_mfma_f32_16x16x32_bf16 v[64:67], v[182:185], v[198:201], v[64:67]
	v_mfma_f32_16x16x32_bf16 v[40:43], v[174:177], v[208:211], v[40:43]
	v_mfma_f32_16x16x32_bf16 v[32:35], v[182:185], v[208:211], v[32:35]
	v_mfma_f32_16x16x32_bf16 v[8:11], v[174:177], v[216:219], v[8:11]
	v_mfma_f32_16x16x32_bf16 v[0:3], v[182:185], v[216:219], v[0:3]
	v_mfma_f32_16x16x32_bf16 v[104:107], v[178:181], v[194:197], v[104:107]
	v_mfma_f32_16x16x32_bf16 v[96:99], v[186:189], v[194:197], v[96:99]
	v_mfma_f32_16x16x32_bf16 v[72:75], v[178:181], v[202:205], v[72:75]
	v_mfma_f32_16x16x32_bf16 v[64:67], v[186:189], v[202:205], v[64:67]
	v_mfma_f32_16x16x32_bf16 v[40:43], v[178:181], v[212:215], v[40:43]
	v_mfma_f32_16x16x32_bf16 v[32:35], v[186:189], v[212:215], v[32:35]
	v_mfma_f32_16x16x32_bf16 v[8:11], v[178:181], v[220:223], v[8:11]
	v_mfma_f32_16x16x32_bf16 v[0:3], v[186:189], v[220:223], v[0:3]
	s_setprio 0
	s_barrier
	s_add_i32 s58, 0, 0x1c000
	v_add_u32_e32 v136, s58, v149
	ds_read_b128 v[158:161], v156
	ds_read_b128 v[162:165], v156 offset:1024
	ds_read_b128 v[166:169], v156 offset:2048
	ds_read_b128 v[170:173], v156 offset:3072
	ds_read_b128 v[174:177], v136
	ds_read_b128 v[178:181], v136 offset:1024
	ds_read_b128 v[182:185], v136 offset:2048
	ds_read_b128 v[186:189], v136 offset:3072
	s_add_u32 s14, s66, s8
	s_addc_u32 s15, s67, s9
	s_mov_b32 m0, s73
	v_lshl_add_u64 v[236:237], s[14:15], 0, v[134:135]
	ds_read_b128 v[190:193], v155 offset:32768
	ds_read_b128 v[194:197], v155 offset:33792
	ds_read_b128 v[198:201], v155 offset:34816
	ds_read_b128 v[202:205], v155 offset:35840
	ds_read_b128 v[208:211], v155 offset:36864
	ds_read_b128 v[212:215], v155 offset:37888
	ds_read_b128 v[216:219], v155 offset:38912
	ds_read_b128 v[220:223], v155 offset:39936
	global_load_lds_dwordx4 v[236:237], off
	v_lshl_add_u64 v[236:237], s[14:15], 0, v[130:131]
	s_mov_b32 m0, s74
	s_nop 0
	global_load_lds_dwordx4 v[236:237], off
	s_waitcnt vmcnt(8)
	s_waitcnt lgkmcnt(0)
	s_barrier
	s_setprio 1
	v_mfma_f32_16x16x32_bf16 v[124:127], v[158:161], v[190:193], v[124:127]
	v_mfma_f32_16x16x32_bf16 v[116:119], v[166:169], v[190:193], v[116:119]
	v_mfma_f32_16x16x32_bf16 v[92:95], v[158:161], v[198:201], v[92:95]
	v_mfma_f32_16x16x32_bf16 v[84:87], v[166:169], v[198:201], v[84:87]
	v_mfma_f32_16x16x32_bf16 v[60:63], v[158:161], v[208:211], v[60:63]
	v_mfma_f32_16x16x32_bf16 v[52:55], v[166:169], v[208:211], v[52:55]
	v_mfma_f32_16x16x32_bf16 v[28:31], v[158:161], v[216:219], v[28:31]
	v_mfma_f32_16x16x32_bf16 v[20:23], v[166:169], v[216:219], v[20:23]
	v_mfma_f32_16x16x32_bf16 v[124:127], v[162:165], v[194:197], v[124:127]
	v_mfma_f32_16x16x32_bf16 v[116:119], v[170:173], v[194:197], v[116:119]
	v_mfma_f32_16x16x32_bf16 v[92:95], v[162:165], v[202:205], v[92:95]
	v_mfma_f32_16x16x32_bf16 v[84:87], v[170:173], v[202:205], v[84:87]
	v_mfma_f32_16x16x32_bf16 v[60:63], v[162:165], v[212:215], v[60:63]
	v_mfma_f32_16x16x32_bf16 v[52:55], v[170:173], v[212:215], v[52:55]
	v_mfma_f32_16x16x32_bf16 v[28:31], v[162:165], v[220:223], v[28:31]
	v_mfma_f32_16x16x32_bf16 v[20:23], v[170:173], v[220:223], v[20:23]
	v_mfma_f32_16x16x32_bf16 v[108:111], v[174:177], v[190:193], v[108:111]
	v_mfma_f32_16x16x32_bf16 v[100:103], v[182:185], v[190:193], v[100:103]
	v_mfma_f32_16x16x32_bf16 v[76:79], v[174:177], v[198:201], v[76:79]
	v_mfma_f32_16x16x32_bf16 v[68:71], v[182:185], v[198:201], v[68:71]
	v_mfma_f32_16x16x32_bf16 v[44:47], v[174:177], v[208:211], v[44:47]
	v_mfma_f32_16x16x32_bf16 v[36:39], v[182:185], v[208:211], v[36:39]
	v_mfma_f32_16x16x32_bf16 v[12:15], v[174:177], v[216:219], v[12:15]
	v_mfma_f32_16x16x32_bf16 v[4:7], v[182:185], v[216:219], v[4:7]
	v_mfma_f32_16x16x32_bf16 v[108:111], v[178:181], v[194:197], v[108:111]
	v_mfma_f32_16x16x32_bf16 v[100:103], v[186:189], v[194:197], v[100:103]
	v_mfma_f32_16x16x32_bf16 v[76:79], v[178:181], v[202:205], v[76:79]
	v_mfma_f32_16x16x32_bf16 v[68:71], v[186:189], v[202:205], v[68:71]
	v_mfma_f32_16x16x32_bf16 v[44:47], v[178:181], v[212:215], v[44:47]
	v_mfma_f32_16x16x32_bf16 v[36:39], v[186:189], v[212:215], v[36:39]
	v_mfma_f32_16x16x32_bf16 v[12:15], v[178:181], v[220:223], v[12:15]
	v_mfma_f32_16x16x32_bf16 v[4:7], v[186:189], v[220:223], v[4:7]
	s_setprio 0
	s_barrier
; #define PG8_STAGE(bufoff, gbase, voff) do { _Pragma("unroll") for (int _i = 0; _i < 2; ++_i) \
;         __builtin_amdgcn_global_load_lds((const unsigned*)((const char*)(gbase) + (voff)[_i]), (LAS unsigned*)(lds + (bufoff) + ldsw + _i * 8192), 16, 0, 0); } while (0)
; #define PG8_LDA(dst, b, h) do { _Pragma("unroll") for (int m = 0; m < 4; ++m) _Pragma("unroll") for (int k = 0; k < 2; ++k) dst[m][k] = *(const LAS bf16x8*)(lds + PG8_SA(b, h) + aoff + m * 2048 + k * 1024); } while (0)
; #define PG8_MMA(ai, bj, At, Bt) do { __builtin_amdgcn_s_setprio(1); _Pragma("unroll") for (int m = 0; m < 4; ++m) _Pragma("unroll") for (int n = 0; n < 2; ++n) _Pragma("unroll") for (int k = 0; k < 2; ++k) \
;         acc[ai][bj][m][n] = __builtin_amdgcn_mfma_f32_16x16x32_bf16(Bt[n][k], At[m][k], acc[ai][bj][m][n], 0, 0, 0); __builtin_amdgcn_s_setprio(0); } while (0)
; #define PG8_WAIT_V(n) asm volatile("s_waitcnt vmcnt(" #n ")" ::: "memory")
; #define PG8_WAIT_L(n) asm volatile("s_waitcnt lgkmcnt(" #n ")" ::: "memory")
; #define PG8_BAR __builtin_amdgcn_s_barrier()
; #define PG8_SCHED __builtin_amdgcn_sched_barrier(0)
; template <class Epi, class Sched, bool ALIGN_EPI, bool SP2>
; __device__ __forceinline__ void gemm_phase(LAS unsigned char* lds, const Gemm g, const Sched& S, const Epi& E) {
;     ...
;         for (int t = tb; t < te; t += 2) {
;             const bool last = (t == nt - 2);
;             const char* a1 = cA + (size_t)(t + 1) * kstep;
;             const char* a2 = last ? nA : cA + (size_t)(t + 2) * kstep; const char* b2 = last ? nB : cB + (size_t)(t + 2) * kstep;
;             const char* a3 = a2 + kstep; const char* b3 = b2 + kstep;
;             if (last && has_next) S.a_ready(nxt);
;     ...
;             PG8_LDA(At, 1, 1); PG8_STAGE(PG8_SB(1, 0), b3, voffB); PG8_STAGE(PG8_SB(1, 1), b3 + hstepB, voffB); PG8_STAGE(PG8_SA(1, 0), a3, voffA);
;             PG8_WAIT_V(8); PG8_WAIT_L(0); PG8_BAR; PG8_MMA(1, 0, At, B0); PG8_MMA(1, 1, At, B1); PG8_BAR; PG8_SCHED;
	s_add_i32 s14, s87, s57
	v_lshl_add_u64 v[224:225], v[224:225], 0, s[44:45]
	s_mov_b32 m0, s14
	ds_read_b128 v[190:193], v155 offset:49152
	ds_read_b128 v[194:197], v155 offset:50176
	ds_read_b128 v[198:201], v155 offset:51200
	ds_read_b128 v[202:205], v155 offset:52224
	ds_read_b128 v[208:211], v155 offset:53248
	ds_read_b128 v[212:215], v155 offset:54272
	ds_read_b128 v[216:219], v155 offset:55296
	ds_read_b128 v[220:223], v155 offset:56320
	global_load_lds_dwordx4 v[224:225], off
	v_lshl_add_u64 v[224:225], v[226:227], 0, s[44:45]
	s_add_i32 m0, s14, 0x2000
	s_add_i32 s14, s58, s57
	global_load_lds_dwordx4 v[224:225], off
	v_lshl_add_u64 v[224:225], v[228:229], 0, s[44:45]
	s_mov_b32 m0, s14
	s_nop 0
	global_load_lds_dwordx4 v[224:225], off
	v_lshl_add_u64 v[224:225], v[230:231], 0, s[44:45]
	s_add_i32 m0, s14, 0x2000
	s_nop 0
	global_load_lds_dwordx4 v[224:225], off
	v_lshl_add_u64 v[224:225], v[232:233], 0, s[44:45]
	s_mov_b32 m0, s76
	s_nop 0
	global_load_lds_dwordx4 v[224:225], off
	v_lshl_add_u64 v[224:225], v[234:235], 0, s[44:45]
	s_mov_b32 m0, s77
	s_nop 0
	global_load_lds_dwordx4 v[224:225], off
	s_waitcnt vmcnt(8)
	s_waitcnt lgkmcnt(0)
	s_barrier
	s_setprio 1
	v_mfma_f32_16x16x32_bf16 v[120:123], v[158:161], v[190:193], v[120:123]
	v_mfma_f32_16x16x32_bf16 v[112:115], v[166:169], v[190:193], v[112:115]
	v_mfma_f32_16x16x32_bf16 v[88:91], v[158:161], v[198:201], v[88:91]
	v_mfma_f32_16x16x32_bf16 v[80:83], v[166:169], v[198:201], v[80:83]
	v_mfma_f32_16x16x32_bf16 v[56:59], v[158:161], v[208:211], v[56:59]
	v_mfma_f32_16x16x32_bf16 v[48:51], v[166:169], v[208:211], v[48:51]
	v_mfma_f32_16x16x32_bf16 v[24:27], v[158:161], v[216:219], v[24:27]
	v_mfma_f32_16x16x32_bf16 v[16:19], v[166:169], v[216:219], v[16:19]
	v_mfma_f32_16x16x32_bf16 v[120:123], v[162:165], v[194:197], v[120:123]
	v_mfma_f32_16x16x32_bf16 v[112:115], v[170:173], v[194:197], v[112:115]
	v_mfma_f32_16x16x32_bf16 v[88:91], v[162:165], v[202:205], v[88:91]
	v_mfma_f32_16x16x32_bf16 v[80:83], v[170:173], v[202:205], v[80:83]
	v_mfma_f32_16x16x32_bf16 v[56:59], v[162:165], v[212:215], v[56:59]
	v_mfma_f32_16x16x32_bf16 v[48:51], v[170:173], v[212:215], v[48:51]
	v_mfma_f32_16x16x32_bf16 v[24:27], v[162:165], v[220:223], v[24:27]
	v_mfma_f32_16x16x32_bf16 v[16:19], v[170:173], v[220:223], v[16:19]
	v_mfma_f32_16x16x32_bf16 v[104:107], v[174:177], v[190:193], v[104:107]
	v_mfma_f32_16x16x32_bf16 v[96:99], v[182:185], v[190:193], v[96:99]
	v_mfma_f32_16x16x32_bf16 v[72:75], v[174:177], v[198:201], v[72:75]
	v_mfma_f32_16x16x32_bf16 v[64:67], v[182:185], v[198:201], v[64:67]
	v_mfma_f32_16x16x32_bf16 v[40:43], v[174:177], v[208:211], v[40:43]
	v_mfma_f32_16x16x32_bf16 v[32:35], v[182:185], v[208:211], v[32:35]
	v_mfma_f32_16x16x32_bf16 v[8:11], v[174:177], v[216:219], v[8:11]
	v_mfma_f32_16x16x32_bf16 v[0:3], v[182:185], v[216:219], v[0:3]
	v_mfma_f32_16x16x32_bf16 v[104:107], v[178:181], v[194:197], v[104:107]
	v_mfma_f32_16x16x32_bf16 v[96:99], v[186:189], v[194:197], v[96:99]
	v_mfma_f32_16x16x32_bf16 v[72:75], v[178:181], v[202:205], v[72:75]
	v_mfma_f32_16x16x32_bf16 v[64:67], v[186:189], v[202:205], v[64:67]
	v_mfma_f32_16x16x32_bf16 v[40:43], v[178:181], v[212:215], v[40:43]
	v_mfma_f32_16x16x32_bf16 v[32:35], v[186:189], v[212:215], v[32:35]
	v_mfma_f32_16x16x32_bf16 v[8:11], v[178:181], v[220:223], v[8:11]
	v_mfma_f32_16x16x32_bf16 v[0:3], v[186:189], v[220:223], v[0:3]
	s_setprio 0
	s_barrier
	s_add_u32 s64, s64, 0x100
	s_addc_u32 s65, s65, 0
	s_add_u32 s33, s33, 0x100
	s_addc_u32 s49, s49, 0
	s_cmp_ge_i32 s90, s78
	s_mov_b32 s66, s90
	s_cbranch_scc0 .LBB0_502

; #define PG8_STAGE(bufoff, gbase, voff) do { _Pragma("unroll") for (int _i = 0; _i < 2; ++_i) \
;         __builtin_amdgcn_global_load_lds((const unsigned*)((const char*)(gbase) + (voff)[_i]), (LAS unsigned*)(lds + (bufoff) + ldsw + _i * 8192), 16, 0, 0); } while (0)
; #define PG8_LDA(dst, b, h) do { _Pragma("unroll") for (int m = 0; m < 4; ++m) _Pragma("unroll") for (int k = 0; k < 2; ++k) dst[m][k] = *(const LAS bf16x8*)(lds + PG8_SA(b, h) + aoff + m * 2048 + k * 1024); } while (0)
; #define PG8_LDB(dst, b, h) do { _Pragma("unroll") for (int n = 0; n < 2; ++n) _Pragma("unroll") for (int k = 0; k < 2; ++k) dst[n][k] = *(const LAS bf16x8*)(lds + PG8_SB(b, h) + boff + n * 2048 + k * 1024); } while (0)
; #define PG8_MMA(ai, bj, At, Bt) do { __builtin_amdgcn_s_setprio(1); _Pragma("unroll") for (int m = 0; m < 4; ++m) _Pragma("unroll") for (int n = 0; n < 2; ++n) _Pragma("unroll") for (int k = 0; k < 2; ++k) \
;         acc[ai][bj][m][n] = __builtin_amdgcn_mfma_f32_16x16x32_bf16(Bt[n][k], At[m][k], acc[ai][bj][m][n], 0, 0, 0); __builtin_amdgcn_s_setprio(0); } while (0)
; #define PG8_WAIT_V(n) asm volatile("s_waitcnt vmcnt(" #n ")" ::: "memory")
; #define PG8_WAIT_L(n) asm volatile("s_waitcnt lgkmcnt(" #n ")" ::: "memory")
; #define PG8_BAR __builtin_amdgcn_s_barrier()
; #define PG8_SCHED __builtin_amdgcn_sched_barrier(0)
; template <class Epi, class Sched, bool ALIGN_EPI, bool SP2>
; __device__ __forceinline__ void gemm_phase(LAS unsigned char* lds, const Gemm g, const Sched& S, const Epi& E) {
;     ...
;             PG8_LDB(B0, 0, 0); PG8_LDB(B1, 0, 1); PG8_SCHED; PG8_LDA(At, 0, 0); PG8_STAGE(PG8_SA(1, 1), a1 + hstep, voffA);
;             PG8_WAIT_V(8); PG8_WAIT_L(0); PG8_BAR; PG8_MMA(0, 0, At, B0); PG8_MMA(0, 1, At, B1); PG8_BAR; PG8_SCHED;
;             PG8_LDA(At, 0, 1); PG8_STAGE(PG8_SB(0, 0), b2, voffB); PG8_STAGE(PG8_SB(0, 1), b2 + hstepB, voffB); PG8_STAGE(PG8_SA(0, 0), a2, voffA);
;             PG8_WAIT_V(8); PG8_WAIT_L(0); PG8_BAR; PG8_MMA(1, 0, At, B0); PG8_MMA(1, 1, At, B1); PG8_BAR; PG8_SCHED;
.LBB0_788:
	ds_read_b128 v[146:149], v161
	ds_read_b128 v[150:153], v161 offset:1024
	ds_read_b128 v[154:157], v161 offset:2048
	ds_read_b128 v[166:169], v161 offset:3072
	ds_read_b128 v[170:173], v162
	ds_read_b128 v[174:177], v162 offset:1024
	ds_read_b128 v[178:181], v162 offset:2048
	ds_read_b128 v[182:185], v162 offset:3072
	s_add_i32 s86, s49, 2
	s_add_u32 s14, s66, 0x80
	s_addc_u32 s15, s67, 0
	s_cmp_eq_u32 s78, s49
	s_cselect_b32 s69, s1, s15
	s_cselect_b32 s68, s0, s14
	s_cselect_b32 s15, s65, s48
	s_cselect_b32 s14, s64, s33
	s_mov_b32 m0, s81
	v_lshl_add_u64 v[220:221], s[66:67], 0, v[138:139]
	ds_read_b128 v[186:189], v163
	ds_read_b128 v[190:193], v163 offset:1024
	ds_read_b128 v[194:197], v163 offset:2048
	ds_read_b128 v[198:201], v163 offset:3072
	ds_read_b128 v[202:205], v163 offset:4096
	ds_read_b128 v[208:211], v163 offset:5120
	ds_read_b128 v[212:215], v163 offset:6144
	ds_read_b128 v[216:219], v163 offset:7168
	global_load_lds_dwordx4 v[220:221], off
	v_lshl_add_u64 v[220:221], s[66:67], 0, v[140:141]
	s_mov_b32 m0, s82
	s_nop 0
	global_load_lds_dwordx4 v[220:221], off
	s_waitcnt vmcnt(8)
	s_waitcnt lgkmcnt(0)
	s_barrier
	s_setprio 1
	v_mfma_f32_16x16x32_bf16 v[124:127], v[146:149], v[186:189], v[124:127]
	v_mfma_f32_16x16x32_bf16 v[120:123], v[154:157], v[186:189], v[120:123]
	v_mfma_f32_16x16x32_bf16 v[116:119], v[146:149], v[194:197], v[116:119]
	v_mfma_f32_16x16x32_bf16 v[112:115], v[154:157], v[194:197], v[112:115]
	v_mfma_f32_16x16x32_bf16 v[104:107], v[146:149], v[202:205], v[104:107]
	v_mfma_f32_16x16x32_bf16 v[96:99], v[154:157], v[202:205], v[96:99]
	v_mfma_f32_16x16x32_bf16 v[88:91], v[146:149], v[212:215], v[88:91]
	v_mfma_f32_16x16x32_bf16 v[80:83], v[154:157], v[212:215], v[80:83]
	v_mfma_f32_16x16x32_bf16 v[124:127], v[150:153], v[190:193], v[124:127]
	v_mfma_f32_16x16x32_bf16 v[120:123], v[166:169], v[190:193], v[120:123]
	v_mfma_f32_16x16x32_bf16 v[116:119], v[150:153], v[198:201], v[116:119]
	v_mfma_f32_16x16x32_bf16 v[112:115], v[166:169], v[198:201], v[112:115]
	v_mfma_f32_16x16x32_bf16 v[104:107], v[150:153], v[208:211], v[104:107]
	v_mfma_f32_16x16x32_bf16 v[96:99], v[166:169], v[208:211], v[96:99]
	v_mfma_f32_16x16x32_bf16 v[88:91], v[150:153], v[216:219], v[88:91]
	v_mfma_f32_16x16x32_bf16 v[80:83], v[166:169], v[216:219], v[80:83]
	v_mfma_f32_16x16x32_bf16 v[108:111], v[170:173], v[186:189], v[108:111]
	v_mfma_f32_16x16x32_bf16 v[100:103], v[178:181], v[186:189], v[100:103]
	v_mfma_f32_16x16x32_bf16 v[92:95], v[170:173], v[194:197], v[92:95]
	v_mfma_f32_16x16x32_bf16 v[84:87], v[178:181], v[194:197], v[84:87]
	v_mfma_f32_16x16x32_bf16 v[76:79], v[170:173], v[202:205], v[76:79]
	v_mfma_f32_16x16x32_bf16 v[72:75], v[178:181], v[202:205], v[72:75]
	v_mfma_f32_16x16x32_bf16 v[68:71], v[170:173], v[212:215], v[68:71]
	v_mfma_f32_16x16x32_bf16 v[64:67], v[178:181], v[212:215], v[64:67]
	v_mfma_f32_16x16x32_bf16 v[108:111], v[174:177], v[190:193], v[108:111]
	v_mfma_f32_16x16x32_bf16 v[100:103], v[182:185], v[190:193], v[100:103]
	v_mfma_f32_16x16x32_bf16 v[92:95], v[174:177], v[198:201], v[92:95]
	v_mfma_f32_16x16x32_bf16 v[84:87], v[182:185], v[198:201], v[84:87]
	v_mfma_f32_16x16x32_bf16 v[76:79], v[174:177], v[208:211], v[76:79]
	v_mfma_f32_16x16x32_bf16 v[72:75], v[182:185], v[208:211], v[72:75]
	v_mfma_f32_16x16x32_bf16 v[68:71], v[174:177], v[216:219], v[68:71]
	v_mfma_f32_16x16x32_bf16 v[64:67], v[182:185], v[216:219], v[64:67]
	s_setprio 0
	s_barrier
	s_add_i32 s49, s79, s57
	v_lshl_add_u64 v[220:221], s[14:15], 0, v[130:131]
	s_mov_b32 m0, s49
	ds_read_b128 v[186:189], v163 offset:16384
	ds_read_b128 v[190:193], v163 offset:17408
	ds_read_b128 v[194:197], v163 offset:18432
	ds_read_b128 v[198:201], v163 offset:19456
	ds_read_b128 v[202:205], v163 offset:20480
	ds_read_b128 v[208:211], v163 offset:21504
	ds_read_b128 v[212:215], v163 offset:22528
	ds_read_b128 v[216:219], v163 offset:23552
	global_load_lds_dwordx4 v[220:221], off
	s_add_i32 m0, s49, 0x2000
	v_lshl_add_u64 v[222:223], s[14:15], 0, v[134:135]
	s_add_u32 s14, s14, s10
	s_addc_u32 s15, s15, s11
	s_add_i32 s49, s80, s57
	global_load_lds_dwordx4 v[222:223], off
	v_lshl_add_u64 v[224:225], s[14:15], 0, v[130:131]
	s_mov_b32 m0, s49
	v_lshl_add_u64 v[226:227], s[14:15], 0, v[134:135]
	global_load_lds_dwordx4 v[224:225], off
	s_add_i32 m0, s49, 0x2000
	v_lshl_add_u64 v[228:229], s[68:69], 0, v[128:129]
	global_load_lds_dwordx4 v[226:227], off
	s_mov_b32 m0, s70
	v_lshl_add_u64 v[230:231], s[68:69], 0, v[132:133]
	global_load_lds_dwordx4 v[228:229], off
	s_mov_b32 m0, s71
	s_nop 0
	global_load_lds_dwordx4 v[230:231], off
	s_waitcnt vmcnt(8)
	s_waitcnt lgkmcnt(0)
	s_barrier
; #define PG8_STAGE(bufoff, gbase, voff) do { _Pragma("unroll") for (int _i = 0; _i < 2; ++_i) \
;         __builtin_amdgcn_global_load_lds((const unsigned*)((const char*)(gbase) + (voff)[_i]), (LAS unsigned*)(lds + (bufoff) + ldsw + _i * 8192), 16, 0, 0); } while (0)
; #define PG8_LDA(dst, b, h) do { _Pragma("unroll") for (int m = 0; m < 4; ++m) _Pragma("unroll") for (int k = 0; k < 2; ++k) dst[m][k] = *(const LAS bf16x8*)(lds + PG8_SA(b, h) + aoff + m * 2048 + k * 1024); } while (0)
; #define PG8_LDB(dst, b, h) do { _Pragma("unroll") for (int n = 0; n < 2; ++n) _Pragma("unroll") for (int k = 0; k < 2; ++k) dst[n][k] = *(const LAS bf16x8*)(lds + PG8_SB(b, h) + boff + n * 2048 + k * 1024); } while (0)
; #define PG8_MMA(ai, bj, At, Bt) do { __builtin_amdgcn_s_setprio(1); _Pragma("unroll") for (int m = 0; m < 4; ++m) _Pragma("unroll") for (int n = 0; n < 2; ++n) _Pragma("unroll") for (int k = 0; k < 2; ++k) \
;         acc[ai][bj][m][n] = __builtin_amdgcn_mfma_f32_16x16x32_bf16(Bt[n][k], At[m][k], acc[ai][bj][m][n], 0, 0, 0); __builtin_amdgcn_s_setprio(0); } while (0)
; #define PG8_WAIT_V(n) asm volatile("s_waitcnt vmcnt(" #n ")" ::: "memory")
; #define PG8_WAIT_L(n) asm volatile("s_waitcnt lgkmcnt(" #n ")" ::: "memory")
; #define PG8_BAR __builtin_amdgcn_s_barrier()
; #define PG8_SCHED __builtin_amdgcn_sched_barrier(0)
; template <class Epi, class Sched, bool ALIGN_EPI, bool SP2>
; __device__ __forceinline__ void gemm_phase(LAS unsigned char* lds, const Gemm g, const Sched& S, const Epi& E) {
;     ...
;             PG8_WAIT_V(8); PG8_WAIT_L(0); PG8_BAR; PG8_MMA(1, 0, At, B0); PG8_MMA(1, 1, At, B1); PG8_BAR; PG8_SCHED;
;             PG8_LDB(B0, 1, 0); PG8_LDB(B1, 1, 1); PG8_SCHED; PG8_LDA(At, 1, 0); PG8_STAGE(PG8_SA(0, 1), a2 + hstep, voffA);
;             PG8_WAIT_V(8); PG8_WAIT_L(0); PG8_BAR; PG8_MMA(0, 0, At, B0); PG8_MMA(0, 1, At, B1); PG8_BAR; PG8_SCHED;
	s_setprio 1
	v_mfma_f32_16x16x32_bf16 v[60:63], v[146:149], v[186:189], v[60:63]
	v_mfma_f32_16x16x32_bf16 v[56:59], v[154:157], v[186:189], v[56:59]
	v_mfma_f32_16x16x32_bf16 v[52:55], v[146:149], v[194:197], v[52:55]
	v_mfma_f32_16x16x32_bf16 v[48:51], v[154:157], v[194:197], v[48:51]
	v_mfma_f32_16x16x32_bf16 v[40:43], v[146:149], v[202:205], v[40:43]
	v_mfma_f32_16x16x32_bf16 v[32:35], v[154:157], v[202:205], v[32:35]
	v_mfma_f32_16x16x32_bf16 v[24:27], v[146:149], v[212:215], v[24:27]
	v_mfma_f32_16x16x32_bf16 v[16:19], v[154:157], v[212:215], v[16:19]
	v_mfma_f32_16x16x32_bf16 v[60:63], v[150:153], v[190:193], v[60:63]
	v_mfma_f32_16x16x32_bf16 v[56:59], v[166:169], v[190:193], v[56:59]
	v_mfma_f32_16x16x32_bf16 v[52:55], v[150:153], v[198:201], v[52:55]
	v_mfma_f32_16x16x32_bf16 v[48:51], v[166:169], v[198:201], v[48:51]
	v_mfma_f32_16x16x32_bf16 v[40:43], v[150:153], v[208:211], v[40:43]
	v_mfma_f32_16x16x32_bf16 v[32:35], v[166:169], v[208:211], v[32:35]
	v_mfma_f32_16x16x32_bf16 v[24:27], v[150:153], v[216:219], v[24:27]
	v_mfma_f32_16x16x32_bf16 v[16:19], v[166:169], v[216:219], v[16:19]
	v_mfma_f32_16x16x32_bf16 v[44:47], v[170:173], v[186:189], v[44:47]
	v_mfma_f32_16x16x32_bf16 v[36:39], v[178:181], v[186:189], v[36:39]
	v_mfma_f32_16x16x32_bf16 v[28:31], v[170:173], v[194:197], v[28:31]
	v_mfma_f32_16x16x32_bf16 v[20:23], v[178:181], v[194:197], v[20:23]
	v_mfma_f32_16x16x32_bf16 v[12:15], v[170:173], v[202:205], v[12:15]
	v_mfma_f32_16x16x32_bf16 v[8:11], v[178:181], v[202:205], v[8:11]
	v_mfma_f32_16x16x32_bf16 v[4:7], v[170:173], v[212:215], v[4:7]
	v_mfma_f32_16x16x32_bf16 v[0:3], v[178:181], v[212:215], v[0:3]
	v_mfma_f32_16x16x32_bf16 v[44:47], v[174:177], v[190:193], v[44:47]
	v_mfma_f32_16x16x32_bf16 v[36:39], v[182:185], v[190:193], v[36:39]
	v_mfma_f32_16x16x32_bf16 v[28:31], v[174:177], v[198:201], v[28:31]
	v_mfma_f32_16x16x32_bf16 v[20:23], v[182:185], v[198:201], v[20:23]
	v_mfma_f32_16x16x32_bf16 v[12:15], v[174:177], v[208:211], v[12:15]
	v_mfma_f32_16x16x32_bf16 v[8:11], v[182:185], v[208:211], v[8:11]
	v_mfma_f32_16x16x32_bf16 v[4:7], v[174:177], v[216:219], v[4:7]
	v_mfma_f32_16x16x32_bf16 v[0:3], v[182:185], v[216:219], v[0:3]
	s_setprio 0
	s_barrier
	s_add_i32 s49, 0, 0x18000
	v_add_u32_e32 v136, s49, v158
	s_add_i32 s58, 0, 0x1c000
	ds_read_b128 v[146:149], v136
	ds_read_b128 v[150:153], v136 offset:1024
	ds_read_b128 v[154:157], v136 offset:2048
	ds_read_b128 v[166:169], v136 offset:3072
	v_add_u32_e32 v136, s58, v158
	ds_read_b128 v[170:173], v136
	ds_read_b128 v[174:177], v136 offset:1024
	ds_read_b128 v[178:181], v136 offset:2048
	ds_read_b128 v[182:185], v136 offset:3072
	s_add_u32 s14, s68, s10
	s_addc_u32 s15, s69, s11
	s_mov_b32 m0, s72
	v_lshl_add_u64 v[232:233], s[14:15], 0, v[128:129]
	ds_read_b128 v[186:189], v163 offset:32768
	ds_read_b128 v[190:193], v163 offset:33792
	ds_read_b128 v[194:197], v163 offset:34816
	ds_read_b128 v[198:201], v163 offset:35840
	ds_read_b128 v[202:205], v163 offset:36864
	ds_read_b128 v[208:211], v163 offset:37888
	ds_read_b128 v[212:215], v163 offset:38912
	ds_read_b128 v[216:219], v163 offset:39936
	global_load_lds_dwordx4 v[232:233], off
	v_lshl_add_u64 v[232:233], s[14:15], 0, v[132:133]
	s_mov_b32 m0, s73
	s_nop 0
	global_load_lds_dwordx4 v[232:233], off
	s_waitcnt vmcnt(8)
	s_waitcnt lgkmcnt(0)
	s_barrier
	s_setprio 1
	v_mfma_f32_16x16x32_bf16 v[124:127], v[146:149], v[186:189], v[124:127]
	v_mfma_f32_16x16x32_bf16 v[120:123], v[154:157], v[186:189], v[120:123]
	v_mfma_f32_16x16x32_bf16 v[116:119], v[146:149], v[194:197], v[116:119]
	v_mfma_f32_16x16x32_bf16 v[112:115], v[154:157], v[194:197], v[112:115]
	v_mfma_f32_16x16x32_bf16 v[104:107], v[146:149], v[202:205], v[104:107]
	v_mfma_f32_16x16x32_bf16 v[96:99], v[154:157], v[202:205], v[96:99]
	v_mfma_f32_16x16x32_bf16 v[88:91], v[146:149], v[212:215], v[88:91]
	v_mfma_f32_16x16x32_bf16 v[80:83], v[154:157], v[212:215], v[80:83]
	v_mfma_f32_16x16x32_bf16 v[124:127], v[150:153], v[190:193], v[124:127]
	v_mfma_f32_16x16x32_bf16 v[120:123], v[166:169], v[190:193], v[120:123]
	v_mfma_f32_16x16x32_bf16 v[116:119], v[150:153], v[198:201], v[116:119]
	v_mfma_f32_16x16x32_bf16 v[112:115], v[166:169], v[198:201], v[112:115]
	v_mfma_f32_16x16x32_bf16 v[104:107], v[150:153], v[208:211], v[104:107]
	v_mfma_f32_16x16x32_bf16 v[96:99], v[166:169], v[208:211], v[96:99]
	v_mfma_f32_16x16x32_bf16 v[88:91], v[150:153], v[216:219], v[88:91]
	v_mfma_f32_16x16x32_bf16 v[80:83], v[166:169], v[216:219], v[80:83]
	v_mfma_f32_16x16x32_bf16 v[108:111], v[170:173], v[186:189], v[108:111]
	v_mfma_f32_16x16x32_bf16 v[100:103], v[178:181], v[186:189], v[100:103]
	v_mfma_f32_16x16x32_bf16 v[92:95], v[170:173], v[194:197], v[92:95]
	v_mfma_f32_16x16x32_bf16 v[84:87], v[178:181], v[194:197], v[84:87]
	v_mfma_f32_16x16x32_bf16 v[76:79], v[170:173], v[202:205], v[76:79]
	v_mfma_f32_16x16x32_bf16 v[72:75], v[178:181], v[202:205], v[72:75]
	v_mfma_f32_16x16x32_bf16 v[68:71], v[170:173], v[212:215], v[68:71]
	v_mfma_f32_16x16x32_bf16 v[64:67], v[178:181], v[212:215], v[64:67]
	v_mfma_f32_16x16x32_bf16 v[108:111], v[174:177], v[190:193], v[108:111]
	v_mfma_f32_16x16x32_bf16 v[100:103], v[182:185], v[190:193], v[100:103]
	v_mfma_f32_16x16x32_bf16 v[92:95], v[174:177], v[198:201], v[92:95]
	v_mfma_f32_16x16x32_bf16 v[84:87], v[182:185], v[198:201], v[84:87]
	v_mfma_f32_16x16x32_bf16 v[76:79], v[174:177], v[208:211], v[76:79]
	v_mfma_f32_16x16x32_bf16 v[72:75], v[182:185], v[208:211], v[72:75]
	v_mfma_f32_16x16x32_bf16 v[68:71], v[174:177], v[216:219], v[68:71]
	v_mfma_f32_16x16x32_bf16 v[64:67], v[182:185], v[216:219], v[64:67]
	s_setprio 0
	s_barrier
; #define PG8_STAGE(bufoff, gbase, voff) do { _Pragma("unroll") for (int _i = 0; _i < 2; ++_i) \
;         __builtin_amdgcn_global_load_lds((const unsigned*)((const char*)(gbase) + (voff)[_i]), (LAS unsigned*)(lds + (bufoff) + ldsw + _i * 8192), 16, 0, 0); } while (0)
; #define PG8_LDA(dst, b, h) do { _Pragma("unroll") for (int m = 0; m < 4; ++m) _Pragma("unroll") for (int k = 0; k < 2; ++k) dst[m][k] = *(const LAS bf16x8*)(lds + PG8_SA(b, h) + aoff + m * 2048 + k * 1024); } while (0)
; #define PG8_MMA(ai, bj, At, Bt) do { __builtin_amdgcn_s_setprio(1); _Pragma("unroll") for (int m = 0; m < 4; ++m) _Pragma("unroll") for (int n = 0; n < 2; ++n) _Pragma("unroll") for (int k = 0; k < 2; ++k) \
;         acc[ai][bj][m][n] = __builtin_amdgcn_mfma_f32_16x16x32_bf16(Bt[n][k], At[m][k], acc[ai][bj][m][n], 0, 0, 0); __builtin_amdgcn_s_setprio(0); } while (0)
; #define PG8_WAIT_V(n) asm volatile("s_waitcnt vmcnt(" #n ")" ::: "memory")
; #define PG8_WAIT_L(n) asm volatile("s_waitcnt lgkmcnt(" #n ")" ::: "memory")
; #define PG8_BAR __builtin_amdgcn_s_barrier()
; #define PG8_SCHED __builtin_amdgcn_sched_barrier(0)
; template <class Epi, class Sched, bool ALIGN_EPI, bool SP2>
; __device__ __forceinline__ void gemm_phase(LAS unsigned char* lds, const Gemm g, const Sched& S, const Epi& E) {
;     ...
;         for (int t = tb; t < te; t += 2) {
;             const bool last = (t == nt - 2);
;             const char* a1 = cA + (size_t)(t + 1) * kstep;
;             const char* a2 = last ? nA : cA + (size_t)(t + 2) * kstep; const char* b2 = last ? nB : cB + (size_t)(t + 2) * kstep;
;             const char* a3 = a2 + kstep; const char* b3 = b2 + kstep;
;             if (last && has_next) S.a_ready(nxt);
;     ...
;             PG8_LDA(At, 1, 1); PG8_STAGE(PG8_SB(1, 0), b3, voffB); PG8_STAGE(PG8_SB(1, 1), b3 + hstepB, voffB); PG8_STAGE(PG8_SA(1, 0), a3, voffA);
;             PG8_WAIT_V(8); PG8_WAIT_L(0); PG8_BAR; PG8_MMA(1, 0, At, B0); PG8_MMA(1, 1, At, B1); PG8_BAR; PG8_SCHED;
	s_add_i32 s14, s49, s57
	v_lshl_add_u64 v[220:221], v[220:221], 0, s[44:45]
	s_mov_b32 m0, s14
	ds_read_b128 v[186:189], v163 offset:49152
	ds_read_b128 v[190:193], v163 offset:50176
	ds_read_b128 v[194:197], v163 offset:51200
	ds_read_b128 v[198:201], v163 offset:52224
	ds_read_b128 v[202:205], v163 offset:53248
	ds_read_b128 v[208:211], v163 offset:54272
	ds_read_b128 v[212:215], v163 offset:55296
	ds_read_b128 v[216:219], v163 offset:56320
	global_load_lds_dwordx4 v[220:221], off
	v_lshl_add_u64 v[220:221], v[222:223], 0, s[44:45]
	s_add_i32 m0, s14, 0x2000
	s_add_i32 s14, s58, s57
	global_load_lds_dwordx4 v[220:221], off
	v_lshl_add_u64 v[220:221], v[224:225], 0, s[44:45]
	s_mov_b32 m0, s14
	s_nop 0
	global_load_lds_dwordx4 v[220:221], off
	v_lshl_add_u64 v[220:221], v[226:227], 0, s[44:45]
	s_add_i32 m0, s14, 0x2000
	s_nop 0
	global_load_lds_dwordx4 v[220:221], off
	v_lshl_add_u64 v[220:221], v[228:229], 0, s[44:45]
	s_mov_b32 m0, s75
	s_nop 0
	global_load_lds_dwordx4 v[220:221], off
	v_lshl_add_u64 v[220:221], v[230:231], 0, s[44:45]
	s_mov_b32 m0, s76
	s_nop 0
	global_load_lds_dwordx4 v[220:221], off
	s_waitcnt vmcnt(8)
	s_waitcnt lgkmcnt(0)
	s_barrier
	s_setprio 1
	v_mfma_f32_16x16x32_bf16 v[60:63], v[146:149], v[186:189], v[60:63]
	v_mfma_f32_16x16x32_bf16 v[56:59], v[154:157], v[186:189], v[56:59]
	v_mfma_f32_16x16x32_bf16 v[52:55], v[146:149], v[194:197], v[52:55]
	v_mfma_f32_16x16x32_bf16 v[48:51], v[154:157], v[194:197], v[48:51]
	v_mfma_f32_16x16x32_bf16 v[40:43], v[146:149], v[202:205], v[40:43]
	v_mfma_f32_16x16x32_bf16 v[32:35], v[154:157], v[202:205], v[32:35]
	v_mfma_f32_16x16x32_bf16 v[24:27], v[146:149], v[212:215], v[24:27]
	v_mfma_f32_16x16x32_bf16 v[16:19], v[154:157], v[212:215], v[16:19]
	v_mfma_f32_16x16x32_bf16 v[60:63], v[150:153], v[190:193], v[60:63]
	v_mfma_f32_16x16x32_bf16 v[56:59], v[166:169], v[190:193], v[56:59]
	v_mfma_f32_16x16x32_bf16 v[52:55], v[150:153], v[198:201], v[52:55]
	v_mfma_f32_16x16x32_bf16 v[48:51], v[166:169], v[198:201], v[48:51]
	v_mfma_f32_16x16x32_bf16 v[40:43], v[150:153], v[208:211], v[40:43]
	v_mfma_f32_16x16x32_bf16 v[32:35], v[166:169], v[208:211], v[32:35]
	v_mfma_f32_16x16x32_bf16 v[24:27], v[150:153], v[216:219], v[24:27]
	v_mfma_f32_16x16x32_bf16 v[16:19], v[166:169], v[216:219], v[16:19]
	v_mfma_f32_16x16x32_bf16 v[44:47], v[170:173], v[186:189], v[44:47]
	v_mfma_f32_16x16x32_bf16 v[36:39], v[178:181], v[186:189], v[36:39]
	v_mfma_f32_16x16x32_bf16 v[28:31], v[170:173], v[194:197], v[28:31]
	v_mfma_f32_16x16x32_bf16 v[20:23], v[178:181], v[194:197], v[20:23]
	v_mfma_f32_16x16x32_bf16 v[12:15], v[170:173], v[202:205], v[12:15]
	v_mfma_f32_16x16x32_bf16 v[8:11], v[178:181], v[202:205], v[8:11]
	v_mfma_f32_16x16x32_bf16 v[4:7], v[170:173], v[212:215], v[4:7]
	v_mfma_f32_16x16x32_bf16 v[0:3], v[178:181], v[212:215], v[0:3]
	v_mfma_f32_16x16x32_bf16 v[44:47], v[174:177], v[190:193], v[44:47]
	v_mfma_f32_16x16x32_bf16 v[36:39], v[182:185], v[190:193], v[36:39]
	v_mfma_f32_16x16x32_bf16 v[28:31], v[174:177], v[198:201], v[28:31]
	v_mfma_f32_16x16x32_bf16 v[20:23], v[182:185], v[198:201], v[20:23]
	v_mfma_f32_16x16x32_bf16 v[12:15], v[174:177], v[208:211], v[12:15]
	v_mfma_f32_16x16x32_bf16 v[8:11], v[182:185], v[208:211], v[8:11]
	v_mfma_f32_16x16x32_bf16 v[4:7], v[174:177], v[216:219], v[4:7]
	v_mfma_f32_16x16x32_bf16 v[0:3], v[182:185], v[216:219], v[0:3]
	s_setprio 0
	s_barrier
	s_add_u32 s66, s66, 0x100
	s_addc_u32 s67, s67, 0
	s_add_u32 s33, s33, 0x100
	s_addc_u32 s48, s48, 0
	s_cmp_ge_i32 s86, s77
	s_mov_b32 s49, s86
	s_cbranch_scc0 .LBB0_788
;     __device__ __forceinline__ void operator()(const f32x4 (&acc)[2][2][4][2], const Unit& u, int wr, int wc, int fr, int fq) const {
;     ...
;                     const f32x4 v0 = acc[ai][bj][m][0] * (1.f / 1024.f), v1 = acc[ai][bj][m][1] * (1.f / 1024.f);
	v_pk_mul_f32 v[150:151], v[126:127], s[62:63] op_sel_hi:[1,0]
	v_pk_mul_f32 v[154:155], v[124:125], s[62:63] op_sel_hi:[1,0]
	v_pk_mul_f32 v[152:153], v[122:123], s[62:63] op_sel_hi:[1,0]
	v_pk_mul_f32 v[156:157], v[120:121], s[62:63] op_sel_hi:[1,0]
	v_pk_mul_f32 v[124:125], v[110:111], s[62:63] op_sel_hi:[1,0]
	v_pk_mul_f32 v[146:147], v[108:109], s[62:63] op_sel_hi:[1,0]
	v_pk_mul_f32 v[126:127], v[102:103], s[62:63] op_sel_hi:[1,0]
	v_pk_mul_f32 v[148:149], v[100:101], s[62:63] op_sel_hi:[1,0]
	v_pk_mul_f32 v[118:119], v[118:119], s[62:63] op_sel_hi:[1,0]
	v_pk_mul_f32 v[120:121], v[116:117], s[62:63] op_sel_hi:[1,0]
	v_pk_mul_f32 v[116:117], v[114:115], s[62:63] op_sel_hi:[1,0]
	v_pk_mul_f32 v[122:123], v[112:113], s[62:63] op_sel_hi:[1,0]
	v_pk_mul_f32 v[108:109], v[94:95], s[62:63] op_sel_hi:[1,0]
	v_pk_mul_f32 v[110:111], v[92:93], s[62:63] op_sel_hi:[1,0]
	v_pk_mul_f32 v[112:113], v[86:87], s[62:63] op_sel_hi:[1,0]
	v_pk_mul_f32 v[114:115], v[84:85], s[62:63] op_sel_hi:[1,0]
	v_pk_mul_f32 v[100:101], v[106:107], s[62:63] op_sel_hi:[1,0]
	v_pk_mul_f32 v[104:105], v[104:105], s[62:63] op_sel_hi:[1,0]
	v_pk_mul_f32 v[102:103], v[98:99], s[62:63] op_sel_hi:[1,0]
	v_pk_mul_f32 v[106:107], v[96:97], s[62:63] op_sel_hi:[1,0]
	v_pk_mul_f32 v[92:93], v[78:79], s[62:63] op_sel_hi:[1,0]
	v_pk_mul_f32 v[94:95], v[76:77], s[62:63] op_sel_hi:[1,0]
	v_pk_mul_f32 v[96:97], v[74:75], s[62:63] op_sel_hi:[1,0]
	v_pk_mul_f32 v[98:99], v[72:73], s[62:63] op_sel_hi:[1,0]
	v_pk_mul_f32 v[84:85], v[90:91], s[62:63] op_sel_hi:[1,0]
	v_pk_mul_f32 v[88:89], v[88:89], s[62:63] op_sel_hi:[1,0]
	v_pk_mul_f32 v[86:87], v[82:83], s[62:63] op_sel_hi:[1,0]
	v_pk_mul_f32 v[90:91], v[80:81], s[62:63] op_sel_hi:[1,0]
	v_pk_mul_f32 v[76:77], v[70:71], s[62:63] op_sel_hi:[1,0]
	v_pk_mul_f32 v[78:79], v[68:69], s[62:63] op_sel_hi:[1,0]
	v_pk_mul_f32 v[80:81], v[66:67], s[62:63] op_sel_hi:[1,0]
	v_pk_mul_f32 v[82:83], v[64:65], s[62:63] op_sel_hi:[1,0]
	v_pk_mul_f32 v[68:69], v[62:63], s[62:63] op_sel_hi:[1,0]
	v_pk_mul_f32 v[72:73], v[60:61], s[62:63] op_sel_hi:[1,0]
	v_pk_mul_f32 v[70:71], v[58:59], s[62:63] op_sel_hi:[1,0]
	v_pk_mul_f32 v[74:75], v[56:57], s[62:63] op_sel_hi:[1,0]
	v_pk_mul_f32 v[60:61], v[46:47], s[62:63] op_sel_hi:[1,0]
	v_pk_mul_f32 v[62:63], v[44:45], s[62:63] op_sel_hi:[1,0]
	v_pk_mul_f32 v[64:65], v[38:39], s[62:63] op_sel_hi:[1,0]
	v_pk_mul_f32 v[66:67], v[36:37], s[62:63] op_sel_hi:[1,0]
	v_pk_mul_f32 v[54:55], v[54:55], s[62:63] op_sel_hi:[1,0]
	v_pk_mul_f32 v[56:57], v[52:53], s[62:63] op_sel_hi:[1,0]
	v_pk_mul_f32 v[52:53], v[50:51], s[62:63] op_sel_hi:[1,0]
	v_pk_mul_f32 v[58:59], v[48:49], s[62:63] op_sel_hi:[1,0]
	v_pk_mul_f32 v[44:45], v[30:31], s[62:63] op_sel_hi:[1,0]
	v_pk_mul_f32 v[46:47], v[28:29], s[62:63] op_sel_hi:[1,0]
	v_pk_mul_f32 v[48:49], v[22:23], s[62:63] op_sel_hi:[1,0]
	v_pk_mul_f32 v[50:51], v[20:21], s[62:63] op_sel_hi:[1,0]
	v_pk_mul_f32 v[36:37], v[42:43], s[62:63] op_sel_hi:[1,0]
	v_pk_mul_f32 v[38:39], v[40:41], s[62:63] op_sel_hi:[1,0]
	v_pk_mul_f32 v[34:35], v[34:35], s[62:63] op_sel_hi:[1,0]
	v_pk_mul_f32 v[32:33], v[32:33], s[62:63] op_sel_hi:[1,0]
	v_pk_mul_f32 v[20:21], v[14:15], s[62:63] op_sel_hi:[1,0]
	v_pk_mul_f32 v[22:23], v[12:13], s[62:63] op_sel_hi:[1,0]
	v_pk_mul_f32 v[28:29], v[10:11], s[62:63] op_sel_hi:[1,0]
	v_pk_mul_f32 v[30:31], v[8:9], s[62:63] op_sel_hi:[1,0]
	v_pk_mul_f32 v[8:9], v[26:27], s[62:63] op_sel_hi:[1,0]
	v_pk_mul_f32 v[12:13], v[24:25], s[62:63] op_sel_hi:[1,0]
	v_pk_mul_f32 v[10:11], v[18:19], s[62:63] op_sel_hi:[1,0]
	v_pk_mul_f32 v[14:15], v[16:17], s[62:63] op_sel_hi:[1,0]
	v_pk_mul_f32 v[6:7], v[6:7], s[62:63] op_sel_hi:[1,0]
	v_pk_mul_f32 v[4:5], v[4:5], s[62:63] op_sel_hi:[1,0]
	v_pk_mul_f32 v[2:3], v[2:3], s[62:63] op_sel_hi:[1,0]
	v_pk_mul_f32 v[0:1], v[0:1], s[62:63] op_sel_hi:[1,0]

; #define PG8_STAGE(bufoff, gbase, voff) do { _Pragma("unroll") for (int _i = 0; _i < 2; ++_i) \
;         __builtin_amdgcn_global_load_lds((const unsigned*)((const char*)(gbase) + (voff)[_i]), (LAS unsigned*)(lds + (bufoff) + ldsw + _i * 8192), 16, 0, 0); } while (0)
; #define PG8_LDA(dst, b, h) do { _Pragma("unroll") for (int m = 0; m < 4; ++m) _Pragma("unroll") for (int k = 0; k < 2; ++k) dst[m][k] = *(const LAS bf16x8*)(lds + PG8_SA(b, h) + aoff + m * 2048 + k * 1024); } while (0)
; #define PG8_LDB(dst, b, h) do { _Pragma("unroll") for (int n = 0; n < 2; ++n) _Pragma("unroll") for (int k = 0; k < 2; ++k) dst[n][k] = *(const LAS bf16x8*)(lds + PG8_SB(b, h) + boff + n * 2048 + k * 1024); } while (0)
; #define PG8_MMA(ai, bj, At, Bt) do { __builtin_amdgcn_s_setprio(1); _Pragma("unroll") for (int m = 0; m < 4; ++m) _Pragma("unroll") for (int n = 0; n < 2; ++n) _Pragma("unroll") for (int k = 0; k < 2; ++k) \
;         acc[ai][bj][m][n] = __builtin_amdgcn_mfma_f32_16x16x32_bf16(Bt[n][k], At[m][k], acc[ai][bj][m][n], 0, 0, 0); __builtin_amdgcn_s_setprio(0); } while (0)
; #define PG8_WAIT_V(n) asm volatile("s_waitcnt vmcnt(" #n ")" ::: "memory")
; #define PG8_WAIT_L(n) asm volatile("s_waitcnt lgkmcnt(" #n ")" ::: "memory")
; template <class Epi, class Sched, bool ALIGN_EPI, bool SP2>
; __device__ __forceinline__ void gemm_phase(LAS unsigned char* lds, const Gemm g, const Sched& S, const Epi& E) {
;     ...
;         for (int t = tb; t < te; t += 2) {
;             const bool last = (t == nt - 2);
;             const char* a1 = cA + (size_t)(t + 1) * kstep;
;             const char* a2 = last ? nA : cA + (size_t)(t + 2) * kstep; const char* b2 = last ? nB : cB + (size_t)(t + 2) * kstep;
;             const char* a3 = a2 + kstep; const char* b3 = b2 + kstep;
;             if (last && has_next) S.a_ready(nxt);
;             if constexpr (SP2) {
;             PG8_LDB(B0, 0, 0); PG8_LDB(B1, 0, 1); PG8_SCHED; PG8_LDA(At, 0, 0); PG8_STAGE(PG8_SA(1, 1), a1 + hstep, voffA);
;             PG8_WAIT_V(8); PG8_WAIT_L(0); PG8_BAR; PG8_MMA(0, 0, At, B0); PG8_MMA(0, 1, At, B1); PG8_BAR; PG8_SCHED;
;             PG8_LDA(At, 0, 1); PG8_STAGE(PG8_SB(0, 0), b2, voffB); PG8_STAGE(PG8_SB(0, 1), b2 + hstepB, voffB); PG8_STAGE(PG8_SA(0, 0), a2, voffA);
;             PG8_WAIT_V(8); PG8_WAIT_L(0); PG8_BAR; PG8_MMA(1, 0, At, B0); PG8_MMA(1, 1, At, B1); PG8_BAR; PG8_SCHED;
.LBB0_878:
	v_add_u32_e32 v1, s95, v185
	ds_read_b128 v[142:145], v1
	ds_read_b128 v[146:149], v1 offset:1024
	ds_read_b128 v[150:153], v1 offset:2048
	ds_read_b128 v[154:157], v1 offset:3072
	v_add_u32_e32 v1, s96, v185
	ds_read_b128 v[158:161], v1
	ds_read_b128 v[190:193], v1 offset:1024
	ds_read_b128 v[194:197], v1 offset:2048
	ds_read_b128 v[198:201], v1 offset:3072
	s_add_i32 s10, s10, 2
	s_add_u32 s14, s84, s76
	s_addc_u32 s15, s85, s77
	s_add_u32 s49, s82, s76
	s_addc_u32 s58, s83, s77
	s_cmp_eq_u32 s76, s80
	s_cselect_b32 s89, s65, s15
	s_cselect_b32 s88, s71, s14
	s_cselect_b32 s87, s63, s58
	s_cselect_b32 s86, s48, s49
	v_lshl_add_u64 v[162:163], v[140:141], 0, s[76:77]
	s_add_i32 m0, s59, 0xc000
	ds_read_b128 v[202:205], v187
	ds_read_b128 v[208:211], v187 offset:1024
	ds_read_b128 v[212:215], v187 offset:2048
	ds_read_b128 v[216:219], v187 offset:3072
	ds_read_b128 v[220:223], v187 offset:4096
	ds_read_b128 v[224:227], v187 offset:5120
	ds_read_b128 v[228:231], v187 offset:6144
	ds_read_b128 v[232:235], v187 offset:7168
	global_load_lds_dwordx4 v[162:163], off
	v_lshl_add_u64 v[162:163], v[2:3], 0, s[76:77]
	s_add_i32 m0, s59, 0xe000
	s_nop 0
	global_load_lds_dwordx4 v[162:163], off
	s_waitcnt vmcnt(8)
	s_waitcnt lgkmcnt(0)
	s_barrier
	s_setprio 1
	v_mfma_f32_16x16x32_bf16 v[128:131], v[142:145], v[202:205], v[128:131]
	v_mfma_f32_16x16x32_bf16 v[124:127], v[150:153], v[202:205], v[124:127]
	v_mfma_f32_16x16x32_bf16 v[112:115], v[142:145], v[212:215], v[112:115]
	v_mfma_f32_16x16x32_bf16 v[108:111], v[150:153], v[212:215], v[108:111]
	v_mfma_f32_16x16x32_bf16 v[96:99], v[142:145], v[220:223], v[96:99]
	v_mfma_f32_16x16x32_bf16 v[92:95], v[150:153], v[220:223], v[92:95]
	v_mfma_f32_16x16x32_bf16 v[80:83], v[142:145], v[228:231], v[80:83]
	v_mfma_f32_16x16x32_bf16 v[76:79], v[150:153], v[228:231], v[76:79]
	v_mfma_f32_16x16x32_bf16 v[128:131], v[146:149], v[208:211], v[128:131]
	v_mfma_f32_16x16x32_bf16 v[124:127], v[154:157], v[208:211], v[124:127]
	v_mfma_f32_16x16x32_bf16 v[112:115], v[146:149], v[216:219], v[112:115]
	v_mfma_f32_16x16x32_bf16 v[108:111], v[154:157], v[216:219], v[108:111]
	v_mfma_f32_16x16x32_bf16 v[96:99], v[146:149], v[224:227], v[96:99]
	v_mfma_f32_16x16x32_bf16 v[92:95], v[154:157], v[224:227], v[92:95]
	v_mfma_f32_16x16x32_bf16 v[80:83], v[146:149], v[232:235], v[80:83]
	v_mfma_f32_16x16x32_bf16 v[76:79], v[154:157], v[232:235], v[76:79]
	v_mfma_f32_16x16x32_bf16 v[120:123], v[158:161], v[202:205], v[120:123]
	v_mfma_f32_16x16x32_bf16 v[116:119], v[194:197], v[202:205], v[116:119]
	v_mfma_f32_16x16x32_bf16 v[104:107], v[158:161], v[212:215], v[104:107]
	v_mfma_f32_16x16x32_bf16 v[100:103], v[194:197], v[212:215], v[100:103]
	v_mfma_f32_16x16x32_bf16 v[88:91], v[158:161], v[220:223], v[88:91]
	v_mfma_f32_16x16x32_bf16 v[84:87], v[194:197], v[220:223], v[84:87]
	v_mfma_f32_16x16x32_bf16 v[72:75], v[158:161], v[228:231], v[72:75]
	v_mfma_f32_16x16x32_bf16 v[68:71], v[194:197], v[228:231], v[68:71]
	v_mfma_f32_16x16x32_bf16 v[120:123], v[190:193], v[208:211], v[120:123]
	v_mfma_f32_16x16x32_bf16 v[116:119], v[198:201], v[208:211], v[116:119]
	v_mfma_f32_16x16x32_bf16 v[104:107], v[190:193], v[216:219], v[104:107]
	v_mfma_f32_16x16x32_bf16 v[100:103], v[198:201], v[216:219], v[100:103]
	v_mfma_f32_16x16x32_bf16 v[88:91], v[190:193], v[224:227], v[88:91]
	v_mfma_f32_16x16x32_bf16 v[84:87], v[198:201], v[224:227], v[84:87]
	v_mfma_f32_16x16x32_bf16 v[72:75], v[190:193], v[232:235], v[72:75]
	v_mfma_f32_16x16x32_bf16 v[68:71], v[198:201], v[232:235], v[68:71]
	s_setprio 0
	s_barrier
	s_add_i32 s14, s95, s57
	v_lshl_add_u64 v[162:163], s[86:87], 0, v[166:167]
	s_mov_b32 m0, s14
	ds_read_b128 v[202:205], v187 offset:16384
	ds_read_b128 v[208:211], v187 offset:17408
	ds_read_b128 v[212:215], v187 offset:18432
	ds_read_b128 v[216:219], v187 offset:19456
	ds_read_b128 v[220:223], v187 offset:20480
	ds_read_b128 v[224:227], v187 offset:21504
	ds_read_b128 v[228:231], v187 offset:22528
	ds_read_b128 v[232:235], v187 offset:23552
	global_load_lds_dwordx4 v[162:163], off
	s_add_i32 m0, s14, 0x2000
	s_add_u32 s14, s86, 0x80000
	v_lshl_add_u64 v[182:183], s[86:87], 0, v[170:171]
	s_addc_u32 s15, s87, 0
	s_add_i32 s49, s96, s57
	global_load_lds_dwordx4 v[182:183], off
	v_lshl_add_u64 v[236:237], s[14:15], 0, v[166:167]
	s_mov_b32 m0, s49
	v_lshl_add_u64 v[238:239], s[88:89], 0, v[168:169]
	global_load_lds_dwordx4 v[236:237], off
	v_lshl_add_u64 v[236:237], s[14:15], 0, v[170:171]
	s_add_i32 m0, s49, 0x2000
	s_nop 0
	global_load_lds_dwordx4 v[236:237], off
	v_lshl_add_u64 v[236:237], s[88:89], 0, v[164:165]
	s_mov_b32 m0, s59
	s_nop 0
	global_load_lds_dwordx4 v[236:237], off
	s_mov_b32 m0, s90
	s_nop 0
	global_load_lds_dwordx4 v[238:239], off
	s_waitcnt vmcnt(8)
	s_waitcnt lgkmcnt(0)
	s_barrier
; #define PG8_STAGE(bufoff, gbase, voff) do { _Pragma("unroll") for (int _i = 0; _i < 2; ++_i) \
;         __builtin_amdgcn_global_load_lds((const unsigned*)((const char*)(gbase) + (voff)[_i]), (LAS unsigned*)(lds + (bufoff) + ldsw + _i * 8192), 16, 0, 0); } while (0)
; #define PG8_LDA(dst, b, h) do { _Pragma("unroll") for (int m = 0; m < 4; ++m) _Pragma("unroll") for (int k = 0; k < 2; ++k) dst[m][k] = *(const LAS bf16x8*)(lds + PG8_SA(b, h) + aoff + m * 2048 + k * 1024); } while (0)
; #define PG8_LDB(dst, b, h) do { _Pragma("unroll") for (int n = 0; n < 2; ++n) _Pragma("unroll") for (int k = 0; k < 2; ++k) dst[n][k] = *(const LAS bf16x8*)(lds + PG8_SB(b, h) + boff + n * 2048 + k * 1024); } while (0)
; #define PG8_MMA(ai, bj, At, Bt) do { __builtin_amdgcn_s_setprio(1); _Pragma("unroll") for (int m = 0; m < 4; ++m) _Pragma("unroll") for (int n = 0; n < 2; ++n) _Pragma("unroll") for (int k = 0; k < 2; ++k) \
;         acc[ai][bj][m][n] = __builtin_amdgcn_mfma_f32_16x16x32_bf16(Bt[n][k], At[m][k], acc[ai][bj][m][n], 0, 0, 0); __builtin_amdgcn_s_setprio(0); } while (0)
; #define PG8_WAIT_V(n) asm volatile("s_waitcnt vmcnt(" #n ")" ::: "memory")
; #define PG8_WAIT_L(n) asm volatile("s_waitcnt lgkmcnt(" #n ")" ::: "memory")
; #define PG8_BAR __builtin_amdgcn_s_barrier()
; #define PG8_SCHED __builtin_amdgcn_sched_barrier(0)
; template <class Epi, class Sched, bool ALIGN_EPI, bool SP2>
; __device__ __forceinline__ void gemm_phase(LAS unsigned char* lds, const Gemm g, const Sched& S, const Epi& E) {
;     ...
;             PG8_WAIT_V(8); PG8_WAIT_L(0); PG8_BAR; PG8_MMA(1, 0, At, B0); PG8_MMA(1, 1, At, B1); PG8_BAR; PG8_SCHED;
;             PG8_LDB(B0, 1, 0); PG8_LDB(B1, 1, 1); PG8_SCHED; PG8_LDA(At, 1, 0); PG8_STAGE(PG8_SA(0, 1), a2 + hstep, voffA);
;             PG8_WAIT_V(8); PG8_WAIT_L(0); PG8_BAR; PG8_MMA(0, 0, At, B0); PG8_MMA(0, 1, At, B1); PG8_BAR; PG8_SCHED;
	s_setprio 1
	v_mfma_f32_16x16x32_bf16 v[64:67], v[142:145], v[202:205], v[64:67]
	v_mfma_f32_16x16x32_bf16 v[60:63], v[150:153], v[202:205], v[60:63]
	v_mfma_f32_16x16x32_bf16 v[48:51], v[142:145], v[212:215], v[48:51]
	v_mfma_f32_16x16x32_bf16 v[44:47], v[150:153], v[212:215], v[44:47]
	v_mfma_f32_16x16x32_bf16 v[32:35], v[142:145], v[220:223], v[32:35]
	v_mfma_f32_16x16x32_bf16 v[28:31], v[150:153], v[220:223], v[28:31]
	v_mfma_f32_16x16x32_bf16 v[16:19], v[142:145], v[228:231], v[16:19]
	v_mfma_f32_16x16x32_bf16 v[12:15], v[150:153], v[228:231], v[12:15]
	v_mfma_f32_16x16x32_bf16 v[64:67], v[146:149], v[208:211], v[64:67]
	v_mfma_f32_16x16x32_bf16 v[60:63], v[154:157], v[208:211], v[60:63]
	v_mfma_f32_16x16x32_bf16 v[48:51], v[146:149], v[216:219], v[48:51]
	v_mfma_f32_16x16x32_bf16 v[44:47], v[154:157], v[216:219], v[44:47]
	v_mfma_f32_16x16x32_bf16 v[32:35], v[146:149], v[224:227], v[32:35]
	v_mfma_f32_16x16x32_bf16 v[28:31], v[154:157], v[224:227], v[28:31]
	v_mfma_f32_16x16x32_bf16 v[16:19], v[146:149], v[232:235], v[16:19]
	v_mfma_f32_16x16x32_bf16 v[12:15], v[154:157], v[232:235], v[12:15]
	v_mfma_f32_16x16x32_bf16 v[56:59], v[158:161], v[202:205], v[56:59]
	v_mfma_f32_16x16x32_bf16 v[52:55], v[194:197], v[202:205], v[52:55]
	v_mfma_f32_16x16x32_bf16 v[40:43], v[158:161], v[212:215], v[40:43]
	v_mfma_f32_16x16x32_bf16 v[36:39], v[194:197], v[212:215], v[36:39]
	v_mfma_f32_16x16x32_bf16 v[24:27], v[158:161], v[220:223], v[24:27]
	v_mfma_f32_16x16x32_bf16 v[20:23], v[194:197], v[220:223], v[20:23]
	v_mfma_f32_16x16x32_bf16 v[8:11], v[158:161], v[228:231], v[8:11]
	v_mfma_f32_16x16x32_bf16 v[4:7], v[194:197], v[228:231], v[4:7]
	v_mfma_f32_16x16x32_bf16 v[56:59], v[190:193], v[208:211], v[56:59]
	v_mfma_f32_16x16x32_bf16 v[52:55], v[198:201], v[208:211], v[52:55]
	v_mfma_f32_16x16x32_bf16 v[40:43], v[190:193], v[216:219], v[40:43]
	v_mfma_f32_16x16x32_bf16 v[36:39], v[198:201], v[216:219], v[36:39]
	v_mfma_f32_16x16x32_bf16 v[24:27], v[190:193], v[224:227], v[24:27]
	v_mfma_f32_16x16x32_bf16 v[20:23], v[198:201], v[224:227], v[20:23]
	v_mfma_f32_16x16x32_bf16 v[8:11], v[190:193], v[232:235], v[8:11]
	v_mfma_f32_16x16x32_bf16 v[4:7], v[198:201], v[232:235], v[4:7]
	s_setprio 0
	s_barrier
	s_add_i32 s49, 0, 0x18000
	v_add_u32_e32 v1, s49, v185
	s_add_i32 s58, 0, 0x1c000
	ds_read_b128 v[142:145], v1
	ds_read_b128 v[146:149], v1 offset:1024
	ds_read_b128 v[150:153], v1 offset:2048
	ds_read_b128 v[154:157], v1 offset:3072
	v_add_u32_e32 v1, s58, v185
	ds_read_b128 v[158:161], v1
	ds_read_b128 v[190:193], v1 offset:1024
	ds_read_b128 v[194:197], v1 offset:2048
	ds_read_b128 v[198:201], v1 offset:3072
	s_add_u32 s14, s88, 0x80000
	s_addc_u32 s15, s89, 0
	s_mov_b32 m0, s91
	v_lshl_add_u64 v[240:241], s[14:15], 0, v[164:165]
	ds_read_b128 v[202:205], v187 offset:32768
	ds_read_b128 v[208:211], v187 offset:33792
	ds_read_b128 v[212:215], v187 offset:34816
	ds_read_b128 v[216:219], v187 offset:35840
	ds_read_b128 v[220:223], v187 offset:36864
	ds_read_b128 v[224:227], v187 offset:37888
	ds_read_b128 v[228:231], v187 offset:38912
	ds_read_b128 v[232:235], v187 offset:39936
	global_load_lds_dwordx4 v[240:241], off
	v_lshl_add_u64 v[240:241], s[14:15], 0, v[168:169]
	s_mov_b32 m0, s92
	s_nop 0
	global_load_lds_dwordx4 v[240:241], off
	s_waitcnt vmcnt(8)
	s_waitcnt lgkmcnt(0)
	s_barrier
	s_setprio 1
	v_mfma_f32_16x16x32_bf16 v[128:131], v[142:145], v[202:205], v[128:131]
	v_mfma_f32_16x16x32_bf16 v[124:127], v[150:153], v[202:205], v[124:127]
	v_mfma_f32_16x16x32_bf16 v[112:115], v[142:145], v[212:215], v[112:115]
	v_mfma_f32_16x16x32_bf16 v[108:111], v[150:153], v[212:215], v[108:111]
	v_mfma_f32_16x16x32_bf16 v[96:99], v[142:145], v[220:223], v[96:99]
	v_mfma_f32_16x16x32_bf16 v[92:95], v[150:153], v[220:223], v[92:95]
	v_mfma_f32_16x16x32_bf16 v[80:83], v[142:145], v[228:231], v[80:83]
	v_mfma_f32_16x16x32_bf16 v[76:79], v[150:153], v[228:231], v[76:79]
	v_mfma_f32_16x16x32_bf16 v[128:131], v[146:149], v[208:211], v[128:131]
	v_mfma_f32_16x16x32_bf16 v[124:127], v[154:157], v[208:211], v[124:127]
	v_mfma_f32_16x16x32_bf16 v[112:115], v[146:149], v[216:219], v[112:115]
	v_mfma_f32_16x16x32_bf16 v[108:111], v[154:157], v[216:219], v[108:111]
	v_mfma_f32_16x16x32_bf16 v[96:99], v[146:149], v[224:227], v[96:99]
	v_mfma_f32_16x16x32_bf16 v[92:95], v[154:157], v[224:227], v[92:95]
	v_mfma_f32_16x16x32_bf16 v[80:83], v[146:149], v[232:235], v[80:83]
	v_mfma_f32_16x16x32_bf16 v[76:79], v[154:157], v[232:235], v[76:79]
	v_mfma_f32_16x16x32_bf16 v[120:123], v[158:161], v[202:205], v[120:123]
	v_mfma_f32_16x16x32_bf16 v[116:119], v[194:197], v[202:205], v[116:119]
	v_mfma_f32_16x16x32_bf16 v[104:107], v[158:161], v[212:215], v[104:107]
	v_mfma_f32_16x16x32_bf16 v[100:103], v[194:197], v[212:215], v[100:103]
	v_mfma_f32_16x16x32_bf16 v[88:91], v[158:161], v[220:223], v[88:91]
	v_mfma_f32_16x16x32_bf16 v[84:87], v[194:197], v[220:223], v[84:87]
	v_mfma_f32_16x16x32_bf16 v[72:75], v[158:161], v[228:231], v[72:75]
	v_mfma_f32_16x16x32_bf16 v[68:71], v[194:197], v[228:231], v[68:71]
	v_mfma_f32_16x16x32_bf16 v[120:123], v[190:193], v[208:211], v[120:123]
	v_mfma_f32_16x16x32_bf16 v[116:119], v[198:201], v[208:211], v[116:119]
	v_mfma_f32_16x16x32_bf16 v[104:107], v[190:193], v[216:219], v[104:107]
	v_mfma_f32_16x16x32_bf16 v[100:103], v[198:201], v[216:219], v[100:103]
	v_mfma_f32_16x16x32_bf16 v[88:91], v[190:193], v[224:227], v[88:91]
	v_mfma_f32_16x16x32_bf16 v[84:87], v[198:201], v[224:227], v[84:87]
	v_mfma_f32_16x16x32_bf16 v[72:75], v[190:193], v[232:235], v[72:75]
	v_mfma_f32_16x16x32_bf16 v[68:71], v[198:201], v[232:235], v[68:71]
	s_setprio 0
	s_barrier
; #define PG8_STAGE(bufoff, gbase, voff) do { _Pragma("unroll") for (int _i = 0; _i < 2; ++_i) \
;         __builtin_amdgcn_global_load_lds((const unsigned*)((const char*)(gbase) + (voff)[_i]), (LAS unsigned*)(lds + (bufoff) + ldsw + _i * 8192), 16, 0, 0); } while (0)
; #define PG8_LDA(dst, b, h) do { _Pragma("unroll") for (int m = 0; m < 4; ++m) _Pragma("unroll") for (int k = 0; k < 2; ++k) dst[m][k] = *(const LAS bf16x8*)(lds + PG8_SA(b, h) + aoff + m * 2048 + k * 1024); } while (0)
; #define PG8_MMA(ai, bj, At, Bt) do { __builtin_amdgcn_s_setprio(1); _Pragma("unroll") for (int m = 0; m < 4; ++m) _Pragma("unroll") for (int n = 0; n < 2; ++n) _Pragma("unroll") for (int k = 0; k < 2; ++k) \
;         acc[ai][bj][m][n] = __builtin_amdgcn_mfma_f32_16x16x32_bf16(Bt[n][k], At[m][k], acc[ai][bj][m][n], 0, 0, 0); __builtin_amdgcn_s_setprio(0); } while (0)
; #define PG8_WAIT_V(n) asm volatile("s_waitcnt vmcnt(" #n ")" ::: "memory")
; #define PG8_WAIT_L(n) asm volatile("s_waitcnt lgkmcnt(" #n ")" ::: "memory")
; #define PG8_BAR __builtin_amdgcn_s_barrier()
; #define PG8_SCHED __builtin_amdgcn_sched_barrier(0)
; template <class Epi, class Sched, bool ALIGN_EPI, bool SP2>
; __device__ __forceinline__ void gemm_phase(LAS unsigned char* lds, const Gemm g, const Sched& S, const Epi& E) {
;     ...
;         for (int t = tb; t < te; t += 2) {
;             const bool last = (t == nt - 2);
;             const char* a1 = cA + (size_t)(t + 1) * kstep;
;             const char* a2 = last ? nA : cA + (size_t)(t + 2) * kstep; const char* b2 = last ? nB : cB + (size_t)(t + 2) * kstep;
;             const char* a3 = a2 + kstep; const char* b3 = b2 + kstep;
;     ...
;             PG8_LDA(At, 1, 1); PG8_STAGE(PG8_SB(1, 0), b3, voffB); PG8_STAGE(PG8_SB(1, 1), b3 + hstepB, voffB); PG8_STAGE(PG8_SA(1, 0), a3, voffA);
;             PG8_WAIT_V(8); PG8_WAIT_L(0); PG8_BAR; PG8_MMA(1, 0, At, B0); PG8_MMA(1, 1, At, B1); PG8_BAR; PG8_SCHED;
	s_add_i32 s14, s49, s57
	v_lshl_add_u64 v[162:163], v[162:163], 0, s[42:43]
	s_mov_b32 m0, s14
	ds_read_b128 v[202:205], v187 offset:49152
	ds_read_b128 v[208:211], v187 offset:50176
	ds_read_b128 v[212:215], v187 offset:51200
	ds_read_b128 v[216:219], v187 offset:52224
	ds_read_b128 v[220:223], v187 offset:53248
	ds_read_b128 v[224:227], v187 offset:54272
	ds_read_b128 v[228:231], v187 offset:55296
	ds_read_b128 v[232:235], v187 offset:56320
	global_load_lds_dwordx4 v[162:163], off
	s_add_i32 m0, s14, 0x2000
	s_add_u32 s14, s86, 0x80080
	v_lshl_add_u64 v[162:163], v[182:183], 0, s[42:43]
	s_addc_u32 s15, s87, 0
	s_add_i32 s49, s58, s57
	global_load_lds_dwordx4 v[162:163], off
	v_lshl_add_u64 v[162:163], s[14:15], 0, v[166:167]
	s_mov_b32 m0, s49
	s_nop 0
	global_load_lds_dwordx4 v[162:163], off
	v_lshl_add_u64 v[162:163], s[14:15], 0, v[170:171]
	s_add_i32 m0, s49, 0x2000
	s_nop 0
	global_load_lds_dwordx4 v[162:163], off
	v_lshl_add_u64 v[162:163], v[236:237], 0, s[42:43]
	s_mov_b32 m0, s93
	s_nop 0
	global_load_lds_dwordx4 v[162:163], off
	v_lshl_add_u64 v[162:163], v[238:239], 0, s[42:43]
	s_mov_b32 m0, s94
	s_nop 0
	global_load_lds_dwordx4 v[162:163], off
	s_waitcnt vmcnt(8)
	s_waitcnt lgkmcnt(0)
	s_barrier
	s_setprio 1
	v_mfma_f32_16x16x32_bf16 v[64:67], v[142:145], v[202:205], v[64:67]
	v_mfma_f32_16x16x32_bf16 v[60:63], v[150:153], v[202:205], v[60:63]
	v_mfma_f32_16x16x32_bf16 v[48:51], v[142:145], v[212:215], v[48:51]
	v_mfma_f32_16x16x32_bf16 v[44:47], v[150:153], v[212:215], v[44:47]
	v_mfma_f32_16x16x32_bf16 v[32:35], v[142:145], v[220:223], v[32:35]
	v_mfma_f32_16x16x32_bf16 v[28:31], v[150:153], v[220:223], v[28:31]
	v_mfma_f32_16x16x32_bf16 v[16:19], v[142:145], v[228:231], v[16:19]
	v_mfma_f32_16x16x32_bf16 v[12:15], v[150:153], v[228:231], v[12:15]
	v_mfma_f32_16x16x32_bf16 v[64:67], v[146:149], v[208:211], v[64:67]
	v_mfma_f32_16x16x32_bf16 v[60:63], v[154:157], v[208:211], v[60:63]
	v_mfma_f32_16x16x32_bf16 v[48:51], v[146:149], v[216:219], v[48:51]
	v_mfma_f32_16x16x32_bf16 v[44:47], v[154:157], v[216:219], v[44:47]
	v_mfma_f32_16x16x32_bf16 v[32:35], v[146:149], v[224:227], v[32:35]
	v_mfma_f32_16x16x32_bf16 v[28:31], v[154:157], v[224:227], v[28:31]
	v_mfma_f32_16x16x32_bf16 v[16:19], v[146:149], v[232:235], v[16:19]
	v_mfma_f32_16x16x32_bf16 v[12:15], v[154:157], v[232:235], v[12:15]
	v_mfma_f32_16x16x32_bf16 v[56:59], v[158:161], v[202:205], v[56:59]
	v_mfma_f32_16x16x32_bf16 v[52:55], v[194:197], v[202:205], v[52:55]
	v_mfma_f32_16x16x32_bf16 v[40:43], v[158:161], v[212:215], v[40:43]
	v_mfma_f32_16x16x32_bf16 v[36:39], v[194:197], v[212:215], v[36:39]
	v_mfma_f32_16x16x32_bf16 v[24:27], v[158:161], v[220:223], v[24:27]
	v_mfma_f32_16x16x32_bf16 v[20:23], v[194:197], v[220:223], v[20:23]
	v_mfma_f32_16x16x32_bf16 v[8:11], v[158:161], v[228:231], v[8:11]
	v_mfma_f32_16x16x32_bf16 v[4:7], v[194:197], v[228:231], v[4:7]
	v_mfma_f32_16x16x32_bf16 v[56:59], v[190:193], v[208:211], v[56:59]
	v_mfma_f32_16x16x32_bf16 v[52:55], v[198:201], v[208:211], v[52:55]
	v_mfma_f32_16x16x32_bf16 v[40:43], v[190:193], v[216:219], v[40:43]
	v_mfma_f32_16x16x32_bf16 v[36:39], v[198:201], v[216:219], v[36:39]
	v_mfma_f32_16x16x32_bf16 v[24:27], v[190:193], v[224:227], v[24:27]
	v_mfma_f32_16x16x32_bf16 v[20:23], v[198:201], v[224:227], v[20:23]
	v_mfma_f32_16x16x32_bf16 v[8:11], v[190:193], v[232:235], v[8:11]
	v_mfma_f32_16x16x32_bf16 v[4:7], v[198:201], v[232:235], v[4:7]
	s_setprio 0
	s_barrier
	s_add_u32 s84, s84, 0x100
	s_addc_u32 s85, s85, 0
	s_add_u32 s82, s82, 0x100
	s_addc_u32 s83, s83, 0
	s_add_u32 s80, s80, 0xffffff00
	s_addc_u32 s81, s81, -1
	v_lshl_add_u64 v[140:141], v[140:141], 0, s[46:47]
	s_cmp_ge_u32 s10, s33
	v_lshl_add_u64 v[2:3], v[2:3], 0, s[46:47]
	s_cbranch_scc0 .LBB0_878

; #define PG8_STAGE(bufoff, gbase, voff) do { _Pragma("unroll") for (int _i = 0; _i < 2; ++_i) \
;         __builtin_amdgcn_global_load_lds((const unsigned*)((const char*)(gbase) + (voff)[_i]), (LAS unsigned*)(lds + (bufoff) + ldsw + _i * 8192), 16, 0, 0); } while (0)
; #define PG8_LDA(dst, b, h) do { _Pragma("unroll") for (int m = 0; m < 4; ++m) _Pragma("unroll") for (int k = 0; k < 2; ++k) dst[m][k] = *(const LAS bf16x8*)(lds + PG8_SA(b, h) + aoff + m * 2048 + k * 1024); } while (0)
; #define PG8_LDB(dst, b, h) do { _Pragma("unroll") for (int n = 0; n < 2; ++n) _Pragma("unroll") for (int k = 0; k < 2; ++k) dst[n][k] = *(const LAS bf16x8*)(lds + PG8_SB(b, h) + boff + n * 2048 + k * 1024); } while (0)
; #define PG8_MMA(ai, bj, At, Bt) do { __builtin_amdgcn_s_setprio(1); _Pragma("unroll") for (int m = 0; m < 4; ++m) _Pragma("unroll") for (int n = 0; n < 2; ++n) _Pragma("unroll") for (int k = 0; k < 2; ++k) \
;         acc[ai][bj][m][n] = __builtin_amdgcn_mfma_f32_16x16x32_bf16(Bt[n][k], At[m][k], acc[ai][bj][m][n], 0, 0, 0); __builtin_amdgcn_s_setprio(0); } while (0)
; #define PG8_WAIT_V(n) asm volatile("s_waitcnt vmcnt(" #n ")" ::: "memory")
; #define PG8_WAIT_L(n) asm volatile("s_waitcnt lgkmcnt(" #n ")" ::: "memory")
; template <class Epi, class Sched, bool ALIGN_EPI, bool SP2>
; __device__ __forceinline__ void gemm_phase(LAS unsigned char* lds, const Gemm g, const Sched& S, const Epi& E) {
;     ...
;         for (int t = tb; t < te; t += 2) {
;             const bool last = (t == nt - 2);
;             const char* a1 = cA + (size_t)(t + 1) * kstep;
;             const char* a2 = last ? nA : cA + (size_t)(t + 2) * kstep; const char* b2 = last ? nB : cB + (size_t)(t + 2) * kstep;
;             const char* a3 = a2 + kstep; const char* b3 = b2 + kstep;
;             if (last && has_next) S.a_ready(nxt);
;             if constexpr (SP2) {
;             PG8_LDB(B0, 0, 0); PG8_LDB(B1, 0, 1); PG8_SCHED; PG8_LDA(At, 0, 0); PG8_STAGE(PG8_SA(1, 1), a1 + hstep, voffA);
;             PG8_WAIT_V(8); PG8_WAIT_L(0); PG8_BAR; PG8_MMA(0, 0, At, B0); PG8_MMA(0, 1, At, B1); PG8_BAR; PG8_SCHED;
;             PG8_LDA(At, 0, 1); PG8_STAGE(PG8_SB(0, 0), b2, voffB); PG8_STAGE(PG8_SB(0, 1), b2 + hstepB, voffB); PG8_STAGE(PG8_SA(0, 0), a2, voffA);
;             PG8_WAIT_V(8); PG8_WAIT_L(0); PG8_BAR; PG8_MMA(1, 0, At, B0); PG8_MMA(1, 1, At, B1); PG8_BAR; PG8_SCHED;
.LBB0_979:
	v_add_u32_e32 v131, s89, v210
	ds_read_b128 v[152:155], v131
	ds_read_b128 v[156:159], v131 offset:1024
	ds_read_b128 v[160:163], v131 offset:2048
	ds_read_b128 v[164:167], v131 offset:3072
	v_add_u32_e32 v131, s90, v210
	ds_read_b128 v[168:171], v131
	ds_read_b128 v[172:175], v131 offset:1024
	ds_read_b128 v[176:179], v131 offset:2048
	ds_read_b128 v[180:183], v131 offset:3072
	s_add_u32 s0, s76, 0xfff80080
	s_addc_u32 s58, s77, -1
	s_and_b64 s[14:15], s[78:79], exec
	s_cselect_b32 s81, s48, s58
	s_cselect_b32 s80, s49, s0
	s_cselect_b32 s79, s63, s97
	s_cselect_b32 s78, s65, s71
	v_lshl_add_u64 v[204:205], s[76:77], 0, v[142:143]
	s_add_i32 m0, s59, 0xc000
	ds_read_b128 v[184:187], v214
	ds_read_b128 v[188:191], v214 offset:1024
	ds_read_b128 v[192:195], v214 offset:2048
	ds_read_b128 v[196:199], v214 offset:3072
	ds_read_b128 v[200:203], v214 offset:4096
	ds_read_b128 v[216:219], v214 offset:5120
	ds_read_b128 v[220:223], v214 offset:6144
	ds_read_b128 v[224:227], v214 offset:7168
	global_load_lds_dwordx4 v[204:205], off
	v_lshl_add_u64 v[204:205], s[76:77], 0, v[144:145]
	s_add_i32 m0, s59, 0xe000
	s_nop 0
	global_load_lds_dwordx4 v[204:205], off
	s_waitcnt vmcnt(8)
	s_waitcnt lgkmcnt(0)
	s_barrier
	s_setprio 1
	v_mfma_f32_16x16x32_bf16 v[124:127], v[152:155], v[184:187], v[124:127]
	v_mfma_f32_16x16x32_bf16 v[120:123], v[160:163], v[184:187], v[120:123]
	v_mfma_f32_16x16x32_bf16 v[76:79], v[152:155], v[192:195], v[76:79]
	v_mfma_f32_16x16x32_bf16 v[28:31], v[160:163], v[192:195], v[28:31]
	v_mfma_f32_16x16x32_bf16 v[52:55], v[152:155], v[200:203], v[52:55]
	v_mfma_f32_16x16x32_bf16 v[20:23], v[160:163], v[200:203], v[20:23]
	v_mfma_f32_16x16x32_bf16 v[108:111], v[152:155], v[220:223], v[108:111]
	v_mfma_f32_16x16x32_bf16 v[104:107], v[160:163], v[220:223], v[104:107]
	v_mfma_f32_16x16x32_bf16 v[124:127], v[156:159], v[188:191], v[124:127]
	v_mfma_f32_16x16x32_bf16 v[120:123], v[164:167], v[188:191], v[120:123]
	v_mfma_f32_16x16x32_bf16 v[76:79], v[156:159], v[196:199], v[76:79]
	v_mfma_f32_16x16x32_bf16 v[28:31], v[164:167], v[196:199], v[28:31]
	v_mfma_f32_16x16x32_bf16 v[52:55], v[156:159], v[216:219], v[52:55]
	v_mfma_f32_16x16x32_bf16 v[20:23], v[164:167], v[216:219], v[20:23]
	v_mfma_f32_16x16x32_bf16 v[108:111], v[156:159], v[224:227], v[108:111]
	v_mfma_f32_16x16x32_bf16 v[104:107], v[164:167], v[224:227], v[104:107]
	v_mfma_f32_16x16x32_bf16 v[116:119], v[168:171], v[184:187], v[116:119]
	v_mfma_f32_16x16x32_bf16 v[112:115], v[176:179], v[184:187], v[112:115]
	v_mfma_f32_16x16x32_bf16 v[64:67], v[168:171], v[192:195], v[64:67]
	v_mfma_f32_16x16x32_bf16 v[24:27], v[176:179], v[192:195], v[24:27]
	v_mfma_f32_16x16x32_bf16 v[48:51], v[168:171], v[200:203], v[48:51]
	v_mfma_f32_16x16x32_bf16 v[16:19], v[176:179], v[200:203], v[16:19]
	v_mfma_f32_16x16x32_bf16 v[100:103], v[168:171], v[220:223], v[100:103]
	v_mfma_f32_16x16x32_bf16 v[96:99], v[176:179], v[220:223], v[96:99]
	v_mfma_f32_16x16x32_bf16 v[116:119], v[172:175], v[188:191], v[116:119]
	v_mfma_f32_16x16x32_bf16 v[112:115], v[180:183], v[188:191], v[112:115]
	v_mfma_f32_16x16x32_bf16 v[64:67], v[172:175], v[196:199], v[64:67]
	v_mfma_f32_16x16x32_bf16 v[24:27], v[180:183], v[196:199], v[24:27]
	v_mfma_f32_16x16x32_bf16 v[48:51], v[172:175], v[216:219], v[48:51]
	v_mfma_f32_16x16x32_bf16 v[16:19], v[180:183], v[216:219], v[16:19]
	v_mfma_f32_16x16x32_bf16 v[100:103], v[172:175], v[224:227], v[100:103]
	v_mfma_f32_16x16x32_bf16 v[96:99], v[180:183], v[224:227], v[96:99]
	s_setprio 0
	s_barrier
	s_add_i32 s0, s89, s57
	v_lshl_add_u64 v[204:205], s[78:79], 0, v[134:135]
	s_mov_b32 m0, s0
	ds_read_b128 v[184:187], v214 offset:16384
	ds_read_b128 v[188:191], v214 offset:17408
	ds_read_b128 v[192:195], v214 offset:18432
	ds_read_b128 v[196:199], v214 offset:19456
	ds_read_b128 v[200:203], v214 offset:20480
	ds_read_b128 v[216:219], v214 offset:21504
	ds_read_b128 v[220:223], v214 offset:22528
	ds_read_b128 v[224:227], v214 offset:23552
	global_load_lds_dwordx4 v[204:205], off
	s_add_i32 m0, s0, 0x2000
	s_add_u32 s14, s78, 0x80000
	v_lshl_add_u64 v[228:229], s[78:79], 0, v[138:139]
	s_addc_u32 s15, s79, 0
	s_add_i32 s0, s90, s57
	global_load_lds_dwordx4 v[228:229], off
	v_lshl_add_u64 v[230:231], s[14:15], 0, v[134:135]
	s_mov_b32 m0, s0
	v_lshl_add_u64 v[232:233], s[80:81], 0, v[136:137]
	global_load_lds_dwordx4 v[230:231], off
	v_lshl_add_u64 v[230:231], s[14:15], 0, v[138:139]
	s_add_i32 m0, s0, 0x2000
	s_nop 0
	global_load_lds_dwordx4 v[230:231], off
	v_lshl_add_u64 v[230:231], s[80:81], 0, v[132:133]
	s_mov_b32 m0, s59
	s_nop 0
	global_load_lds_dwordx4 v[230:231], off
	s_mov_b32 m0, s73
	s_nop 0
	global_load_lds_dwordx4 v[232:233], off
	s_waitcnt vmcnt(8)
	s_waitcnt lgkmcnt(0)
	s_barrier
; #define PG8_STAGE(bufoff, gbase, voff) do { _Pragma("unroll") for (int _i = 0; _i < 2; ++_i) \
;         __builtin_amdgcn_global_load_lds((const unsigned*)((const char*)(gbase) + (voff)[_i]), (LAS unsigned*)(lds + (bufoff) + ldsw + _i * 8192), 16, 0, 0); } while (0)
; #define PG8_LDA(dst, b, h) do { _Pragma("unroll") for (int m = 0; m < 4; ++m) _Pragma("unroll") for (int k = 0; k < 2; ++k) dst[m][k] = *(const LAS bf16x8*)(lds + PG8_SA(b, h) + aoff + m * 2048 + k * 1024); } while (0)
; #define PG8_LDB(dst, b, h) do { _Pragma("unroll") for (int n = 0; n < 2; ++n) _Pragma("unroll") for (int k = 0; k < 2; ++k) dst[n][k] = *(const LAS bf16x8*)(lds + PG8_SB(b, h) + boff + n * 2048 + k * 1024); } while (0)
; #define PG8_MMA(ai, bj, At, Bt) do { __builtin_amdgcn_s_setprio(1); _Pragma("unroll") for (int m = 0; m < 4; ++m) _Pragma("unroll") for (int n = 0; n < 2; ++n) _Pragma("unroll") for (int k = 0; k < 2; ++k) \
;         acc[ai][bj][m][n] = __builtin_amdgcn_mfma_f32_16x16x32_bf16(Bt[n][k], At[m][k], acc[ai][bj][m][n], 0, 0, 0); __builtin_amdgcn_s_setprio(0); } while (0)
; #define PG8_WAIT_V(n) asm volatile("s_waitcnt vmcnt(" #n ")" ::: "memory")
; #define PG8_WAIT_L(n) asm volatile("s_waitcnt lgkmcnt(" #n ")" ::: "memory")
; #define PG8_BAR __builtin_amdgcn_s_barrier()
; #define PG8_SCHED __builtin_amdgcn_sched_barrier(0)
; template <class Epi, class Sched, bool ALIGN_EPI, bool SP2>
; __device__ __forceinline__ void gemm_phase(LAS unsigned char* lds, const Gemm g, const Sched& S, const Epi& E) {
;     ...
;             PG8_WAIT_V(8); PG8_WAIT_L(0); PG8_BAR; PG8_MMA(1, 0, At, B0); PG8_MMA(1, 1, At, B1); PG8_BAR; PG8_SCHED;
;             PG8_LDB(B0, 1, 0); PG8_LDB(B1, 1, 1); PG8_SCHED; PG8_LDA(At, 1, 0); PG8_STAGE(PG8_SA(0, 1), a2 + hstep, voffA);
;             PG8_WAIT_V(8); PG8_WAIT_L(0); PG8_BAR; PG8_MMA(0, 0, At, B0); PG8_MMA(0, 1, At, B1); PG8_BAR; PG8_SCHED;
	s_setprio 1
	v_mfma_f32_16x16x32_bf16 v[92:95], v[152:155], v[184:187], v[92:95]
	v_mfma_f32_16x16x32_bf16 v[88:91], v[160:163], v[184:187], v[88:91]
	v_mfma_f32_16x16x32_bf16 v[44:47], v[152:155], v[192:195], v[44:47]
	v_mfma_f32_16x16x32_bf16 v[12:15], v[160:163], v[192:195], v[12:15]
	v_mfma_f32_16x16x32_bf16 v[36:39], v[152:155], v[200:203], v[36:39]
	v_mfma_f32_16x16x32_bf16 v[4:7], v[160:163], v[200:203], v[4:7]
	v_mfma_f32_16x16x32_bf16 v[72:75], v[152:155], v[220:223], v[72:75]
	v_mfma_f32_16x16x32_bf16 v[68:71], v[160:163], v[220:223], v[68:71]
	v_mfma_f32_16x16x32_bf16 v[92:95], v[156:159], v[188:191], v[92:95]
	v_mfma_f32_16x16x32_bf16 v[88:91], v[164:167], v[188:191], v[88:91]
	v_mfma_f32_16x16x32_bf16 v[44:47], v[156:159], v[196:199], v[44:47]
	v_mfma_f32_16x16x32_bf16 v[12:15], v[164:167], v[196:199], v[12:15]
	v_mfma_f32_16x16x32_bf16 v[36:39], v[156:159], v[216:219], v[36:39]
	v_mfma_f32_16x16x32_bf16 v[4:7], v[164:167], v[216:219], v[4:7]
	v_mfma_f32_16x16x32_bf16 v[72:75], v[156:159], v[224:227], v[72:75]
	v_mfma_f32_16x16x32_bf16 v[68:71], v[164:167], v[224:227], v[68:71]
	v_mfma_f32_16x16x32_bf16 v[84:87], v[168:171], v[184:187], v[84:87]
	v_mfma_f32_16x16x32_bf16 v[80:83], v[176:179], v[184:187], v[80:83]
	v_mfma_f32_16x16x32_bf16 v[40:43], v[168:171], v[192:195], v[40:43]
	v_mfma_f32_16x16x32_bf16 v[8:11], v[176:179], v[192:195], v[8:11]
	v_mfma_f32_16x16x32_bf16 v[32:35], v[168:171], v[200:203], v[32:35]
	v_mfma_f32_16x16x32_bf16 v[0:3], v[176:179], v[200:203], v[0:3]
	v_mfma_f32_16x16x32_bf16 v[60:63], v[168:171], v[220:223], v[60:63]
	v_mfma_f32_16x16x32_bf16 v[56:59], v[176:179], v[220:223], v[56:59]
	v_mfma_f32_16x16x32_bf16 v[84:87], v[172:175], v[188:191], v[84:87]
	v_mfma_f32_16x16x32_bf16 v[80:83], v[180:183], v[188:191], v[80:83]
	v_mfma_f32_16x16x32_bf16 v[40:43], v[172:175], v[196:199], v[40:43]
	v_mfma_f32_16x16x32_bf16 v[8:11], v[180:183], v[196:199], v[8:11]
	v_mfma_f32_16x16x32_bf16 v[32:35], v[172:175], v[216:219], v[32:35]
	v_mfma_f32_16x16x32_bf16 v[0:3], v[180:183], v[216:219], v[0:3]
	v_mfma_f32_16x16x32_bf16 v[60:63], v[172:175], v[224:227], v[60:63]
	v_mfma_f32_16x16x32_bf16 v[56:59], v[180:183], v[224:227], v[56:59]
	s_setprio 0
	s_barrier
	s_add_i32 s0, 0, 0x18000
	v_add_u32_e32 v131, s0, v210
	s_add_i32 s58, 0, 0x1c000
	ds_read_b128 v[152:155], v131
	ds_read_b128 v[156:159], v131 offset:1024
	ds_read_b128 v[160:163], v131 offset:2048
	ds_read_b128 v[164:167], v131 offset:3072
	v_add_u32_e32 v131, s58, v210
	ds_read_b128 v[168:171], v131
	ds_read_b128 v[172:175], v131 offset:1024
	ds_read_b128 v[176:179], v131 offset:2048
	ds_read_b128 v[180:183], v131 offset:3072
	s_add_u32 s14, s80, 0x80000
	s_addc_u32 s15, s81, 0
	s_mov_b32 m0, s84
	v_lshl_add_u64 v[234:235], s[14:15], 0, v[132:133]
	ds_read_b128 v[184:187], v214 offset:32768
	ds_read_b128 v[188:191], v214 offset:33792
	ds_read_b128 v[192:195], v214 offset:34816
	ds_read_b128 v[196:199], v214 offset:35840
	ds_read_b128 v[200:203], v214 offset:36864
	ds_read_b128 v[216:219], v214 offset:37888
	ds_read_b128 v[220:223], v214 offset:38912
	ds_read_b128 v[224:227], v214 offset:39936
	global_load_lds_dwordx4 v[234:235], off
	v_lshl_add_u64 v[234:235], s[14:15], 0, v[136:137]
	s_mov_b32 m0, s85
	s_nop 0
	global_load_lds_dwordx4 v[234:235], off
	s_waitcnt vmcnt(8)
	s_waitcnt lgkmcnt(0)
	s_barrier
	s_setprio 1
	v_mfma_f32_16x16x32_bf16 v[124:127], v[152:155], v[184:187], v[124:127]
	v_mfma_f32_16x16x32_bf16 v[120:123], v[160:163], v[184:187], v[120:123]
	v_mfma_f32_16x16x32_bf16 v[76:79], v[152:155], v[192:195], v[76:79]
	v_mfma_f32_16x16x32_bf16 v[28:31], v[160:163], v[192:195], v[28:31]
	v_mfma_f32_16x16x32_bf16 v[52:55], v[152:155], v[200:203], v[52:55]
	v_mfma_f32_16x16x32_bf16 v[20:23], v[160:163], v[200:203], v[20:23]
	v_mfma_f32_16x16x32_bf16 v[108:111], v[152:155], v[220:223], v[108:111]
	v_mfma_f32_16x16x32_bf16 v[104:107], v[160:163], v[220:223], v[104:107]
	v_mfma_f32_16x16x32_bf16 v[124:127], v[156:159], v[188:191], v[124:127]
	v_mfma_f32_16x16x32_bf16 v[120:123], v[164:167], v[188:191], v[120:123]
	v_mfma_f32_16x16x32_bf16 v[76:79], v[156:159], v[196:199], v[76:79]
	v_mfma_f32_16x16x32_bf16 v[28:31], v[164:167], v[196:199], v[28:31]
	v_mfma_f32_16x16x32_bf16 v[52:55], v[156:159], v[216:219], v[52:55]
	v_mfma_f32_16x16x32_bf16 v[20:23], v[164:167], v[216:219], v[20:23]
	v_mfma_f32_16x16x32_bf16 v[108:111], v[156:159], v[224:227], v[108:111]
	v_mfma_f32_16x16x32_bf16 v[104:107], v[164:167], v[224:227], v[104:107]
	v_mfma_f32_16x16x32_bf16 v[116:119], v[168:171], v[184:187], v[116:119]
	v_mfma_f32_16x16x32_bf16 v[112:115], v[176:179], v[184:187], v[112:115]
	v_mfma_f32_16x16x32_bf16 v[64:67], v[168:171], v[192:195], v[64:67]
	v_mfma_f32_16x16x32_bf16 v[24:27], v[176:179], v[192:195], v[24:27]
	v_mfma_f32_16x16x32_bf16 v[48:51], v[168:171], v[200:203], v[48:51]
	v_mfma_f32_16x16x32_bf16 v[16:19], v[176:179], v[200:203], v[16:19]
	v_mfma_f32_16x16x32_bf16 v[100:103], v[168:171], v[220:223], v[100:103]
	v_mfma_f32_16x16x32_bf16 v[96:99], v[176:179], v[220:223], v[96:99]
	v_mfma_f32_16x16x32_bf16 v[116:119], v[172:175], v[188:191], v[116:119]
	v_mfma_f32_16x16x32_bf16 v[112:115], v[180:183], v[188:191], v[112:115]
	v_mfma_f32_16x16x32_bf16 v[64:67], v[172:175], v[196:199], v[64:67]
	v_mfma_f32_16x16x32_bf16 v[24:27], v[180:183], v[196:199], v[24:27]
	v_mfma_f32_16x16x32_bf16 v[48:51], v[172:175], v[216:219], v[48:51]
	v_mfma_f32_16x16x32_bf16 v[16:19], v[180:183], v[216:219], v[16:19]
	v_mfma_f32_16x16x32_bf16 v[100:103], v[172:175], v[224:227], v[100:103]
	v_mfma_f32_16x16x32_bf16 v[96:99], v[180:183], v[224:227], v[96:99]
	s_setprio 0
	s_barrier
; #define PG8_STAGE(bufoff, gbase, voff) do { _Pragma("unroll") for (int _i = 0; _i < 2; ++_i) \
;         __builtin_amdgcn_global_load_lds((const unsigned*)((const char*)(gbase) + (voff)[_i]), (LAS unsigned*)(lds + (bufoff) + ldsw + _i * 8192), 16, 0, 0); } while (0)
; #define PG8_LDA(dst, b, h) do { _Pragma("unroll") for (int m = 0; m < 4; ++m) _Pragma("unroll") for (int k = 0; k < 2; ++k) dst[m][k] = *(const LAS bf16x8*)(lds + PG8_SA(b, h) + aoff + m * 2048 + k * 1024); } while (0)
; #define PG8_MMA(ai, bj, At, Bt) do { __builtin_amdgcn_s_setprio(1); _Pragma("unroll") for (int m = 0; m < 4; ++m) _Pragma("unroll") for (int n = 0; n < 2; ++n) _Pragma("unroll") for (int k = 0; k < 2; ++k) \
;         acc[ai][bj][m][n] = __builtin_amdgcn_mfma_f32_16x16x32_bf16(Bt[n][k], At[m][k], acc[ai][bj][m][n], 0, 0, 0); __builtin_amdgcn_s_setprio(0); } while (0)
; #define PG8_WAIT_V(n) asm volatile("s_waitcnt vmcnt(" #n ")" ::: "memory")
; #define PG8_WAIT_L(n) asm volatile("s_waitcnt lgkmcnt(" #n ")" ::: "memory")
; #define PG8_BAR __builtin_amdgcn_s_barrier()
; #define PG8_SCHED __builtin_amdgcn_sched_barrier(0)
; template <class Epi, class Sched, bool ALIGN_EPI, bool SP2>
; __device__ __forceinline__ void gemm_phase(LAS unsigned char* lds, const Gemm g, const Sched& S, const Epi& E) {
;     ...
;             PG8_LDA(At, 1, 1); PG8_STAGE(PG8_SB(1, 0), b3, voffB); PG8_STAGE(PG8_SB(1, 1), b3 + hstepB, voffB); PG8_STAGE(PG8_SA(1, 0), a3, voffA);
;             PG8_WAIT_V(8); PG8_WAIT_L(0); PG8_BAR; PG8_MMA(1, 0, At, B0); PG8_MMA(1, 1, At, B1); PG8_BAR; PG8_SCHED;
	s_add_i32 s0, s0, s57
	v_lshl_add_u64 v[204:205], v[204:205], 0, s[42:43]
	s_mov_b32 m0, s0
	ds_read_b128 v[184:187], v214 offset:49152
	ds_read_b128 v[188:191], v214 offset:50176
	ds_read_b128 v[192:195], v214 offset:51200
	ds_read_b128 v[196:199], v214 offset:52224
	ds_read_b128 v[200:203], v214 offset:53248
	ds_read_b128 v[216:219], v214 offset:54272
	ds_read_b128 v[220:223], v214 offset:55296
	ds_read_b128 v[224:227], v214 offset:56320
	global_load_lds_dwordx4 v[204:205], off
	s_add_i32 m0, s0, 0x2000
	s_add_u32 s14, s78, 0x80080
	v_lshl_add_u64 v[204:205], v[228:229], 0, s[42:43]
	s_addc_u32 s15, s79, 0
	s_add_i32 s0, s58, s57
	global_load_lds_dwordx4 v[204:205], off
	v_lshl_add_u64 v[204:205], s[14:15], 0, v[134:135]
	s_mov_b32 m0, s0
	s_nop 0
	global_load_lds_dwordx4 v[204:205], off
	v_lshl_add_u64 v[204:205], s[14:15], 0, v[138:139]
	s_add_i32 m0, s0, 0x2000
	s_nop 0
	global_load_lds_dwordx4 v[204:205], off
	v_lshl_add_u64 v[204:205], v[230:231], 0, s[42:43]
	s_mov_b32 m0, s87
	s_nop 0
	global_load_lds_dwordx4 v[204:205], off
	v_lshl_add_u64 v[204:205], v[232:233], 0, s[42:43]
	s_mov_b32 m0, s88
	s_nop 0
	global_load_lds_dwordx4 v[204:205], off
	s_waitcnt vmcnt(8)
	s_waitcnt lgkmcnt(0)
	s_barrier
	s_setprio 1
	v_mfma_f32_16x16x32_bf16 v[92:95], v[152:155], v[184:187], v[92:95]
	v_mfma_f32_16x16x32_bf16 v[88:91], v[160:163], v[184:187], v[88:91]
	v_mfma_f32_16x16x32_bf16 v[44:47], v[152:155], v[192:195], v[44:47]
	v_mfma_f32_16x16x32_bf16 v[12:15], v[160:163], v[192:195], v[12:15]
	v_mfma_f32_16x16x32_bf16 v[36:39], v[152:155], v[200:203], v[36:39]
	v_mfma_f32_16x16x32_bf16 v[4:7], v[160:163], v[200:203], v[4:7]
	v_mfma_f32_16x16x32_bf16 v[72:75], v[152:155], v[220:223], v[72:75]
	v_mfma_f32_16x16x32_bf16 v[68:71], v[160:163], v[220:223], v[68:71]
	v_mfma_f32_16x16x32_bf16 v[92:95], v[156:159], v[188:191], v[92:95]
	v_mfma_f32_16x16x32_bf16 v[88:91], v[164:167], v[188:191], v[88:91]
	v_mfma_f32_16x16x32_bf16 v[44:47], v[156:159], v[196:199], v[44:47]
	v_mfma_f32_16x16x32_bf16 v[12:15], v[164:167], v[196:199], v[12:15]
	v_mfma_f32_16x16x32_bf16 v[36:39], v[156:159], v[216:219], v[36:39]
	v_mfma_f32_16x16x32_bf16 v[4:7], v[164:167], v[216:219], v[4:7]
	v_mfma_f32_16x16x32_bf16 v[72:75], v[156:159], v[224:227], v[72:75]
	v_mfma_f32_16x16x32_bf16 v[68:71], v[164:167], v[224:227], v[68:71]
	v_mfma_f32_16x16x32_bf16 v[84:87], v[168:171], v[184:187], v[84:87]
	v_mfma_f32_16x16x32_bf16 v[80:83], v[176:179], v[184:187], v[80:83]
	v_mfma_f32_16x16x32_bf16 v[40:43], v[168:171], v[192:195], v[40:43]
	v_mfma_f32_16x16x32_bf16 v[8:11], v[176:179], v[192:195], v[8:11]
	v_mfma_f32_16x16x32_bf16 v[32:35], v[168:171], v[200:203], v[32:35]
	v_mfma_f32_16x16x32_bf16 v[0:3], v[176:179], v[200:203], v[0:3]
	v_mfma_f32_16x16x32_bf16 v[60:63], v[168:171], v[220:223], v[60:63]
	v_mfma_f32_16x16x32_bf16 v[56:59], v[176:179], v[220:223], v[56:59]
	v_mfma_f32_16x16x32_bf16 v[84:87], v[172:175], v[188:191], v[84:87]
	v_mfma_f32_16x16x32_bf16 v[80:83], v[180:183], v[188:191], v[80:83]
	v_mfma_f32_16x16x32_bf16 v[40:43], v[172:175], v[196:199], v[40:43]
	v_mfma_f32_16x16x32_bf16 v[8:11], v[180:183], v[196:199], v[8:11]
	v_mfma_f32_16x16x32_bf16 v[32:35], v[172:175], v[216:219], v[32:35]
	v_mfma_f32_16x16x32_bf16 v[0:3], v[180:183], v[216:219], v[0:3]
	v_mfma_f32_16x16x32_bf16 v[60:63], v[172:175], v[224:227], v[60:63]
	v_mfma_f32_16x16x32_bf16 v[56:59], v[180:183], v[224:227], v[56:59]
	s_setprio 0
	s_barrier
	s_add_i32 s33, s33, 2
	s_add_u32 s76, s76, 0x100
	s_addc_u32 s77, s77, 0
	s_add_u32 s71, s71, 0x100
	s_addc_u32 s97, s97, 0
	s_cmp_gt_u32 s33, 29
	s_cbranch_scc1 .LBB0_987

; #define PG8_STAGE(bufoff, gbase, voff) do { _Pragma("unroll") for (int _i = 0; _i < 2; ++_i) \
;         __builtin_amdgcn_global_load_lds((const unsigned*)((const char*)(gbase) + (voff)[_i]), (LAS unsigned*)(lds + (bufoff) + ldsw + _i * 8192), 16, 0, 0); } while (0)
; #define PG8_LDA(dst, b, h) do { _Pragma("unroll") for (int m = 0; m < 4; ++m) _Pragma("unroll") for (int k = 0; k < 2; ++k) dst[m][k] = *(const LAS bf16x8*)(lds + PG8_SA(b, h) + aoff + m * 2048 + k * 1024); } while (0)
; #define PG8_LDB(dst, b, h) do { _Pragma("unroll") for (int n = 0; n < 2; ++n) _Pragma("unroll") for (int k = 0; k < 2; ++k) dst[n][k] = *(const LAS bf16x8*)(lds + PG8_SB(b, h) + boff + n * 2048 + k * 1024); } while (0)
; #define PG8_MMA(ai, bj, At, Bt) do { __builtin_amdgcn_s_setprio(1); _Pragma("unroll") for (int m = 0; m < 4; ++m) _Pragma("unroll") for (int n = 0; n < 2; ++n) _Pragma("unroll") for (int k = 0; k < 2; ++k) \
;         acc[ai][bj][m][n] = __builtin_amdgcn_mfma_f32_16x16x32_bf16(Bt[n][k], At[m][k], acc[ai][bj][m][n], 0, 0, 0); __builtin_amdgcn_s_setprio(0); } while (0)
; #define PG8_WAIT_V(n) asm volatile("s_waitcnt vmcnt(" #n ")" ::: "memory")
; #define PG8_WAIT_L(n) asm volatile("s_waitcnt lgkmcnt(" #n ")" ::: "memory")
; template <class Epi, class Sched, bool ALIGN_EPI, bool SP2>
; __device__ __forceinline__ void gemm_phase(LAS unsigned char* lds, const Gemm g, const Sched& S, const Epi& E) {
;     ...
;         for (int t = tb; t < te; t += 2) {
;             const bool last = (t == nt - 2);
;             const char* a1 = cA + (size_t)(t + 1) * kstep;
;             const char* a2 = last ? nA : cA + (size_t)(t + 2) * kstep; const char* b2 = last ? nB : cB + (size_t)(t + 2) * kstep;
;             const char* a3 = a2 + kstep; const char* b3 = b2 + kstep;
;             if (last && has_next) S.a_ready(nxt);
;             if constexpr (SP2) {
;             PG8_LDB(B0, 0, 0); PG8_LDB(B1, 0, 1); PG8_SCHED; PG8_LDA(At, 0, 0); PG8_STAGE(PG8_SA(1, 1), a1 + hstep, voffA);
;             PG8_WAIT_V(8); PG8_WAIT_L(0); PG8_BAR; PG8_MMA(0, 0, At, B0); PG8_MMA(0, 1, At, B1); PG8_BAR; PG8_SCHED;
;             PG8_LDA(At, 0, 1); PG8_STAGE(PG8_SB(0, 0), b2, voffB); PG8_STAGE(PG8_SB(0, 1), b2 + hstepB, voffB); PG8_STAGE(PG8_SA(0, 0), a2, voffA);
;             PG8_WAIT_V(8); PG8_WAIT_L(0); PG8_BAR; PG8_MMA(1, 0, At, B0); PG8_MMA(1, 1, At, B1); PG8_BAR; PG8_SCHED;
.LBB0_1140:
	ds_read_b128 v[128:131], v161
	ds_read_b128 v[132:135], v161 offset:1024
	ds_read_b128 v[152:155], v161 offset:2048
	ds_read_b128 v[166:169], v161 offset:3072
	ds_read_b128 v[170:173], v162
	ds_read_b128 v[174:177], v162 offset:1024
	ds_read_b128 v[178:181], v162 offset:2048
	ds_read_b128 v[182:185], v162 offset:3072
	s_add_u32 s38, s24, 0x100
	s_addc_u32 s39, s25, 0
	s_cmpk_eq_i32 s65, 0x54
	s_cselect_b32 s43, s1, s39
	s_cselect_b32 s42, s0, s38
	s_cselect_b32 s41, s23, s64
	s_cselect_b32 s40, s22, s33
	v_lshl_add_u64 v[156:157], s[24:25], 0, v[144:145]
	s_add_i32 m0, s45, 0xc000
	ds_read_b128 v[186:189], v163
	ds_read_b128 v[190:193], v163 offset:1024
	ds_read_b128 v[194:197], v163 offset:2048
	ds_read_b128 v[198:201], v163 offset:3072
	ds_read_b128 v[202:205], v163 offset:4096
	ds_read_b128 v[208:211], v163 offset:5120
	ds_read_b128 v[212:215], v163 offset:6144
	ds_read_b128 v[216:219], v163 offset:7168
	global_load_lds_dwordx4 v[156:157], off
	v_lshl_add_u64 v[156:157], s[24:25], 0, v[146:147]
	s_add_i32 m0, s45, 0xe000
	s_nop 0
	global_load_lds_dwordx4 v[156:157], off
	s_waitcnt vmcnt(8)
	s_waitcnt lgkmcnt(0)
	s_barrier
	s_setprio 1
	v_mfma_f32_16x16x32_bf16 v[124:127], v[128:131], v[186:189], v[124:127]
	v_mfma_f32_16x16x32_bf16 v[120:123], v[152:155], v[186:189], v[120:123]
	v_mfma_f32_16x16x32_bf16 v[108:111], v[128:131], v[194:197], v[108:111]
	v_mfma_f32_16x16x32_bf16 v[104:107], v[152:155], v[194:197], v[104:107]
	v_mfma_f32_16x16x32_bf16 v[92:95], v[128:131], v[202:205], v[92:95]
	v_mfma_f32_16x16x32_bf16 v[88:91], v[152:155], v[202:205], v[88:91]
	v_mfma_f32_16x16x32_bf16 v[76:79], v[128:131], v[212:215], v[76:79]
	v_mfma_f32_16x16x32_bf16 v[72:75], v[152:155], v[212:215], v[72:75]
	v_mfma_f32_16x16x32_bf16 v[124:127], v[132:135], v[190:193], v[124:127]
	v_mfma_f32_16x16x32_bf16 v[120:123], v[166:169], v[190:193], v[120:123]
	v_mfma_f32_16x16x32_bf16 v[108:111], v[132:135], v[198:201], v[108:111]
	v_mfma_f32_16x16x32_bf16 v[104:107], v[166:169], v[198:201], v[104:107]
	v_mfma_f32_16x16x32_bf16 v[92:95], v[132:135], v[208:211], v[92:95]
	v_mfma_f32_16x16x32_bf16 v[88:91], v[166:169], v[208:211], v[88:91]
	v_mfma_f32_16x16x32_bf16 v[76:79], v[132:135], v[216:219], v[76:79]
	v_mfma_f32_16x16x32_bf16 v[72:75], v[166:169], v[216:219], v[72:75]
	v_mfma_f32_16x16x32_bf16 v[116:119], v[170:173], v[186:189], v[116:119]
	v_mfma_f32_16x16x32_bf16 v[112:115], v[178:181], v[186:189], v[112:115]
	v_mfma_f32_16x16x32_bf16 v[100:103], v[170:173], v[194:197], v[100:103]
	v_mfma_f32_16x16x32_bf16 v[96:99], v[178:181], v[194:197], v[96:99]
	v_mfma_f32_16x16x32_bf16 v[84:87], v[170:173], v[202:205], v[84:87]
	v_mfma_f32_16x16x32_bf16 v[80:83], v[178:181], v[202:205], v[80:83]
	v_mfma_f32_16x16x32_bf16 v[68:71], v[170:173], v[212:215], v[68:71]
	v_mfma_f32_16x16x32_bf16 v[64:67], v[178:181], v[212:215], v[64:67]
	v_mfma_f32_16x16x32_bf16 v[116:119], v[174:177], v[190:193], v[116:119]
	v_mfma_f32_16x16x32_bf16 v[112:115], v[182:185], v[190:193], v[112:115]
	v_mfma_f32_16x16x32_bf16 v[100:103], v[174:177], v[198:201], v[100:103]
	v_mfma_f32_16x16x32_bf16 v[96:99], v[182:185], v[198:201], v[96:99]
	v_mfma_f32_16x16x32_bf16 v[84:87], v[174:177], v[208:211], v[84:87]
	v_mfma_f32_16x16x32_bf16 v[80:83], v[182:185], v[208:211], v[80:83]
	v_mfma_f32_16x16x32_bf16 v[68:71], v[174:177], v[216:219], v[68:71]
	v_mfma_f32_16x16x32_bf16 v[64:67], v[182:185], v[216:219], v[64:67]
	s_setprio 0
	s_barrier
	s_add_i32 s14, s60, s44
	v_lshl_add_u64 v[156:157], s[40:41], 0, v[138:139]
	s_mov_b32 m0, s14
	ds_read_b128 v[186:189], v163 offset:16384
	ds_read_b128 v[190:193], v163 offset:17408
	ds_read_b128 v[194:197], v163 offset:18432
	ds_read_b128 v[198:201], v163 offset:19456
	ds_read_b128 v[202:205], v163 offset:20480
	ds_read_b128 v[208:211], v163 offset:21504
	ds_read_b128 v[212:215], v163 offset:22528
	ds_read_b128 v[216:219], v163 offset:23552
	global_load_lds_dwordx4 v[156:157], off
	s_add_i32 m0, s14, 0x2000
	s_add_u32 s14, s40, 0x160000
	v_lshl_add_u64 v[220:221], s[40:41], 0, v[142:143]
	s_addc_u32 s15, s41, 0
	s_add_i32 s24, s61, s44
	global_load_lds_dwordx4 v[220:221], off
	v_lshl_add_u64 v[222:223], s[14:15], 0, v[138:139]
	s_mov_b32 m0, s24
	v_lshl_add_u64 v[224:225], s[42:43], 0, v[140:141]
	global_load_lds_dwordx4 v[222:223], off
	v_lshl_add_u64 v[222:223], s[14:15], 0, v[142:143]
	s_add_i32 m0, s24, 0x2000
	s_nop 0
	global_load_lds_dwordx4 v[222:223], off
	v_lshl_add_u64 v[222:223], s[42:43], 0, v[136:137]
	s_mov_b32 m0, s45
	s_nop 0
	global_load_lds_dwordx4 v[222:223], off
	s_mov_b32 m0, s46
	s_nop 0
	global_load_lds_dwordx4 v[224:225], off
	s_waitcnt vmcnt(8)
	s_waitcnt lgkmcnt(0)
	s_barrier
; #define PG8_STAGE(bufoff, gbase, voff) do { _Pragma("unroll") for (int _i = 0; _i < 2; ++_i) \
;         __builtin_amdgcn_global_load_lds((const unsigned*)((const char*)(gbase) + (voff)[_i]), (LAS unsigned*)(lds + (bufoff) + ldsw + _i * 8192), 16, 0, 0); } while (0)
; #define PG8_LDA(dst, b, h) do { _Pragma("unroll") for (int m = 0; m < 4; ++m) _Pragma("unroll") for (int k = 0; k < 2; ++k) dst[m][k] = *(const LAS bf16x8*)(lds + PG8_SA(b, h) + aoff + m * 2048 + k * 1024); } while (0)
; #define PG8_LDB(dst, b, h) do { _Pragma("unroll") for (int n = 0; n < 2; ++n) _Pragma("unroll") for (int k = 0; k < 2; ++k) dst[n][k] = *(const LAS bf16x8*)(lds + PG8_SB(b, h) + boff + n * 2048 + k * 1024); } while (0)
; #define PG8_MMA(ai, bj, At, Bt) do { __builtin_amdgcn_s_setprio(1); _Pragma("unroll") for (int m = 0; m < 4; ++m) _Pragma("unroll") for (int n = 0; n < 2; ++n) _Pragma("unroll") for (int k = 0; k < 2; ++k) \
;         acc[ai][bj][m][n] = __builtin_amdgcn_mfma_f32_16x16x32_bf16(Bt[n][k], At[m][k], acc[ai][bj][m][n], 0, 0, 0); __builtin_amdgcn_s_setprio(0); } while (0)
; #define PG8_WAIT_V(n) asm volatile("s_waitcnt vmcnt(" #n ")" ::: "memory")
; #define PG8_WAIT_L(n) asm volatile("s_waitcnt lgkmcnt(" #n ")" ::: "memory")
; #define PG8_BAR __builtin_amdgcn_s_barrier()
; #define PG8_SCHED __builtin_amdgcn_sched_barrier(0)
; template <class Epi, class Sched, bool ALIGN_EPI, bool SP2>
; __device__ __forceinline__ void gemm_phase(LAS unsigned char* lds, const Gemm g, const Sched& S, const Epi& E) {
;     ...
;             PG8_WAIT_V(8); PG8_WAIT_L(0); PG8_BAR; PG8_MMA(1, 0, At, B0); PG8_MMA(1, 1, At, B1); PG8_BAR; PG8_SCHED;
;             PG8_LDB(B0, 1, 0); PG8_LDB(B1, 1, 1); PG8_SCHED; PG8_LDA(At, 1, 0); PG8_STAGE(PG8_SA(0, 1), a2 + hstep, voffA);
;             PG8_WAIT_V(8); PG8_WAIT_L(0); PG8_BAR; PG8_MMA(0, 0, At, B0); PG8_MMA(0, 1, At, B1); PG8_BAR; PG8_SCHED;
	s_setprio 1
	v_mfma_f32_16x16x32_bf16 v[60:63], v[128:131], v[186:189], v[60:63]
	v_mfma_f32_16x16x32_bf16 v[56:59], v[152:155], v[186:189], v[56:59]
	v_mfma_f32_16x16x32_bf16 v[44:47], v[128:131], v[194:197], v[44:47]
	v_mfma_f32_16x16x32_bf16 v[40:43], v[152:155], v[194:197], v[40:43]
	v_mfma_f32_16x16x32_bf16 v[28:31], v[128:131], v[202:205], v[28:31]
	v_mfma_f32_16x16x32_bf16 v[24:27], v[152:155], v[202:205], v[24:27]
	v_mfma_f32_16x16x32_bf16 v[12:15], v[128:131], v[212:215], v[12:15]
	v_mfma_f32_16x16x32_bf16 v[8:11], v[152:155], v[212:215], v[8:11]
	v_mfma_f32_16x16x32_bf16 v[60:63], v[132:135], v[190:193], v[60:63]
	v_mfma_f32_16x16x32_bf16 v[56:59], v[166:169], v[190:193], v[56:59]
	v_mfma_f32_16x16x32_bf16 v[44:47], v[132:135], v[198:201], v[44:47]
	v_mfma_f32_16x16x32_bf16 v[40:43], v[166:169], v[198:201], v[40:43]
	v_mfma_f32_16x16x32_bf16 v[28:31], v[132:135], v[208:211], v[28:31]
	v_mfma_f32_16x16x32_bf16 v[24:27], v[166:169], v[208:211], v[24:27]
	v_mfma_f32_16x16x32_bf16 v[12:15], v[132:135], v[216:219], v[12:15]
	v_mfma_f32_16x16x32_bf16 v[8:11], v[166:169], v[216:219], v[8:11]
	v_mfma_f32_16x16x32_bf16 v[52:55], v[170:173], v[186:189], v[52:55]
	v_mfma_f32_16x16x32_bf16 v[48:51], v[178:181], v[186:189], v[48:51]
	v_mfma_f32_16x16x32_bf16 v[36:39], v[170:173], v[194:197], v[36:39]
	v_mfma_f32_16x16x32_bf16 v[32:35], v[178:181], v[194:197], v[32:35]
	v_mfma_f32_16x16x32_bf16 v[20:23], v[170:173], v[202:205], v[20:23]
	v_mfma_f32_16x16x32_bf16 v[16:19], v[178:181], v[202:205], v[16:19]
	v_mfma_f32_16x16x32_bf16 v[4:7], v[170:173], v[212:215], v[4:7]
	v_mfma_f32_16x16x32_bf16 v[0:3], v[178:181], v[212:215], v[0:3]
	v_mfma_f32_16x16x32_bf16 v[52:55], v[174:177], v[190:193], v[52:55]
	v_mfma_f32_16x16x32_bf16 v[48:51], v[182:185], v[190:193], v[48:51]
	v_mfma_f32_16x16x32_bf16 v[36:39], v[174:177], v[198:201], v[36:39]
	v_mfma_f32_16x16x32_bf16 v[32:35], v[182:185], v[198:201], v[32:35]
	v_mfma_f32_16x16x32_bf16 v[20:23], v[174:177], v[208:211], v[20:23]
	v_mfma_f32_16x16x32_bf16 v[16:19], v[182:185], v[208:211], v[16:19]
	v_mfma_f32_16x16x32_bf16 v[4:7], v[174:177], v[216:219], v[4:7]
	v_mfma_f32_16x16x32_bf16 v[0:3], v[182:185], v[216:219], v[0:3]
	s_setprio 0
	s_barrier
	s_add_i32 s24, 0, 0x18000
	v_add_u32_e32 v165, s24, v159
	s_add_i32 s25, 0, 0x1c000
	ds_read_b128 v[128:131], v165
	ds_read_b128 v[132:135], v165 offset:1024
	ds_read_b128 v[152:155], v165 offset:2048
	ds_read_b128 v[166:169], v165 offset:3072
	v_add_u32_e32 v165, s25, v159
	ds_read_b128 v[170:173], v165
	ds_read_b128 v[174:177], v165 offset:1024
	ds_read_b128 v[178:181], v165 offset:2048
	ds_read_b128 v[182:185], v165 offset:3072
	s_add_u32 s14, s42, 0x160000
	s_addc_u32 s15, s43, 0
	s_mov_b32 m0, s47
	v_lshl_add_u64 v[226:227], s[14:15], 0, v[136:137]
	ds_read_b128 v[186:189], v163 offset:32768
	ds_read_b128 v[190:193], v163 offset:33792
	ds_read_b128 v[194:197], v163 offset:34816
	ds_read_b128 v[198:201], v163 offset:35840
	ds_read_b128 v[202:205], v163 offset:36864
	ds_read_b128 v[208:211], v163 offset:37888
	ds_read_b128 v[212:215], v163 offset:38912
	ds_read_b128 v[216:219], v163 offset:39936
	global_load_lds_dwordx4 v[226:227], off
	v_lshl_add_u64 v[226:227], s[14:15], 0, v[140:141]
	s_mov_b32 m0, s50
	s_nop 0
	global_load_lds_dwordx4 v[226:227], off
	s_waitcnt vmcnt(8)
	s_waitcnt lgkmcnt(0)
	s_barrier
	s_setprio 1
	v_mfma_f32_16x16x32_bf16 v[124:127], v[128:131], v[186:189], v[124:127]
	v_mfma_f32_16x16x32_bf16 v[120:123], v[152:155], v[186:189], v[120:123]
	v_mfma_f32_16x16x32_bf16 v[108:111], v[128:131], v[194:197], v[108:111]
	v_mfma_f32_16x16x32_bf16 v[104:107], v[152:155], v[194:197], v[104:107]
	v_mfma_f32_16x16x32_bf16 v[92:95], v[128:131], v[202:205], v[92:95]
	v_mfma_f32_16x16x32_bf16 v[88:91], v[152:155], v[202:205], v[88:91]
	v_mfma_f32_16x16x32_bf16 v[76:79], v[128:131], v[212:215], v[76:79]
	v_mfma_f32_16x16x32_bf16 v[72:75], v[152:155], v[212:215], v[72:75]
	v_mfma_f32_16x16x32_bf16 v[124:127], v[132:135], v[190:193], v[124:127]
	v_mfma_f32_16x16x32_bf16 v[120:123], v[166:169], v[190:193], v[120:123]
	v_mfma_f32_16x16x32_bf16 v[108:111], v[132:135], v[198:201], v[108:111]
	v_mfma_f32_16x16x32_bf16 v[104:107], v[166:169], v[198:201], v[104:107]
	v_mfma_f32_16x16x32_bf16 v[92:95], v[132:135], v[208:211], v[92:95]
	v_mfma_f32_16x16x32_bf16 v[88:91], v[166:169], v[208:211], v[88:91]
	v_mfma_f32_16x16x32_bf16 v[76:79], v[132:135], v[216:219], v[76:79]
	v_mfma_f32_16x16x32_bf16 v[72:75], v[166:169], v[216:219], v[72:75]
	v_mfma_f32_16x16x32_bf16 v[116:119], v[170:173], v[186:189], v[116:119]
	v_mfma_f32_16x16x32_bf16 v[112:115], v[178:181], v[186:189], v[112:115]
	v_mfma_f32_16x16x32_bf16 v[100:103], v[170:173], v[194:197], v[100:103]
	v_mfma_f32_16x16x32_bf16 v[96:99], v[178:181], v[194:197], v[96:99]
	v_mfma_f32_16x16x32_bf16 v[84:87], v[170:173], v[202:205], v[84:87]
	v_mfma_f32_16x16x32_bf16 v[80:83], v[178:181], v[202:205], v[80:83]
	v_mfma_f32_16x16x32_bf16 v[68:71], v[170:173], v[212:215], v[68:71]
	v_mfma_f32_16x16x32_bf16 v[64:67], v[178:181], v[212:215], v[64:67]
	v_mfma_f32_16x16x32_bf16 v[116:119], v[174:177], v[190:193], v[116:119]
	v_mfma_f32_16x16x32_bf16 v[112:115], v[182:185], v[190:193], v[112:115]
	v_mfma_f32_16x16x32_bf16 v[100:103], v[174:177], v[198:201], v[100:103]
	v_mfma_f32_16x16x32_bf16 v[96:99], v[182:185], v[198:201], v[96:99]
	v_mfma_f32_16x16x32_bf16 v[84:87], v[174:177], v[208:211], v[84:87]
	v_mfma_f32_16x16x32_bf16 v[80:83], v[182:185], v[208:211], v[80:83]
	v_mfma_f32_16x16x32_bf16 v[68:71], v[174:177], v[216:219], v[68:71]
	v_mfma_f32_16x16x32_bf16 v[64:67], v[182:185], v[216:219], v[64:67]
	s_setprio 0
	s_barrier
; #define PG8_STAGE(bufoff, gbase, voff) do { _Pragma("unroll") for (int _i = 0; _i < 2; ++_i) \
;         __builtin_amdgcn_global_load_lds((const unsigned*)((const char*)(gbase) + (voff)[_i]), (LAS unsigned*)(lds + (bufoff) + ldsw + _i * 8192), 16, 0, 0); } while (0)
; #define PG8_LDA(dst, b, h) do { _Pragma("unroll") for (int m = 0; m < 4; ++m) _Pragma("unroll") for (int k = 0; k < 2; ++k) dst[m][k] = *(const LAS bf16x8*)(lds + PG8_SA(b, h) + aoff + m * 2048 + k * 1024); } while (0)
; #define PG8_MMA(ai, bj, At, Bt) do { __builtin_amdgcn_s_setprio(1); _Pragma("unroll") for (int m = 0; m < 4; ++m) _Pragma("unroll") for (int n = 0; n < 2; ++n) _Pragma("unroll") for (int k = 0; k < 2; ++k) \
;         acc[ai][bj][m][n] = __builtin_amdgcn_mfma_f32_16x16x32_bf16(Bt[n][k], At[m][k], acc[ai][bj][m][n], 0, 0, 0); __builtin_amdgcn_s_setprio(0); } while (0)
; #define PG8_WAIT_V(n) asm volatile("s_waitcnt vmcnt(" #n ")" ::: "memory")
; #define PG8_WAIT_L(n) asm volatile("s_waitcnt lgkmcnt(" #n ")" ::: "memory")
; #define PG8_BAR __builtin_amdgcn_s_barrier()
; #define PG8_SCHED __builtin_amdgcn_sched_barrier(0)
; template <class Epi, class Sched, bool ALIGN_EPI, bool SP2>
; __device__ __forceinline__ void gemm_phase(LAS unsigned char* lds, const Gemm g, const Sched& S, const Epi& E) {
;     ...
;             PG8_LDA(At, 1, 1); PG8_STAGE(PG8_SB(1, 0), b3, voffB); PG8_STAGE(PG8_SB(1, 1), b3 + hstepB, voffB); PG8_STAGE(PG8_SA(1, 0), a3, voffA);
;             PG8_WAIT_V(8); PG8_WAIT_L(0); PG8_BAR; PG8_MMA(1, 0, At, B0); PG8_MMA(1, 1, At, B1); PG8_BAR; PG8_SCHED;
;     ...
;         if constexpr (ALIGN_EPI) { if (wr == 0) PG8_BAR; }
	s_add_i32 s14, s24, s44
	v_lshl_add_u64 v[156:157], v[156:157], 0, s[10:11]
	s_mov_b32 m0, s14
	ds_read_b128 v[186:189], v163 offset:49152
	ds_read_b128 v[190:193], v163 offset:50176
	ds_read_b128 v[194:197], v163 offset:51200
	ds_read_b128 v[198:201], v163 offset:52224
	ds_read_b128 v[202:205], v163 offset:53248
	ds_read_b128 v[208:211], v163 offset:54272
	ds_read_b128 v[212:215], v163 offset:55296
	ds_read_b128 v[216:219], v163 offset:56320
	global_load_lds_dwordx4 v[156:157], off
	s_add_i32 m0, s14, 0x2000
	s_add_u32 s14, s40, 0x160080
	v_lshl_add_u64 v[156:157], v[220:221], 0, s[10:11]
	s_addc_u32 s15, s41, 0
	s_add_i32 s24, s25, s44
	global_load_lds_dwordx4 v[156:157], off
	v_lshl_add_u64 v[156:157], s[14:15], 0, v[138:139]
	s_mov_b32 m0, s24
	s_nop 0
	global_load_lds_dwordx4 v[156:157], off
	v_lshl_add_u64 v[156:157], s[14:15], 0, v[142:143]
	s_add_i32 m0, s24, 0x2000
	s_nop 0
	global_load_lds_dwordx4 v[156:157], off
	v_lshl_add_u64 v[156:157], v[222:223], 0, s[10:11]
	s_mov_b32 m0, s57
	s_nop 0
	global_load_lds_dwordx4 v[156:157], off
	v_lshl_add_u64 v[156:157], v[224:225], 0, s[10:11]
	s_mov_b32 m0, s58
	s_nop 0
	global_load_lds_dwordx4 v[156:157], off
	s_waitcnt vmcnt(8)
	s_waitcnt lgkmcnt(0)
	s_barrier
	s_setprio 1
	v_mfma_f32_16x16x32_bf16 v[60:63], v[128:131], v[186:189], v[60:63]
	v_mfma_f32_16x16x32_bf16 v[56:59], v[152:155], v[186:189], v[56:59]
	v_mfma_f32_16x16x32_bf16 v[44:47], v[128:131], v[194:197], v[44:47]
	v_mfma_f32_16x16x32_bf16 v[40:43], v[152:155], v[194:197], v[40:43]
	v_mfma_f32_16x16x32_bf16 v[28:31], v[128:131], v[202:205], v[28:31]
	v_mfma_f32_16x16x32_bf16 v[24:27], v[152:155], v[202:205], v[24:27]
	v_mfma_f32_16x16x32_bf16 v[12:15], v[128:131], v[212:215], v[12:15]
	v_mfma_f32_16x16x32_bf16 v[8:11], v[152:155], v[212:215], v[8:11]
	v_mfma_f32_16x16x32_bf16 v[60:63], v[132:135], v[190:193], v[60:63]
	v_mfma_f32_16x16x32_bf16 v[56:59], v[166:169], v[190:193], v[56:59]
	v_mfma_f32_16x16x32_bf16 v[44:47], v[132:135], v[198:201], v[44:47]
	v_mfma_f32_16x16x32_bf16 v[40:43], v[166:169], v[198:201], v[40:43]
	v_mfma_f32_16x16x32_bf16 v[28:31], v[132:135], v[208:211], v[28:31]
	v_mfma_f32_16x16x32_bf16 v[24:27], v[166:169], v[208:211], v[24:27]
	v_mfma_f32_16x16x32_bf16 v[12:15], v[132:135], v[216:219], v[12:15]
	v_mfma_f32_16x16x32_bf16 v[8:11], v[166:169], v[216:219], v[8:11]
	v_mfma_f32_16x16x32_bf16 v[52:55], v[170:173], v[186:189], v[52:55]
	v_mfma_f32_16x16x32_bf16 v[48:51], v[178:181], v[186:189], v[48:51]
	v_mfma_f32_16x16x32_bf16 v[36:39], v[170:173], v[194:197], v[36:39]
	v_mfma_f32_16x16x32_bf16 v[32:35], v[178:181], v[194:197], v[32:35]
	v_mfma_f32_16x16x32_bf16 v[20:23], v[170:173], v[202:205], v[20:23]
	v_mfma_f32_16x16x32_bf16 v[16:19], v[178:181], v[202:205], v[16:19]
	v_mfma_f32_16x16x32_bf16 v[4:7], v[170:173], v[212:215], v[4:7]
	v_mfma_f32_16x16x32_bf16 v[0:3], v[178:181], v[212:215], v[0:3]
	v_mfma_f32_16x16x32_bf16 v[52:55], v[174:177], v[190:193], v[52:55]
	v_mfma_f32_16x16x32_bf16 v[48:51], v[182:185], v[190:193], v[48:51]
	v_mfma_f32_16x16x32_bf16 v[36:39], v[174:177], v[198:201], v[36:39]
	v_mfma_f32_16x16x32_bf16 v[32:35], v[182:185], v[198:201], v[32:35]
	v_mfma_f32_16x16x32_bf16 v[20:23], v[174:177], v[208:211], v[20:23]
	v_mfma_f32_16x16x32_bf16 v[16:19], v[182:185], v[208:211], v[16:19]
	v_mfma_f32_16x16x32_bf16 v[4:7], v[174:177], v[216:219], v[4:7]
	v_mfma_f32_16x16x32_bf16 v[0:3], v[182:185], v[216:219], v[0:3]
	s_setprio 0
	s_barrier
	s_add_i32 s65, s65, 2
	s_add_u32 s33, s33, 0x100
	s_addc_u32 s64, s64, 0
	s_cmpk_gt_u32 s65, 0x55
	s_mov_b64 s[24:25], s[38:39]
	s_cbranch_scc0 .LBB0_1140
	s_and_b64 vcc, exec, s[12:13]
	s_cbranch_vccz .LBB0_1143
	s_barrier
